# GEMM k-loop: last two iterations peeled, no clamped duplicate loads / duplicate-slice LDS store; waits re-derived
# speedup vs baseline: 1.0927x; 1.0112x over previous
; template <int NJ>
; __device__ __forceinline__ void gemm_tile(const f16* __restrict__ A, int lda, const f16* __restrict__ Bt, int ldb,
;                                           int K, f32x4 (&acc)[4][NJ], f16* sA, f16* sB, const int tid) {
;     ...
;   G_LOAD(ra0, rb0, 0)
;   if (K > 64) G_LOAD(ra1, rb1, 64)
;   __syncthreads();
;   G_STORE(ra0, rb0, 0)
;   if (K > 128) G_LOAD(ra0, rb0, 128)
;   __syncthreads();
; #pragma unroll 1
;   for (int k0 = 0; k0 < K; k0 += 128) {
;     {
;       const int kof = (k0 + 192 < K) ? k0 + 192 : K - 64;
;       G_STEP(0, ra1, rb1, true, true, kof)
.LBB0_195:
	ds_read_b128 v[204:207], v168 offset:16384
	ds_read_b128 v[208:211], v168 offset:18432
	ds_read_b128 v[212:215], v168 offset:20480
	ds_read_b128 v[216:219], v168 offset:22528
	s_add_i32 s7, s6, 0xc0
	ds_read_b128 v[192:195], v170
	ds_read_b128 v[196:199], v170 offset:2048
	s_cmpk_lt_u32 s6, 0x340
	s_cselect_b32 s42, s7, 0x3c0
	ds_read_b128 v[200:203], v170 offset:4096
	s_lshl_b64 s[8:9], s[42:43], 1
	v_lshl_add_u64 v[162:163], v[156:157], 0, s[8:9]
	ds_read_b128 v[132:135], v170 offset:6144
	ds_read_b128 v[244:247], v243 offset:16384
	ds_read_b128 v[248:251], v243 offset:18432
	ds_read_b128 v[252:255], v243 offset:20480
	s_waitcnt lgkmcnt(6)
	v_mfma_f32_16x16x32_f16 v[64:67], v[204:207], v[192:195], v[64:67]
	v_lshl_add_u64 v[160:161], v[158:159], 0, s[8:9]
	s_add_i32 s7, s6, 0x100
	s_cmpk_lt_u32 s6, 0x300
	v_mfma_f32_16x16x32_f16 v[60:63], v[208:211], v[192:195], v[60:63]
	s_cselect_b32 s42, s7, 0x3c0
	s_lshl_b64 s[8:9], s[42:43], 1
	s_add_i32 s7, s6, 0x80
	v_mfma_f32_16x16x32_f16 v[56:59], v[212:215], v[192:195], v[56:59]
	s_cmpk_lt_u32 s6, 0x280
	s_mov_b32 s6, s7
	v_mfma_f32_16x16x32_f16 v[52:55], v[216:219], v[192:195], v[52:55]
	ds_read_b128 v[192:195], v243 offset:22528
	s_waitcnt vmcnt(15)
	ds_write_b128 v167, v[68:71] offset:32768
	global_load_dwordx4 v[68:71], v[162:163], off
	s_waitcnt lgkmcnt(7)
	v_mfma_f32_16x16x32_f16 v[48:51], v[204:207], v[196:199], v[48:51]
	v_mfma_f32_16x16x32_f16 v[44:47], v[208:211], v[196:199], v[44:47]
	v_mfma_f32_16x16x32_f16 v[40:43], v[212:215], v[196:199], v[40:43]
	v_mfma_f32_16x16x32_f16 v[36:39], v[216:219], v[196:199], v[36:39]
	ds_read_b128 v[196:199], v242
	s_waitcnt vmcnt(15)
	ds_write_b128 v167, v[76:79] offset:36864
	v_add_co_u32_e32 v76, vcc, s94, v162
	s_nop 1
	v_addc_co_u32_e32 v77, vcc, 0, v163, vcc
	global_load_dwordx4 v[76:79], v[76:77], off
	s_waitcnt lgkmcnt(8)
	v_mfma_f32_16x16x32_f16 v[32:35], v[204:207], v[200:203], v[32:35]
	v_mfma_f32_16x16x32_f16 v[28:31], v[208:211], v[200:203], v[28:31]
	v_mfma_f32_16x16x32_f16 v[24:27], v[212:215], v[200:203], v[24:27]
	v_mfma_f32_16x16x32_f16 v[20:23], v[216:219], v[200:203], v[20:23]
	ds_read_b128 v[200:203], v242 offset:2048
	s_waitcnt vmcnt(15)
	ds_write_b128 v167, v[80:83] offset:40960
	v_add_co_u32_e32 v80, vcc, s72, v162
	s_nop 1
	v_addc_co_u32_e32 v81, vcc, 0, v163, vcc
	global_load_dwordx4 v[80:83], v[80:81], off
	s_waitcnt lgkmcnt(9)
	v_mfma_f32_16x16x32_f16 v[16:19], v[204:207], v[132:135], v[16:19]
	v_mfma_f32_16x16x32_f16 v[12:15], v[208:211], v[132:135], v[12:15]
	v_mfma_f32_16x16x32_f16 v[8:11], v[212:215], v[132:135], v[8:11]
	v_mfma_f32_16x16x32_f16 v[4:7], v[216:219], v[132:135], v[4:7]
	ds_read_b128 v[132:135], v242 offset:4096
	ds_read_b128 v[204:207], v242 offset:6144
	s_waitcnt vmcnt(15)
	ds_write_b128 v167, v[84:87] offset:45056
	v_add_co_u32_e32 v84, vcc, s73, v162
	s_nop 1
	v_addc_co_u32_e32 v85, vcc, 0, v163, vcc
	global_load_dwordx4 v[84:87], v[84:85], off
	s_waitcnt lgkmcnt(6)
	v_mfma_f32_16x16x32_f16 v[64:67], v[244:247], v[196:199], v[64:67]
	v_mfma_f32_16x16x32_f16 v[60:63], v[248:251], v[196:199], v[60:63]
	v_mfma_f32_16x16x32_f16 v[56:59], v[252:255], v[196:199], v[56:59]
	v_mfma_f32_16x16x32_f16 v[52:55], v[192:195], v[196:199], v[52:55]
	s_waitcnt vmcnt(15)
	ds_write_b128 v167, v[72:75] offset:49152
	global_load_dwordx4 v[72:75], v[160:161], off
	v_lshl_add_u64 v[218:219], v[156:157], 0, s[8:9]
	s_waitcnt lgkmcnt(5)
	v_mfma_f32_16x16x32_f16 v[48:51], v[244:247], v[200:203], v[48:51]
	v_lshl_add_u64 v[216:217], v[158:159], 0, s[8:9]
	v_mfma_f32_16x16x32_f16 v[44:47], v[248:251], v[200:203], v[44:47]
	v_mfma_f32_16x16x32_f16 v[40:43], v[252:255], v[200:203], v[40:43]
	v_mfma_f32_16x16x32_f16 v[36:39], v[192:195], v[200:203], v[36:39]
	s_waitcnt vmcnt(15)
	ds_write_b128 v167, v[88:91] offset:53248
	v_add_co_u32_e32 v88, vcc, s94, v160
	s_nop 1
	v_addc_co_u32_e32 v89, vcc, 0, v161, vcc
	global_load_dwordx4 v[88:91], v[88:89], off
	s_waitcnt lgkmcnt(4)
	v_mfma_f32_16x16x32_f16 v[32:35], v[244:247], v[132:135], v[32:35]
	v_mfma_f32_16x16x32_f16 v[28:31], v[248:251], v[132:135], v[28:31]
	v_mfma_f32_16x16x32_f16 v[24:27], v[252:255], v[132:135], v[24:27]
	v_mfma_f32_16x16x32_f16 v[20:23], v[192:195], v[132:135], v[20:23]
	s_waitcnt vmcnt(15)
	ds_write_b128 v167, v[96:99] offset:57344
	v_add_co_u32_e32 v96, vcc, s72, v160
	s_nop 1
	v_addc_co_u32_e32 v97, vcc, 0, v161, vcc
	global_load_dwordx4 v[96:99], v[96:97], off
	s_waitcnt lgkmcnt(4)
	v_mfma_f32_16x16x32_f16 v[16:19], v[244:247], v[204:207], v[16:19]
	v_mfma_f32_16x16x32_f16 v[12:15], v[248:251], v[204:207], v[12:15]
	v_mfma_f32_16x16x32_f16 v[8:11], v[252:255], v[204:207], v[8:11]
	v_mfma_f32_16x16x32_f16 v[4:7], v[192:195], v[204:207], v[4:7]
	s_waitcnt vmcnt(15)
	ds_write_b128 v167, v[100:103] offset:61440
	v_add_co_u32_e32 v100, vcc, s73, v160
	s_nop 1
	v_addc_co_u32_e32 v101, vcc, 0, v161, vcc
	global_load_dwordx4 v[100:103], v[100:101], off
	s_waitcnt lgkmcnt(0)
	s_barrier
; template <int NJ>
; __device__ __forceinline__ void gemm_tile(const f16* __restrict__ A, int lda, const f16* __restrict__ Bt, int ldb,
;                                           int K, f32x4 (&acc)[4][NJ], f16* sA, f16* sB, const int tid) {
;     ...
;     {
;       const int kof = (k0 + 256 < K) ? k0 + 256 : K - 64;
;       G_STEP(1, ra0, rb0, true, true, kof)
;     }
;     __syncthreads();
	ds_read_b128 v[200:203], v168 offset:49152
	ds_read_b128 v[204:207], v168 offset:51200
	ds_read_b128 v[208:211], v168 offset:53248
	ds_read_b128 v[212:215], v168 offset:55296
	ds_read_b128 v[132:135], v170 offset:32768
	ds_read_b128 v[160:163], v170 offset:34816
	ds_read_b128 v[192:195], v170 offset:36864
	ds_read_b128 v[196:199], v170 offset:38912
	ds_read_b128 v[244:247], v243 offset:49152
	ds_read_b128 v[248:251], v243 offset:51200
	ds_read_b128 v[252:255], v243 offset:53248
	s_waitcnt lgkmcnt(6)
	v_mfma_f32_16x16x32_f16 v[64:67], v[200:203], v[132:135], v[64:67]
	v_mfma_f32_16x16x32_f16 v[60:63], v[204:207], v[132:135], v[60:63]
	v_mfma_f32_16x16x32_f16 v[56:59], v[208:211], v[132:135], v[56:59]
	v_mfma_f32_16x16x32_f16 v[52:55], v[212:215], v[132:135], v[52:55]
	ds_read_b128 v[132:135], v243 offset:55296
	s_waitcnt vmcnt(13)
	ds_write_b128 v167, v[92:95]
	global_load_dwordx4 v[92:95], v[218:219], off
	s_waitcnt lgkmcnt(7)
	v_mfma_f32_16x16x32_f16 v[48:51], v[200:203], v[160:163], v[48:51]
	v_mfma_f32_16x16x32_f16 v[44:47], v[204:207], v[160:163], v[44:47]
	v_mfma_f32_16x16x32_f16 v[40:43], v[208:211], v[160:163], v[40:43]
	v_mfma_f32_16x16x32_f16 v[36:39], v[212:215], v[160:163], v[36:39]
	ds_read_b128 v[160:163], v242 offset:32768
	ds_write_b128 v167, v[108:111] offset:4096
	v_add_co_u32_e32 v108, vcc, s94, v218
	s_nop 1
	v_addc_co_u32_e32 v109, vcc, 0, v219, vcc
	global_load_dwordx4 v[108:111], v[108:109], off
	s_waitcnt lgkmcnt(8)
	v_mfma_f32_16x16x32_f16 v[32:35], v[200:203], v[192:195], v[32:35]
	v_mfma_f32_16x16x32_f16 v[28:31], v[204:207], v[192:195], v[28:31]
	v_mfma_f32_16x16x32_f16 v[24:27], v[208:211], v[192:195], v[24:27]
	v_mfma_f32_16x16x32_f16 v[20:23], v[212:215], v[192:195], v[20:23]
	ds_read_b128 v[192:195], v242 offset:34816
	ds_write_b128 v167, v[112:115] offset:8192
	v_add_co_u32_e32 v112, vcc, s72, v218
	s_nop 1
	v_addc_co_u32_e32 v113, vcc, 0, v219, vcc
	global_load_dwordx4 v[112:115], v[112:113], off
	s_waitcnt lgkmcnt(9)
	v_mfma_f32_16x16x32_f16 v[16:19], v[200:203], v[196:199], v[16:19]
	v_mfma_f32_16x16x32_f16 v[12:15], v[204:207], v[196:199], v[12:15]
	v_mfma_f32_16x16x32_f16 v[8:11], v[208:211], v[196:199], v[8:11]
	v_mfma_f32_16x16x32_f16 v[4:7], v[212:215], v[196:199], v[4:7]
	ds_read_b128 v[196:199], v242 offset:36864
	ds_read_b128 v[200:203], v242 offset:38912
	s_waitcnt vmcnt(14)
	ds_write_b128 v167, v[116:119] offset:12288
	v_add_co_u32_e32 v116, vcc, s73, v218
	s_nop 1
	v_addc_co_u32_e32 v117, vcc, 0, v219, vcc
	global_load_dwordx4 v[116:119], v[116:117], off
	s_waitcnt lgkmcnt(6)
	v_mfma_f32_16x16x32_f16 v[64:67], v[244:247], v[160:163], v[64:67]
	v_mfma_f32_16x16x32_f16 v[60:63], v[248:251], v[160:163], v[60:63]
	v_mfma_f32_16x16x32_f16 v[56:59], v[252:255], v[160:163], v[56:59]
	v_mfma_f32_16x16x32_f16 v[52:55], v[132:135], v[160:163], v[52:55]
	ds_write_b128 v167, v[104:107] offset:16384
	global_load_dwordx4 v[104:107], v[216:217], off
	s_waitcnt lgkmcnt(5)
	v_mfma_f32_16x16x32_f16 v[48:51], v[244:247], v[192:195], v[48:51]
	v_mfma_f32_16x16x32_f16 v[44:47], v[248:251], v[192:195], v[44:47]
	v_mfma_f32_16x16x32_f16 v[40:43], v[252:255], v[192:195], v[40:43]
	v_mfma_f32_16x16x32_f16 v[36:39], v[132:135], v[192:195], v[36:39]
	s_waitcnt vmcnt(15)
	ds_write_b128 v167, v[120:123] offset:20480
	v_add_co_u32_e32 v120, vcc, s94, v216
	s_nop 1
	v_addc_co_u32_e32 v121, vcc, 0, v217, vcc
	global_load_dwordx4 v[120:123], v[120:121], off
	s_waitcnt lgkmcnt(4)
	v_mfma_f32_16x16x32_f16 v[32:35], v[244:247], v[196:199], v[32:35]
	v_mfma_f32_16x16x32_f16 v[28:31], v[248:251], v[196:199], v[28:31]
	v_mfma_f32_16x16x32_f16 v[24:27], v[252:255], v[196:199], v[24:27]
	v_mfma_f32_16x16x32_f16 v[20:23], v[132:135], v[196:199], v[20:23]
	s_waitcnt vmcnt(15)
	ds_write_b128 v167, v[124:127] offset:24576
	v_add_co_u32_e32 v124, vcc, s72, v216
	s_nop 1
	v_addc_co_u32_e32 v125, vcc, 0, v217, vcc
	global_load_dwordx4 v[124:127], v[124:125], off
	s_waitcnt lgkmcnt(4)
	v_mfma_f32_16x16x32_f16 v[16:19], v[244:247], v[200:203], v[16:19]
	v_mfma_f32_16x16x32_f16 v[12:15], v[248:251], v[200:203], v[12:15]
	v_mfma_f32_16x16x32_f16 v[8:11], v[252:255], v[200:203], v[8:11]
	v_mfma_f32_16x16x32_f16 v[4:7], v[132:135], v[200:203], v[4:7]
	s_waitcnt vmcnt(15)
	ds_write_b128 v167, v[128:131] offset:28672
	v_add_co_u32_e32 v128, vcc, s73, v216
	s_nop 1
	v_addc_co_u32_e32 v129, vcc, 0, v217, vcc
	global_load_dwordx4 v[128:131], v[128:129], off
	s_waitcnt lgkmcnt(0)
	s_barrier
	s_cbranch_scc1 .LBB0_195
; template <int NJ>
; __device__ __forceinline__ void gemm_tile(const f16* __restrict__ A, int lda, const f16* __restrict__ Bt, int ldb,
;                                           int K, f32x4 (&acc)[4][NJ], f16* sA, f16* sB, const int tid) {
;     ...
;   G_LOAD(ra0, rb0, 0)
;   if (K > 64) G_LOAD(ra1, rb1, 64)
;   __syncthreads();
;   G_STORE(ra0, rb0, 0)
;   if (K > 128) G_LOAD(ra0, rb0, 128)
;   __syncthreads();
; #pragma unroll 1
;   for (int k0 = 0; k0 < K; k0 += 128) {
;     {
;       const int kof = (k0 + 192 < K) ? k0 + 192 : K - 64;
;       G_STEP(0, ra1, rb1, true, true, kof)
	ds_read_b128 v[204:207], v168 offset:16384
	ds_read_b128 v[208:211], v168 offset:18432
	ds_read_b128 v[212:215], v168 offset:20480
	ds_read_b128 v[216:219], v168 offset:22528
	s_add_i32 s7, s6, 0xc0
	ds_read_b128 v[192:195], v170
	ds_read_b128 v[196:199], v170 offset:2048
	s_cmpk_lt_u32 s6, 0x340
	s_cselect_b32 s42, s7, 0x3c0
	ds_read_b128 v[200:203], v170 offset:4096
	s_lshl_b64 s[8:9], s[42:43], 1
	v_lshl_add_u64 v[162:163], v[156:157], 0, s[8:9]
	ds_read_b128 v[132:135], v170 offset:6144
	ds_read_b128 v[244:247], v243 offset:16384
	ds_read_b128 v[248:251], v243 offset:18432
	ds_read_b128 v[252:255], v243 offset:20480
	s_waitcnt lgkmcnt(6)
	v_mfma_f32_16x16x32_f16 v[64:67], v[204:207], v[192:195], v[64:67]
	v_lshl_add_u64 v[160:161], v[158:159], 0, s[8:9]
	s_add_i32 s7, s6, 0x100
	s_cmpk_lt_u32 s6, 0x300
	v_mfma_f32_16x16x32_f16 v[60:63], v[208:211], v[192:195], v[60:63]
	s_cselect_b32 s42, s7, 0x3c0
	s_lshl_b64 s[8:9], s[42:43], 1
	s_add_i32 s7, s6, 0x80
	v_mfma_f32_16x16x32_f16 v[56:59], v[212:215], v[192:195], v[56:59]
	s_cmpk_lt_u32 s6, 0x380
	s_mov_b32 s6, s7
	v_mfma_f32_16x16x32_f16 v[52:55], v[216:219], v[192:195], v[52:55]
	ds_read_b128 v[192:195], v243 offset:22528
	s_waitcnt vmcnt(15)
	ds_write_b128 v167, v[68:71] offset:32768
	global_load_dwordx4 v[68:71], v[162:163], off
	s_waitcnt lgkmcnt(7)
	v_mfma_f32_16x16x32_f16 v[48:51], v[204:207], v[196:199], v[48:51]
	v_mfma_f32_16x16x32_f16 v[44:47], v[208:211], v[196:199], v[44:47]
	v_mfma_f32_16x16x32_f16 v[40:43], v[212:215], v[196:199], v[40:43]
	v_mfma_f32_16x16x32_f16 v[36:39], v[216:219], v[196:199], v[36:39]
	ds_read_b128 v[196:199], v242
	s_waitcnt vmcnt(15)
	ds_write_b128 v167, v[76:79] offset:36864
	v_add_co_u32_e32 v76, vcc, s94, v162
	s_nop 1
	v_addc_co_u32_e32 v77, vcc, 0, v163, vcc
	global_load_dwordx4 v[76:79], v[76:77], off
	s_waitcnt lgkmcnt(8)
	v_mfma_f32_16x16x32_f16 v[32:35], v[204:207], v[200:203], v[32:35]
	v_mfma_f32_16x16x32_f16 v[28:31], v[208:211], v[200:203], v[28:31]
	v_mfma_f32_16x16x32_f16 v[24:27], v[212:215], v[200:203], v[24:27]
	v_mfma_f32_16x16x32_f16 v[20:23], v[216:219], v[200:203], v[20:23]
	ds_read_b128 v[200:203], v242 offset:2048
	s_waitcnt vmcnt(15)
	ds_write_b128 v167, v[80:83] offset:40960
	v_add_co_u32_e32 v80, vcc, s72, v162
	s_nop 1
	v_addc_co_u32_e32 v81, vcc, 0, v163, vcc
	global_load_dwordx4 v[80:83], v[80:81], off
	s_waitcnt lgkmcnt(9)
	v_mfma_f32_16x16x32_f16 v[16:19], v[204:207], v[132:135], v[16:19]
	v_mfma_f32_16x16x32_f16 v[12:15], v[208:211], v[132:135], v[12:15]
	v_mfma_f32_16x16x32_f16 v[8:11], v[212:215], v[132:135], v[8:11]
	v_mfma_f32_16x16x32_f16 v[4:7], v[216:219], v[132:135], v[4:7]
	ds_read_b128 v[132:135], v242 offset:4096
	ds_read_b128 v[204:207], v242 offset:6144
	s_waitcnt vmcnt(15)
	ds_write_b128 v167, v[84:87] offset:45056
	v_add_co_u32_e32 v84, vcc, s73, v162
	s_nop 1
	v_addc_co_u32_e32 v85, vcc, 0, v163, vcc
	global_load_dwordx4 v[84:87], v[84:85], off
	s_waitcnt lgkmcnt(6)
	v_mfma_f32_16x16x32_f16 v[64:67], v[244:247], v[196:199], v[64:67]
	v_mfma_f32_16x16x32_f16 v[60:63], v[248:251], v[196:199], v[60:63]
	v_mfma_f32_16x16x32_f16 v[56:59], v[252:255], v[196:199], v[56:59]
	v_mfma_f32_16x16x32_f16 v[52:55], v[192:195], v[196:199], v[52:55]
	s_waitcnt vmcnt(15)
	ds_write_b128 v167, v[72:75] offset:49152
	global_load_dwordx4 v[72:75], v[160:161], off
	v_lshl_add_u64 v[218:219], v[156:157], 0, s[8:9]
	s_waitcnt lgkmcnt(5)
	v_mfma_f32_16x16x32_f16 v[48:51], v[244:247], v[200:203], v[48:51]
	v_lshl_add_u64 v[216:217], v[158:159], 0, s[8:9]
	v_mfma_f32_16x16x32_f16 v[44:47], v[248:251], v[200:203], v[44:47]
	v_mfma_f32_16x16x32_f16 v[40:43], v[252:255], v[200:203], v[40:43]
	v_mfma_f32_16x16x32_f16 v[36:39], v[192:195], v[200:203], v[36:39]
	s_waitcnt vmcnt(15)
	ds_write_b128 v167, v[88:91] offset:53248
	v_add_co_u32_e32 v88, vcc, s94, v160
	s_nop 1
	v_addc_co_u32_e32 v89, vcc, 0, v161, vcc
	global_load_dwordx4 v[88:91], v[88:89], off
	s_waitcnt lgkmcnt(4)
	v_mfma_f32_16x16x32_f16 v[32:35], v[244:247], v[132:135], v[32:35]
	v_mfma_f32_16x16x32_f16 v[28:31], v[248:251], v[132:135], v[28:31]
	v_mfma_f32_16x16x32_f16 v[24:27], v[252:255], v[132:135], v[24:27]
	v_mfma_f32_16x16x32_f16 v[20:23], v[192:195], v[132:135], v[20:23]
	s_waitcnt vmcnt(15)
	ds_write_b128 v167, v[96:99] offset:57344
	v_add_co_u32_e32 v96, vcc, s72, v160
	s_nop 1
	v_addc_co_u32_e32 v97, vcc, 0, v161, vcc
	global_load_dwordx4 v[96:99], v[96:97], off
	s_waitcnt lgkmcnt(4)
	v_mfma_f32_16x16x32_f16 v[16:19], v[244:247], v[204:207], v[16:19]
	v_mfma_f32_16x16x32_f16 v[12:15], v[248:251], v[204:207], v[12:15]
	v_mfma_f32_16x16x32_f16 v[8:11], v[252:255], v[204:207], v[8:11]
	v_mfma_f32_16x16x32_f16 v[4:7], v[192:195], v[204:207], v[4:7]
	s_waitcnt vmcnt(15)
	ds_write_b128 v167, v[100:103] offset:61440
	v_add_co_u32_e32 v100, vcc, s73, v160
	s_nop 1
	v_addc_co_u32_e32 v101, vcc, 0, v161, vcc
	global_load_dwordx4 v[100:103], v[100:101], off
	s_waitcnt lgkmcnt(0)
	s_barrier
; template <int NJ>
; __device__ __forceinline__ void gemm_tile(const f16* __restrict__ A, int lda, const f16* __restrict__ Bt, int ldb,
;                                           int K, f32x4 (&acc)[4][NJ], f16* sA, f16* sB, const int tid) {
;     ...
;   G_LOAD(ra0, rb0, 0)
;   if (K > 64) G_LOAD(ra1, rb1, 64)
;   __syncthreads();
;   G_STORE(ra0, rb0, 0)
;   if (K > 128) G_LOAD(ra0, rb0, 128)
;   __syncthreads();
; #pragma unroll 1
;   for (int k0 = 0; k0 < K; k0 += 128) {
;     {
;       const int kof = (k0 + 192 < K) ? k0 + 192 : K - 64;
;       G_STEP(0, ra1, rb1, true, true, kof)
;     }
;     __syncthreads();
;     if (k0 + 64 >= K) break;
;     {
;       const int kof = (k0 + 256 < K) ? k0 + 256 : K - 64;
;       G_STEP(1, ra0, rb0, true, true, kof)
	ds_read_b128 v[200:203], v168 offset:49152
	ds_read_b128 v[204:207], v168 offset:51200
	ds_read_b128 v[208:211], v168 offset:53248
	ds_read_b128 v[212:215], v168 offset:55296
	ds_read_b128 v[132:135], v170 offset:32768
	ds_read_b128 v[160:163], v170 offset:34816
	ds_read_b128 v[192:195], v170 offset:36864
	ds_read_b128 v[196:199], v170 offset:38912
	ds_read_b128 v[244:247], v243 offset:49152
	ds_read_b128 v[248:251], v243 offset:51200
	ds_read_b128 v[252:255], v243 offset:53248
	s_waitcnt lgkmcnt(6)
	v_mfma_f32_16x16x32_f16 v[64:67], v[200:203], v[132:135], v[64:67]
	v_mfma_f32_16x16x32_f16 v[60:63], v[204:207], v[132:135], v[60:63]
	v_mfma_f32_16x16x32_f16 v[56:59], v[208:211], v[132:135], v[56:59]
	v_mfma_f32_16x16x32_f16 v[52:55], v[212:215], v[132:135], v[52:55]
	ds_read_b128 v[132:135], v243 offset:55296
	s_waitcnt vmcnt(15)
	ds_write_b128 v167, v[92:95]
	s_waitcnt lgkmcnt(7)
	v_mfma_f32_16x16x32_f16 v[48:51], v[200:203], v[160:163], v[48:51]
	v_mfma_f32_16x16x32_f16 v[44:47], v[204:207], v[160:163], v[44:47]
	v_mfma_f32_16x16x32_f16 v[40:43], v[208:211], v[160:163], v[40:43]
	v_mfma_f32_16x16x32_f16 v[36:39], v[212:215], v[160:163], v[36:39]
	ds_read_b128 v[160:163], v242 offset:32768
	s_waitcnt vmcnt(14)
	ds_write_b128 v167, v[108:111] offset:4096
	s_waitcnt lgkmcnt(8)
	v_mfma_f32_16x16x32_f16 v[32:35], v[200:203], v[192:195], v[32:35]
	v_mfma_f32_16x16x32_f16 v[28:31], v[204:207], v[192:195], v[28:31]
	v_mfma_f32_16x16x32_f16 v[24:27], v[208:211], v[192:195], v[24:27]
	v_mfma_f32_16x16x32_f16 v[20:23], v[212:215], v[192:195], v[20:23]
	ds_read_b128 v[192:195], v242 offset:34816
	s_waitcnt vmcnt(13)
	ds_write_b128 v167, v[112:115] offset:8192
	s_waitcnt lgkmcnt(9)
	v_mfma_f32_16x16x32_f16 v[16:19], v[200:203], v[196:199], v[16:19]
	v_mfma_f32_16x16x32_f16 v[12:15], v[204:207], v[196:199], v[12:15]
	v_mfma_f32_16x16x32_f16 v[8:11], v[208:211], v[196:199], v[8:11]
	v_mfma_f32_16x16x32_f16 v[4:7], v[212:215], v[196:199], v[4:7]
	ds_read_b128 v[196:199], v242 offset:36864
	ds_read_b128 v[200:203], v242 offset:38912
	s_waitcnt vmcnt(12)
	ds_write_b128 v167, v[116:119] offset:12288
	s_waitcnt lgkmcnt(6)
	v_mfma_f32_16x16x32_f16 v[64:67], v[244:247], v[160:163], v[64:67]
	v_mfma_f32_16x16x32_f16 v[60:63], v[248:251], v[160:163], v[60:63]
	v_mfma_f32_16x16x32_f16 v[56:59], v[252:255], v[160:163], v[56:59]
	v_mfma_f32_16x16x32_f16 v[52:55], v[132:135], v[160:163], v[52:55]
	s_waitcnt vmcnt(11)
	ds_write_b128 v167, v[104:107] offset:16384
	s_waitcnt lgkmcnt(5)
	v_mfma_f32_16x16x32_f16 v[48:51], v[244:247], v[192:195], v[48:51]
	v_mfma_f32_16x16x32_f16 v[44:47], v[248:251], v[192:195], v[44:47]
	v_mfma_f32_16x16x32_f16 v[40:43], v[252:255], v[192:195], v[40:43]
	v_mfma_f32_16x16x32_f16 v[36:39], v[132:135], v[192:195], v[36:39]
	s_waitcnt vmcnt(10)
	ds_write_b128 v167, v[120:123] offset:20480
	s_waitcnt lgkmcnt(4)
	v_mfma_f32_16x16x32_f16 v[32:35], v[244:247], v[196:199], v[32:35]
	v_mfma_f32_16x16x32_f16 v[28:31], v[248:251], v[196:199], v[28:31]
	v_mfma_f32_16x16x32_f16 v[24:27], v[252:255], v[196:199], v[24:27]
	v_mfma_f32_16x16x32_f16 v[20:23], v[132:135], v[196:199], v[20:23]
	s_waitcnt vmcnt(9)
	ds_write_b128 v167, v[124:127] offset:24576
	s_waitcnt lgkmcnt(4)
	v_mfma_f32_16x16x32_f16 v[16:19], v[244:247], v[200:203], v[16:19]
	v_mfma_f32_16x16x32_f16 v[12:15], v[248:251], v[200:203], v[12:15]
	v_mfma_f32_16x16x32_f16 v[8:11], v[252:255], v[200:203], v[8:11]
	v_mfma_f32_16x16x32_f16 v[4:7], v[132:135], v[200:203], v[4:7]
	s_waitcnt vmcnt(8)
	ds_write_b128 v167, v[128:131] offset:28672
	s_waitcnt lgkmcnt(0)
	s_barrier
	ds_read_b128 v[204:207], v168 offset:16384
	ds_read_b128 v[208:211], v168 offset:18432
	ds_read_b128 v[212:215], v168 offset:20480
	ds_read_b128 v[216:219], v168 offset:22528
	s_add_i32 s7, s6, 0xc0
	ds_read_b128 v[192:195], v170
	ds_read_b128 v[196:199], v170 offset:2048
	s_cmpk_lt_u32 s6, 0x340
	s_cselect_b32 s42, s7, 0x3c0
	ds_read_b128 v[200:203], v170 offset:4096
	s_lshl_b64 s[8:9], s[42:43], 1
	v_lshl_add_u64 v[162:163], v[156:157], 0, s[8:9]
	ds_read_b128 v[132:135], v170 offset:6144
	ds_read_b128 v[244:247], v243 offset:16384
	ds_read_b128 v[248:251], v243 offset:18432
	ds_read_b128 v[252:255], v243 offset:20480
	s_waitcnt lgkmcnt(6)
	v_mfma_f32_16x16x32_f16 v[64:67], v[204:207], v[192:195], v[64:67]
	v_lshl_add_u64 v[160:161], v[158:159], 0, s[8:9]
	s_add_i32 s7, s6, 0x100
	s_cmpk_lt_u32 s6, 0x300
	v_mfma_f32_16x16x32_f16 v[60:63], v[208:211], v[192:195], v[60:63]
	s_cselect_b32 s42, s7, 0x3c0
	s_lshl_b64 s[8:9], s[42:43], 1
	s_add_i32 s7, s6, 0x80
	v_mfma_f32_16x16x32_f16 v[56:59], v[212:215], v[192:195], v[56:59]
	s_cmpk_lt_u32 s6, 0x380
	s_mov_b32 s6, s7
	v_mfma_f32_16x16x32_f16 v[52:55], v[216:219], v[192:195], v[52:55]
	ds_read_b128 v[192:195], v243 offset:22528
	s_waitcnt vmcnt(7)
	ds_write_b128 v167, v[68:71] offset:32768
	s_waitcnt lgkmcnt(7)
	v_mfma_f32_16x16x32_f16 v[48:51], v[204:207], v[196:199], v[48:51]
	v_mfma_f32_16x16x32_f16 v[44:47], v[208:211], v[196:199], v[44:47]
	v_mfma_f32_16x16x32_f16 v[40:43], v[212:215], v[196:199], v[40:43]
	v_mfma_f32_16x16x32_f16 v[36:39], v[216:219], v[196:199], v[36:39]
	ds_read_b128 v[196:199], v242
	s_waitcnt vmcnt(6)
	ds_write_b128 v167, v[76:79] offset:36864
	s_waitcnt lgkmcnt(8)
	v_mfma_f32_16x16x32_f16 v[32:35], v[204:207], v[200:203], v[32:35]
	v_mfma_f32_16x16x32_f16 v[28:31], v[208:211], v[200:203], v[28:31]
	v_mfma_f32_16x16x32_f16 v[24:27], v[212:215], v[200:203], v[24:27]
	v_mfma_f32_16x16x32_f16 v[20:23], v[216:219], v[200:203], v[20:23]
	ds_read_b128 v[200:203], v242 offset:2048
	s_waitcnt vmcnt(5)
; template <int NJ>
; __device__ __forceinline__ void gemm_tile(const f16* __restrict__ A, int lda, const f16* __restrict__ Bt, int ldb,
;                                           int K, f32x4 (&acc)[4][NJ], f16* sA, f16* sB, const int tid) {
;     ...
;   G_LOAD(ra0, rb0, 0)
;   if (K > 64) G_LOAD(ra1, rb1, 64)
;   __syncthreads();
;   G_STORE(ra0, rb0, 0)
;   if (K > 128) G_LOAD(ra0, rb0, 128)
;   __syncthreads();
; #pragma unroll 1
;   for (int k0 = 0; k0 < K; k0 += 128) {
;     {
;       const int kof = (k0 + 192 < K) ? k0 + 192 : K - 64;
;       G_STEP(0, ra1, rb1, true, true, kof)
;     }
;     __syncthreads();
;     if (k0 + 64 >= K) break;
;     {
;       const int kof = (k0 + 256 < K) ? k0 + 256 : K - 64;
;       G_STEP(1, ra0, rb0, true, true, kof)
;     }
;     __syncthreads();
;   }
; __device__ __forceinline__ void phase_g1(const Params& p, int l, f16* smem) {
;     ...
;     } else {
; #pragma unroll
;       for (int i = 0; i < 4; ++i) {
;         int m = m0 + wm * 64 + i * 16 + (lane & 15);
; #pragma unroll
;         for (int j = 0; j < 4; ++j) {
;           int n = n0 + wn * 64 + j * 16 + 4 * (lane >> 4);
;           if (n < N1) {
;             f16x4 o;
;             o[0] = (f16)acc[i][j][0];
;             o[1] = (f16)acc[i][j][1];
;             o[2] = (f16)acc[i][j][2];
;             o[3] = (f16)acc[i][j][3];
;             *(f16x4*)(proj + (size_t)m * PJ + (n - 384)) = o;
;           }
;         }
	ds_write_b128 v167, v[80:83] offset:40960
	s_waitcnt lgkmcnt(9)
	v_mfma_f32_16x16x32_f16 v[16:19], v[204:207], v[132:135], v[16:19]
	v_mfma_f32_16x16x32_f16 v[12:15], v[208:211], v[132:135], v[12:15]
	v_mfma_f32_16x16x32_f16 v[8:11], v[212:215], v[132:135], v[8:11]
	v_mfma_f32_16x16x32_f16 v[4:7], v[216:219], v[132:135], v[4:7]
	ds_read_b128 v[132:135], v242 offset:4096
	ds_read_b128 v[204:207], v242 offset:6144
	s_waitcnt vmcnt(4)
	ds_write_b128 v167, v[84:87] offset:45056
	s_waitcnt lgkmcnt(6)
	v_mfma_f32_16x16x32_f16 v[64:67], v[244:247], v[196:199], v[64:67]
	v_mfma_f32_16x16x32_f16 v[60:63], v[248:251], v[196:199], v[60:63]
	v_mfma_f32_16x16x32_f16 v[56:59], v[252:255], v[196:199], v[56:59]
	v_mfma_f32_16x16x32_f16 v[52:55], v[192:195], v[196:199], v[52:55]
	s_waitcnt vmcnt(3)
	ds_write_b128 v167, v[72:75] offset:49152
	v_lshl_add_u64 v[218:219], v[156:157], 0, s[8:9]
	s_waitcnt lgkmcnt(5)
	v_mfma_f32_16x16x32_f16 v[48:51], v[244:247], v[200:203], v[48:51]
	v_lshl_add_u64 v[216:217], v[158:159], 0, s[8:9]
	v_mfma_f32_16x16x32_f16 v[44:47], v[248:251], v[200:203], v[44:47]
	v_mfma_f32_16x16x32_f16 v[40:43], v[252:255], v[200:203], v[40:43]
	v_mfma_f32_16x16x32_f16 v[36:39], v[192:195], v[200:203], v[36:39]
	s_waitcnt vmcnt(2)
	ds_write_b128 v167, v[88:91] offset:53248
	s_waitcnt lgkmcnt(4)
	v_mfma_f32_16x16x32_f16 v[32:35], v[244:247], v[132:135], v[32:35]
	v_mfma_f32_16x16x32_f16 v[28:31], v[248:251], v[132:135], v[28:31]
	v_mfma_f32_16x16x32_f16 v[24:27], v[252:255], v[132:135], v[24:27]
	v_mfma_f32_16x16x32_f16 v[20:23], v[192:195], v[132:135], v[20:23]
	s_waitcnt vmcnt(1)
	ds_write_b128 v167, v[96:99] offset:57344
	s_waitcnt lgkmcnt(4)
	v_mfma_f32_16x16x32_f16 v[16:19], v[244:247], v[204:207], v[16:19]
	v_mfma_f32_16x16x32_f16 v[12:15], v[248:251], v[204:207], v[12:15]
	v_mfma_f32_16x16x32_f16 v[8:11], v[252:255], v[204:207], v[8:11]
	v_mfma_f32_16x16x32_f16 v[4:7], v[192:195], v[204:207], v[4:7]
	s_waitcnt vmcnt(0)
	ds_write_b128 v167, v[100:103] offset:61440
	s_waitcnt lgkmcnt(0)
	s_barrier
	ds_read_b128 v[200:203], v168 offset:49152
	ds_read_b128 v[204:207], v168 offset:51200
	ds_read_b128 v[208:211], v168 offset:53248
	ds_read_b128 v[212:215], v168 offset:55296
	ds_read_b128 v[132:135], v170 offset:32768
	ds_read_b128 v[160:163], v170 offset:34816
	ds_read_b128 v[192:195], v170 offset:36864
	ds_read_b128 v[196:199], v170 offset:38912
	ds_read_b128 v[244:247], v243 offset:49152
	ds_read_b128 v[248:251], v243 offset:51200
	ds_read_b128 v[252:255], v243 offset:53248
	s_waitcnt lgkmcnt(6)
	v_mfma_f32_16x16x32_f16 v[64:67], v[200:203], v[132:135], v[64:67]
	v_mfma_f32_16x16x32_f16 v[60:63], v[204:207], v[132:135], v[60:63]
	v_mfma_f32_16x16x32_f16 v[56:59], v[208:211], v[132:135], v[56:59]
	v_mfma_f32_16x16x32_f16 v[52:55], v[212:215], v[132:135], v[52:55]
	ds_read_b128 v[132:135], v243 offset:55296
	s_waitcnt lgkmcnt(6)
	v_mfma_f32_16x16x32_f16 v[48:51], v[200:203], v[160:163], v[48:51]
	v_mfma_f32_16x16x32_f16 v[44:47], v[204:207], v[160:163], v[44:47]
	v_mfma_f32_16x16x32_f16 v[40:43], v[208:211], v[160:163], v[40:43]
	v_mfma_f32_16x16x32_f16 v[36:39], v[212:215], v[160:163], v[36:39]
	ds_read_b128 v[160:163], v242 offset:32768
	s_waitcnt lgkmcnt(6)
	v_mfma_f32_16x16x32_f16 v[32:35], v[200:203], v[192:195], v[32:35]
	v_mfma_f32_16x16x32_f16 v[28:31], v[204:207], v[192:195], v[28:31]
	v_mfma_f32_16x16x32_f16 v[24:27], v[208:211], v[192:195], v[24:27]
	v_mfma_f32_16x16x32_f16 v[20:23], v[212:215], v[192:195], v[20:23]
	ds_read_b128 v[192:195], v242 offset:34816
	s_waitcnt lgkmcnt(6)
	v_mfma_f32_16x16x32_f16 v[16:19], v[200:203], v[196:199], v[16:19]
	v_mfma_f32_16x16x32_f16 v[12:15], v[204:207], v[196:199], v[12:15]
	v_mfma_f32_16x16x32_f16 v[8:11], v[208:211], v[196:199], v[8:11]
	v_mfma_f32_16x16x32_f16 v[4:7], v[212:215], v[196:199], v[4:7]
	ds_read_b128 v[196:199], v242 offset:36864
	ds_read_b128 v[200:203], v242 offset:38912
	s_waitcnt lgkmcnt(3)
	v_mfma_f32_16x16x32_f16 v[64:67], v[244:247], v[160:163], v[64:67]
	v_mfma_f32_16x16x32_f16 v[60:63], v[248:251], v[160:163], v[60:63]
	v_mfma_f32_16x16x32_f16 v[56:59], v[252:255], v[160:163], v[56:59]
	v_mfma_f32_16x16x32_f16 v[52:55], v[132:135], v[160:163], v[52:55]
	s_waitcnt lgkmcnt(2)
	v_mfma_f32_16x16x32_f16 v[48:51], v[244:247], v[192:195], v[48:51]
	v_mfma_f32_16x16x32_f16 v[44:47], v[248:251], v[192:195], v[44:47]
	v_mfma_f32_16x16x32_f16 v[40:43], v[252:255], v[192:195], v[40:43]
	v_mfma_f32_16x16x32_f16 v[36:39], v[132:135], v[192:195], v[36:39]
	s_waitcnt lgkmcnt(1)
	v_mfma_f32_16x16x32_f16 v[32:35], v[244:247], v[196:199], v[32:35]
	v_mfma_f32_16x16x32_f16 v[28:31], v[248:251], v[196:199], v[28:31]
	v_mfma_f32_16x16x32_f16 v[24:27], v[252:255], v[196:199], v[24:27]
	v_mfma_f32_16x16x32_f16 v[20:23], v[132:135], v[196:199], v[20:23]
	s_waitcnt lgkmcnt(0)
	v_mfma_f32_16x16x32_f16 v[16:19], v[244:247], v[200:203], v[16:19]
	v_mfma_f32_16x16x32_f16 v[12:15], v[248:251], v[200:203], v[12:15]
	v_mfma_f32_16x16x32_f16 v[8:11], v[252:255], v[200:203], v[8:11]
	v_mfma_f32_16x16x32_f16 v[4:7], v[132:135], v[200:203], v[4:7]
	s_waitcnt lgkmcnt(0)
	s_barrier
	s_cmp_gt_i32 s21, 5
	s_mov_b64 s[6:7], -1
	s_cbranch_scc0 .LBB0_210
	s_cmp_lt_u32 s21, 9
	s_cbranch_scc1 .LBB0_232
	s_waitcnt vmcnt(15)
	v_add_u32_e32 v70, s14, v143
	v_or_b32_e32 v164, s16, v166
	v_mad_i64_i32 v[68:69], s[6:7], v70, s22, v[144:145]
	v_cmp_gt_i32_e32 vcc, s62, v164
	s_and_saveexec_b64 s[6:7], vcc
	s_cbranch_execz .LBB0_200
	s_waitcnt vmcnt(11)
	v_cvt_pk_f16_f32 v73, v66, v67
	v_cvt_pk_f16_f32 v72, v64, v65
	v_lshl_add_u64 v[74:75], v[164:165], 1, v[68:69]
	global_store_dwordx2 v[74:75], v[72:73], off offset:-768

; template <int NJ>
; __device__ __forceinline__ void gemm_tile(const f16* __restrict__ A, int lda, const f16* __restrict__ Bt, int ldb,
;                                           int K, f32x4 (&acc)[4][NJ], f16* sA, f16* sB, const int tid) {
;     ...
;   G_LOAD(ra0, rb0, 0)
;   if (K > 64) G_LOAD(ra1, rb1, 64)
;   __syncthreads();
;   G_STORE(ra0, rb0, 0)
;   if (K > 128) G_LOAD(ra0, rb0, 128)
;   __syncthreads();
; #pragma unroll 1
;   for (int k0 = 0; k0 < K; k0 += 128) {
;     {
;       const int kof = (k0 + 192 < K) ? k0 + 192 : K - 64;
;       G_STEP(0, ra1, rb1, true, true, kof)
.LBB0_1186:
	ds_read_b128 v[208:211], v192 offset:16384
	ds_read_b128 v[212:215], v192 offset:18432
	ds_read_b128 v[216:219], v192 offset:20480
	ds_read_b128 v[220:223], v192 offset:22528
	s_add_i32 s10, s9, 0xc0
	ds_read_b128 v[196:199], v170
	ds_read_b128 v[200:203], v170 offset:2048
	s_cmpk_lt_u32 s9, 0x340
	s_cselect_b32 s42, s10, 0x3c0
	ds_read_b128 v[204:207], v170 offset:4096
	s_lshl_b64 s[10:11], s[42:43], 1
	v_lshl_add_u64 v[160:161], v[154:155], 0, s[10:11]
	ds_read_b128 v[130:133], v170 offset:6144
	ds_read_b128 v[244:247], v243 offset:16384
	ds_read_b128 v[248:251], v243 offset:18432
	ds_read_b128 v[252:255], v243 offset:20480
	s_waitcnt lgkmcnt(6)
	v_mfma_f32_16x16x32_f16 v[126:129], v[208:211], v[196:199], v[126:129]
	v_lshl_add_u64 v[158:159], v[156:157], 0, s[10:11]
	s_add_i32 s10, s9, 0x100
	s_cmpk_lt_u32 s9, 0x300
	v_mfma_f32_16x16x32_f16 v[122:125], v[212:215], v[196:199], v[122:125]
	s_cselect_b32 s42, s10, 0x3c0
	s_lshl_b64 s[10:11], s[42:43], 1
	v_mfma_f32_16x16x32_f16 v[118:121], v[216:219], v[196:199], v[118:121]
	v_mfma_f32_16x16x32_f16 v[114:117], v[220:223], v[196:199], v[114:117]
	ds_read_b128 v[196:199], v243 offset:22528
	s_waitcnt vmcnt(15)
	ds_write_b128 v169, v[34:37] offset:32768
	global_load_dwordx4 v[34:37], v[160:161], off
	s_waitcnt lgkmcnt(7)
	v_mfma_f32_16x16x32_f16 v[110:113], v[208:211], v[200:203], v[110:113]
	v_mfma_f32_16x16x32_f16 v[106:109], v[212:215], v[200:203], v[106:109]
	v_mfma_f32_16x16x32_f16 v[102:105], v[216:219], v[200:203], v[102:105]
	v_mfma_f32_16x16x32_f16 v[98:101], v[220:223], v[200:203], v[98:101]
	ds_read_b128 v[200:203], v242
	s_waitcnt vmcnt(15)
	ds_write_b128 v169, v[42:45] offset:36864
	v_add_co_u32_e32 v42, vcc, s94, v160
	s_nop 1
	v_addc_co_u32_e32 v43, vcc, 0, v161, vcc
	global_load_dwordx4 v[42:45], v[42:43], off
	s_waitcnt lgkmcnt(8)
	v_mfma_f32_16x16x32_f16 v[30:33], v[208:211], v[204:207], v[30:33]
	v_mfma_f32_16x16x32_f16 v[26:29], v[212:215], v[204:207], v[26:29]
	v_mfma_f32_16x16x32_f16 v[22:25], v[216:219], v[204:207], v[22:25]
	v_mfma_f32_16x16x32_f16 v[18:21], v[220:223], v[204:207], v[18:21]
	ds_read_b128 v[204:207], v242 offset:2048
	s_waitcnt vmcnt(15)
	ds_write_b128 v169, v[46:49] offset:40960
	v_add_co_u32_e32 v46, vcc, s72, v160
	s_nop 1
	v_addc_co_u32_e32 v47, vcc, 0, v161, vcc
	global_load_dwordx4 v[46:49], v[46:47], off
	s_waitcnt lgkmcnt(9)
	v_mfma_f32_16x16x32_f16 v[14:17], v[208:211], v[130:133], v[14:17]
	v_mfma_f32_16x16x32_f16 v[10:13], v[212:215], v[130:133], v[10:13]
	v_mfma_f32_16x16x32_f16 v[6:9], v[216:219], v[130:133], v[6:9]
	v_mfma_f32_16x16x32_f16 v[2:5], v[220:223], v[130:133], v[2:5]
	ds_read_b128 v[130:133], v242 offset:4096
	ds_read_b128 v[208:211], v242 offset:6144
	s_waitcnt vmcnt(15)
	ds_write_b128 v169, v[50:53] offset:45056
	v_add_co_u32_e32 v50, vcc, s73, v160
	s_nop 1
	v_addc_co_u32_e32 v51, vcc, 0, v161, vcc
	global_load_dwordx4 v[50:53], v[50:51], off
	s_waitcnt lgkmcnt(6)
	v_mfma_f32_16x16x32_f16 v[126:129], v[244:247], v[200:203], v[126:129]
	v_mfma_f32_16x16x32_f16 v[122:125], v[248:251], v[200:203], v[122:125]
	v_mfma_f32_16x16x32_f16 v[118:121], v[252:255], v[200:203], v[118:121]
	v_mfma_f32_16x16x32_f16 v[114:117], v[196:199], v[200:203], v[114:117]
	s_waitcnt vmcnt(15)
	ds_write_b128 v169, v[38:41] offset:49152
	global_load_dwordx4 v[38:41], v[158:159], off
	v_lshl_add_u64 v[222:223], v[154:155], 0, s[10:11]
	s_waitcnt lgkmcnt(5)
	v_mfma_f32_16x16x32_f16 v[110:113], v[244:247], v[204:207], v[110:113]
	v_lshl_add_u64 v[220:221], v[156:157], 0, s[10:11]
	s_add_i32 s10, s9, 0x80
	s_cmpk_lt_u32 s9, 0x280
	v_mfma_f32_16x16x32_f16 v[106:109], v[248:251], v[204:207], v[106:109]
	s_mov_b32 s9, s10
	v_mfma_f32_16x16x32_f16 v[102:105], v[252:255], v[204:207], v[102:105]
	v_mfma_f32_16x16x32_f16 v[98:101], v[196:199], v[204:207], v[98:101]
	s_waitcnt vmcnt(15)
	ds_write_b128 v169, v[54:57] offset:53248
	v_add_co_u32_e32 v54, vcc, s94, v158
	s_nop 1
	v_addc_co_u32_e32 v55, vcc, 0, v159, vcc
	global_load_dwordx4 v[54:57], v[54:55], off
	s_waitcnt lgkmcnt(4)
	v_mfma_f32_16x16x32_f16 v[30:33], v[244:247], v[130:133], v[30:33]
	v_mfma_f32_16x16x32_f16 v[26:29], v[248:251], v[130:133], v[26:29]
	v_mfma_f32_16x16x32_f16 v[22:25], v[252:255], v[130:133], v[22:25]
	v_mfma_f32_16x16x32_f16 v[18:21], v[196:199], v[130:133], v[18:21]
	s_waitcnt vmcnt(15)
	ds_write_b128 v169, v[62:65] offset:57344
	v_add_co_u32_e32 v62, vcc, s72, v158
	s_nop 1
	v_addc_co_u32_e32 v63, vcc, 0, v159, vcc
	global_load_dwordx4 v[62:65], v[62:63], off
	s_waitcnt lgkmcnt(4)
	v_mfma_f32_16x16x32_f16 v[14:17], v[244:247], v[208:211], v[14:17]
	v_mfma_f32_16x16x32_f16 v[10:13], v[248:251], v[208:211], v[10:13]
	v_mfma_f32_16x16x32_f16 v[6:9], v[252:255], v[208:211], v[6:9]
	v_mfma_f32_16x16x32_f16 v[2:5], v[196:199], v[208:211], v[2:5]
	s_waitcnt vmcnt(15)
	ds_write_b128 v169, v[66:69] offset:61440
	v_add_co_u32_e32 v66, vcc, s73, v158
	s_nop 1
	v_addc_co_u32_e32 v67, vcc, 0, v159, vcc
	global_load_dwordx4 v[66:69], v[66:67], off
	s_waitcnt lgkmcnt(0)
	s_barrier
; template <int NJ>
; __device__ __forceinline__ void gemm_tile(const f16* __restrict__ A, int lda, const f16* __restrict__ Bt, int ldb,
;                                           int K, f32x4 (&acc)[4][NJ], f16* sA, f16* sB, const int tid) {
;     ...
;     {
;       const int kof = (k0 + 256 < K) ? k0 + 256 : K - 64;
;       G_STEP(1, ra0, rb0, true, true, kof)
;     }
;     __syncthreads();
;   }
	ds_read_b128 v[204:207], v192 offset:49152
	ds_read_b128 v[208:211], v192 offset:51200
	ds_read_b128 v[212:215], v192 offset:53248
	ds_read_b128 v[216:219], v192 offset:55296
	ds_read_b128 v[130:133], v170 offset:32768
	ds_read_b128 v[158:161], v170 offset:34816
	ds_read_b128 v[196:199], v170 offset:36864
	ds_read_b128 v[200:203], v170 offset:38912
	ds_read_b128 v[244:247], v243 offset:49152
	ds_read_b128 v[248:251], v243 offset:51200
	ds_read_b128 v[252:255], v243 offset:53248
	s_waitcnt lgkmcnt(6)
	v_mfma_f32_16x16x32_f16 v[126:129], v[204:207], v[130:133], v[126:129]
	v_mfma_f32_16x16x32_f16 v[122:125], v[208:211], v[130:133], v[122:125]
	v_mfma_f32_16x16x32_f16 v[118:121], v[212:215], v[130:133], v[118:121]
	v_mfma_f32_16x16x32_f16 v[114:117], v[216:219], v[130:133], v[114:117]
	ds_read_b128 v[130:133], v243 offset:55296
	s_waitcnt vmcnt(13)
	ds_write_b128 v169, v[58:61]
	global_load_dwordx4 v[58:61], v[222:223], off
	s_waitcnt lgkmcnt(7)
	v_mfma_f32_16x16x32_f16 v[110:113], v[204:207], v[158:161], v[110:113]
	v_mfma_f32_16x16x32_f16 v[106:109], v[208:211], v[158:161], v[106:109]
	v_mfma_f32_16x16x32_f16 v[102:105], v[212:215], v[158:161], v[102:105]
	v_mfma_f32_16x16x32_f16 v[98:101], v[216:219], v[158:161], v[98:101]
	ds_read_b128 v[158:161], v242 offset:32768
	ds_write_b128 v169, v[74:77] offset:4096
	v_add_co_u32_e32 v74, vcc, s94, v222
	s_nop 1
	v_addc_co_u32_e32 v75, vcc, 0, v223, vcc
	global_load_dwordx4 v[74:77], v[74:75], off
	s_waitcnt lgkmcnt(8)
	v_mfma_f32_16x16x32_f16 v[30:33], v[204:207], v[196:199], v[30:33]
	v_mfma_f32_16x16x32_f16 v[26:29], v[208:211], v[196:199], v[26:29]
	v_mfma_f32_16x16x32_f16 v[22:25], v[212:215], v[196:199], v[22:25]
	v_mfma_f32_16x16x32_f16 v[18:21], v[216:219], v[196:199], v[18:21]
	ds_read_b128 v[196:199], v242 offset:34816
	ds_write_b128 v169, v[78:81] offset:8192
	v_add_co_u32_e32 v78, vcc, s72, v222
	s_nop 1
	v_addc_co_u32_e32 v79, vcc, 0, v223, vcc
	global_load_dwordx4 v[78:81], v[78:79], off
	s_waitcnt lgkmcnt(9)
	v_mfma_f32_16x16x32_f16 v[14:17], v[204:207], v[200:203], v[14:17]
	v_mfma_f32_16x16x32_f16 v[10:13], v[208:211], v[200:203], v[10:13]
	v_mfma_f32_16x16x32_f16 v[6:9], v[212:215], v[200:203], v[6:9]
	v_mfma_f32_16x16x32_f16 v[2:5], v[216:219], v[200:203], v[2:5]
	ds_read_b128 v[200:203], v242 offset:36864
	ds_read_b128 v[204:207], v242 offset:38912
	s_waitcnt vmcnt(14)
	ds_write_b128 v169, v[82:85] offset:12288
	v_add_co_u32_e32 v82, vcc, s73, v222
	s_nop 1
	v_addc_co_u32_e32 v83, vcc, 0, v223, vcc
	global_load_dwordx4 v[82:85], v[82:83], off
	s_waitcnt lgkmcnt(6)
	v_mfma_f32_16x16x32_f16 v[126:129], v[244:247], v[158:161], v[126:129]
	v_mfma_f32_16x16x32_f16 v[122:125], v[248:251], v[158:161], v[122:125]
	v_mfma_f32_16x16x32_f16 v[118:121], v[252:255], v[158:161], v[118:121]
	v_mfma_f32_16x16x32_f16 v[114:117], v[130:133], v[158:161], v[114:117]
	ds_write_b128 v169, v[70:73] offset:16384
	global_load_dwordx4 v[70:73], v[220:221], off
	s_waitcnt lgkmcnt(5)
	v_mfma_f32_16x16x32_f16 v[110:113], v[244:247], v[196:199], v[110:113]
	v_mfma_f32_16x16x32_f16 v[106:109], v[248:251], v[196:199], v[106:109]
	v_mfma_f32_16x16x32_f16 v[102:105], v[252:255], v[196:199], v[102:105]
	v_mfma_f32_16x16x32_f16 v[98:101], v[130:133], v[196:199], v[98:101]
	s_waitcnt vmcnt(15)
	ds_write_b128 v169, v[86:89] offset:20480
	v_add_co_u32_e32 v86, vcc, s94, v220
	s_nop 1
	v_addc_co_u32_e32 v87, vcc, 0, v221, vcc
	global_load_dwordx4 v[86:89], v[86:87], off
	s_waitcnt lgkmcnt(4)
	v_mfma_f32_16x16x32_f16 v[30:33], v[244:247], v[200:203], v[30:33]
	v_mfma_f32_16x16x32_f16 v[26:29], v[248:251], v[200:203], v[26:29]
	v_mfma_f32_16x16x32_f16 v[22:25], v[252:255], v[200:203], v[22:25]
	v_mfma_f32_16x16x32_f16 v[18:21], v[130:133], v[200:203], v[18:21]
	s_waitcnt vmcnt(15)
	ds_write_b128 v169, v[90:93] offset:24576
	v_add_co_u32_e32 v90, vcc, s72, v220
	s_nop 1
	v_addc_co_u32_e32 v91, vcc, 0, v221, vcc
	global_load_dwordx4 v[90:93], v[90:91], off
	s_waitcnt lgkmcnt(4)
	v_mfma_f32_16x16x32_f16 v[14:17], v[244:247], v[204:207], v[14:17]
	v_mfma_f32_16x16x32_f16 v[10:13], v[248:251], v[204:207], v[10:13]
	v_mfma_f32_16x16x32_f16 v[6:9], v[252:255], v[204:207], v[6:9]
	v_mfma_f32_16x16x32_f16 v[2:5], v[130:133], v[204:207], v[2:5]
	s_waitcnt vmcnt(15)
	ds_write_b128 v169, v[94:97] offset:28672
	v_add_co_u32_e32 v94, vcc, s73, v220
	s_nop 1
	v_addc_co_u32_e32 v95, vcc, 0, v221, vcc
	global_load_dwordx4 v[94:97], v[94:95], off
	s_waitcnt lgkmcnt(0)
	s_barrier
	s_cbranch_scc1 .LBB0_1186
; template <int NJ>
; __device__ __forceinline__ void gemm_tile(const f16* __restrict__ A, int lda, const f16* __restrict__ Bt, int ldb,
;                                           int K, f32x4 (&acc)[4][NJ], f16* sA, f16* sB, const int tid) {
;     ...
;   G_LOAD(ra0, rb0, 0)
;   if (K > 64) G_LOAD(ra1, rb1, 64)
;   __syncthreads();
;   G_STORE(ra0, rb0, 0)
;   if (K > 128) G_LOAD(ra0, rb0, 128)
;   __syncthreads();
; #pragma unroll 1
;   for (int k0 = 0; k0 < K; k0 += 128) {
;     {
;       const int kof = (k0 + 192 < K) ? k0 + 192 : K - 64;
;       G_STEP(0, ra1, rb1, true, true, kof)
	ds_read_b128 v[208:211], v192 offset:16384
	ds_read_b128 v[212:215], v192 offset:18432
	ds_read_b128 v[216:219], v192 offset:20480
	ds_read_b128 v[220:223], v192 offset:22528
	s_add_i32 s10, s9, 0xc0
	ds_read_b128 v[196:199], v170
	ds_read_b128 v[200:203], v170 offset:2048
	s_cmpk_lt_u32 s9, 0x340
	s_cselect_b32 s42, s10, 0x3c0
	ds_read_b128 v[204:207], v170 offset:4096
	s_lshl_b64 s[10:11], s[42:43], 1
	v_lshl_add_u64 v[160:161], v[154:155], 0, s[10:11]
	ds_read_b128 v[130:133], v170 offset:6144
	ds_read_b128 v[244:247], v243 offset:16384
	ds_read_b128 v[248:251], v243 offset:18432
	ds_read_b128 v[252:255], v243 offset:20480
	s_waitcnt lgkmcnt(6)
	v_mfma_f32_16x16x32_f16 v[126:129], v[208:211], v[196:199], v[126:129]
	v_lshl_add_u64 v[158:159], v[156:157], 0, s[10:11]
	s_add_i32 s10, s9, 0x100
	s_cmpk_lt_u32 s9, 0x300
	v_mfma_f32_16x16x32_f16 v[122:125], v[212:215], v[196:199], v[122:125]
	s_cselect_b32 s42, s10, 0x3c0
	s_lshl_b64 s[10:11], s[42:43], 1
	v_mfma_f32_16x16x32_f16 v[118:121], v[216:219], v[196:199], v[118:121]
	v_mfma_f32_16x16x32_f16 v[114:117], v[220:223], v[196:199], v[114:117]
	ds_read_b128 v[196:199], v243 offset:22528
	s_waitcnt vmcnt(15)
	ds_write_b128 v169, v[34:37] offset:32768
	global_load_dwordx4 v[34:37], v[160:161], off
	s_waitcnt lgkmcnt(7)
	v_mfma_f32_16x16x32_f16 v[110:113], v[208:211], v[200:203], v[110:113]
	v_mfma_f32_16x16x32_f16 v[106:109], v[212:215], v[200:203], v[106:109]
	v_mfma_f32_16x16x32_f16 v[102:105], v[216:219], v[200:203], v[102:105]
	v_mfma_f32_16x16x32_f16 v[98:101], v[220:223], v[200:203], v[98:101]
	ds_read_b128 v[200:203], v242
	s_waitcnt vmcnt(15)
	ds_write_b128 v169, v[42:45] offset:36864
	v_add_co_u32_e32 v42, vcc, s94, v160
	s_nop 1
	v_addc_co_u32_e32 v43, vcc, 0, v161, vcc
	global_load_dwordx4 v[42:45], v[42:43], off
	s_waitcnt lgkmcnt(8)
	v_mfma_f32_16x16x32_f16 v[30:33], v[208:211], v[204:207], v[30:33]
	v_mfma_f32_16x16x32_f16 v[26:29], v[212:215], v[204:207], v[26:29]
	v_mfma_f32_16x16x32_f16 v[22:25], v[216:219], v[204:207], v[22:25]
	v_mfma_f32_16x16x32_f16 v[18:21], v[220:223], v[204:207], v[18:21]
	ds_read_b128 v[204:207], v242 offset:2048
	s_waitcnt vmcnt(15)
	ds_write_b128 v169, v[46:49] offset:40960
	v_add_co_u32_e32 v46, vcc, s72, v160
	s_nop 1
	v_addc_co_u32_e32 v47, vcc, 0, v161, vcc
	global_load_dwordx4 v[46:49], v[46:47], off
	s_waitcnt lgkmcnt(9)
	v_mfma_f32_16x16x32_f16 v[14:17], v[208:211], v[130:133], v[14:17]
	v_mfma_f32_16x16x32_f16 v[10:13], v[212:215], v[130:133], v[10:13]
	v_mfma_f32_16x16x32_f16 v[6:9], v[216:219], v[130:133], v[6:9]
	v_mfma_f32_16x16x32_f16 v[2:5], v[220:223], v[130:133], v[2:5]
	ds_read_b128 v[130:133], v242 offset:4096
	ds_read_b128 v[208:211], v242 offset:6144
	s_waitcnt vmcnt(15)
	ds_write_b128 v169, v[50:53] offset:45056
	v_add_co_u32_e32 v50, vcc, s73, v160
	s_nop 1
	v_addc_co_u32_e32 v51, vcc, 0, v161, vcc
	global_load_dwordx4 v[50:53], v[50:51], off
	s_waitcnt lgkmcnt(6)
	v_mfma_f32_16x16x32_f16 v[126:129], v[244:247], v[200:203], v[126:129]
	v_mfma_f32_16x16x32_f16 v[122:125], v[248:251], v[200:203], v[122:125]
	v_mfma_f32_16x16x32_f16 v[118:121], v[252:255], v[200:203], v[118:121]
	v_mfma_f32_16x16x32_f16 v[114:117], v[196:199], v[200:203], v[114:117]
	s_waitcnt vmcnt(15)
	ds_write_b128 v169, v[38:41] offset:49152
	global_load_dwordx4 v[38:41], v[158:159], off
	v_lshl_add_u64 v[222:223], v[154:155], 0, s[10:11]
	s_waitcnt lgkmcnt(5)
	v_mfma_f32_16x16x32_f16 v[110:113], v[244:247], v[204:207], v[110:113]
	v_lshl_add_u64 v[220:221], v[156:157], 0, s[10:11]
	s_add_i32 s10, s9, 0x80
	s_cmpk_lt_u32 s9, 0x380
	v_mfma_f32_16x16x32_f16 v[106:109], v[248:251], v[204:207], v[106:109]
	s_mov_b32 s9, s10
	v_mfma_f32_16x16x32_f16 v[102:105], v[252:255], v[204:207], v[102:105]
	v_mfma_f32_16x16x32_f16 v[98:101], v[196:199], v[204:207], v[98:101]
	s_waitcnt vmcnt(15)
	ds_write_b128 v169, v[54:57] offset:53248
	v_add_co_u32_e32 v54, vcc, s94, v158
	s_nop 1
	v_addc_co_u32_e32 v55, vcc, 0, v159, vcc
	global_load_dwordx4 v[54:57], v[54:55], off
	s_waitcnt lgkmcnt(4)
	v_mfma_f32_16x16x32_f16 v[30:33], v[244:247], v[130:133], v[30:33]
	v_mfma_f32_16x16x32_f16 v[26:29], v[248:251], v[130:133], v[26:29]
	v_mfma_f32_16x16x32_f16 v[22:25], v[252:255], v[130:133], v[22:25]
	v_mfma_f32_16x16x32_f16 v[18:21], v[196:199], v[130:133], v[18:21]
	s_waitcnt vmcnt(15)
	ds_write_b128 v169, v[62:65] offset:57344
	v_add_co_u32_e32 v62, vcc, s72, v158
	s_nop 1
	v_addc_co_u32_e32 v63, vcc, 0, v159, vcc
	global_load_dwordx4 v[62:65], v[62:63], off
	s_waitcnt lgkmcnt(4)
	v_mfma_f32_16x16x32_f16 v[14:17], v[244:247], v[208:211], v[14:17]
	v_mfma_f32_16x16x32_f16 v[10:13], v[248:251], v[208:211], v[10:13]
	v_mfma_f32_16x16x32_f16 v[6:9], v[252:255], v[208:211], v[6:9]
	v_mfma_f32_16x16x32_f16 v[2:5], v[196:199], v[208:211], v[2:5]
	s_waitcnt vmcnt(15)
	ds_write_b128 v169, v[66:69] offset:61440
	v_add_co_u32_e32 v66, vcc, s73, v158
	s_nop 1
	v_addc_co_u32_e32 v67, vcc, 0, v159, vcc
	global_load_dwordx4 v[66:69], v[66:67], off
	s_waitcnt lgkmcnt(0)
	s_barrier
; template <int NJ>
; __device__ __forceinline__ void gemm_tile(const f16* __restrict__ A, int lda, const f16* __restrict__ Bt, int ldb,
;                                           int K, f32x4 (&acc)[4][NJ], f16* sA, f16* sB, const int tid) {
;     ...
;   G_LOAD(ra0, rb0, 0)
;   if (K > 64) G_LOAD(ra1, rb1, 64)
;   __syncthreads();
;   G_STORE(ra0, rb0, 0)
;   if (K > 128) G_LOAD(ra0, rb0, 128)
;   __syncthreads();
; #pragma unroll 1
;   for (int k0 = 0; k0 < K; k0 += 128) {
;     {
;       const int kof = (k0 + 192 < K) ? k0 + 192 : K - 64;
;       G_STEP(0, ra1, rb1, true, true, kof)
;     }
;     __syncthreads();
;     if (k0 + 64 >= K) break;
;     {
;       const int kof = (k0 + 256 < K) ? k0 + 256 : K - 64;
;       G_STEP(1, ra0, rb0, true, true, kof)
	ds_read_b128 v[204:207], v192 offset:49152
	ds_read_b128 v[208:211], v192 offset:51200
	ds_read_b128 v[212:215], v192 offset:53248
	ds_read_b128 v[216:219], v192 offset:55296
	ds_read_b128 v[130:133], v170 offset:32768
	ds_read_b128 v[158:161], v170 offset:34816
	ds_read_b128 v[196:199], v170 offset:36864
	ds_read_b128 v[200:203], v170 offset:38912
	ds_read_b128 v[244:247], v243 offset:49152
	ds_read_b128 v[248:251], v243 offset:51200
	ds_read_b128 v[252:255], v243 offset:53248
	s_waitcnt lgkmcnt(6)
	v_mfma_f32_16x16x32_f16 v[126:129], v[204:207], v[130:133], v[126:129]
	v_mfma_f32_16x16x32_f16 v[122:125], v[208:211], v[130:133], v[122:125]
	v_mfma_f32_16x16x32_f16 v[118:121], v[212:215], v[130:133], v[118:121]
	v_mfma_f32_16x16x32_f16 v[114:117], v[216:219], v[130:133], v[114:117]
	ds_read_b128 v[130:133], v243 offset:55296
	s_waitcnt vmcnt(15)
	ds_write_b128 v169, v[58:61]
	s_waitcnt lgkmcnt(7)
	v_mfma_f32_16x16x32_f16 v[110:113], v[204:207], v[158:161], v[110:113]
	v_mfma_f32_16x16x32_f16 v[106:109], v[208:211], v[158:161], v[106:109]
	v_mfma_f32_16x16x32_f16 v[102:105], v[212:215], v[158:161], v[102:105]
	v_mfma_f32_16x16x32_f16 v[98:101], v[216:219], v[158:161], v[98:101]
	ds_read_b128 v[158:161], v242 offset:32768
	s_waitcnt vmcnt(14)
	ds_write_b128 v169, v[74:77] offset:4096
	s_waitcnt lgkmcnt(8)
	v_mfma_f32_16x16x32_f16 v[30:33], v[204:207], v[196:199], v[30:33]
	v_mfma_f32_16x16x32_f16 v[26:29], v[208:211], v[196:199], v[26:29]
	v_mfma_f32_16x16x32_f16 v[22:25], v[212:215], v[196:199], v[22:25]
	v_mfma_f32_16x16x32_f16 v[18:21], v[216:219], v[196:199], v[18:21]
	ds_read_b128 v[196:199], v242 offset:34816
	s_waitcnt vmcnt(13)
	ds_write_b128 v169, v[78:81] offset:8192
	s_waitcnt lgkmcnt(9)
	v_mfma_f32_16x16x32_f16 v[14:17], v[204:207], v[200:203], v[14:17]
	v_mfma_f32_16x16x32_f16 v[10:13], v[208:211], v[200:203], v[10:13]
	v_mfma_f32_16x16x32_f16 v[6:9], v[212:215], v[200:203], v[6:9]
	v_mfma_f32_16x16x32_f16 v[2:5], v[216:219], v[200:203], v[2:5]
	ds_read_b128 v[200:203], v242 offset:36864
	ds_read_b128 v[204:207], v242 offset:38912
	s_waitcnt vmcnt(12)
	ds_write_b128 v169, v[82:85] offset:12288
	s_waitcnt lgkmcnt(6)
	v_mfma_f32_16x16x32_f16 v[126:129], v[244:247], v[158:161], v[126:129]
	v_mfma_f32_16x16x32_f16 v[122:125], v[248:251], v[158:161], v[122:125]
	v_mfma_f32_16x16x32_f16 v[118:121], v[252:255], v[158:161], v[118:121]
	v_mfma_f32_16x16x32_f16 v[114:117], v[130:133], v[158:161], v[114:117]
	s_waitcnt vmcnt(11)
	ds_write_b128 v169, v[70:73] offset:16384
	s_waitcnt lgkmcnt(5)
	v_mfma_f32_16x16x32_f16 v[110:113], v[244:247], v[196:199], v[110:113]
	v_mfma_f32_16x16x32_f16 v[106:109], v[248:251], v[196:199], v[106:109]
	v_mfma_f32_16x16x32_f16 v[102:105], v[252:255], v[196:199], v[102:105]
	v_mfma_f32_16x16x32_f16 v[98:101], v[130:133], v[196:199], v[98:101]
	s_waitcnt vmcnt(10)
	ds_write_b128 v169, v[86:89] offset:20480
	s_waitcnt lgkmcnt(4)
	v_mfma_f32_16x16x32_f16 v[30:33], v[244:247], v[200:203], v[30:33]
	v_mfma_f32_16x16x32_f16 v[26:29], v[248:251], v[200:203], v[26:29]
	v_mfma_f32_16x16x32_f16 v[22:25], v[252:255], v[200:203], v[22:25]
	v_mfma_f32_16x16x32_f16 v[18:21], v[130:133], v[200:203], v[18:21]
	s_waitcnt vmcnt(9)
	ds_write_b128 v169, v[90:93] offset:24576
	s_waitcnt lgkmcnt(4)
	v_mfma_f32_16x16x32_f16 v[14:17], v[244:247], v[204:207], v[14:17]
	v_mfma_f32_16x16x32_f16 v[10:13], v[248:251], v[204:207], v[10:13]
	v_mfma_f32_16x16x32_f16 v[6:9], v[252:255], v[204:207], v[6:9]
	v_mfma_f32_16x16x32_f16 v[2:5], v[130:133], v[204:207], v[2:5]
	s_waitcnt vmcnt(8)
	ds_write_b128 v169, v[94:97] offset:28672
	s_waitcnt lgkmcnt(0)
	s_barrier
	ds_read_b128 v[208:211], v192 offset:16384
	ds_read_b128 v[212:215], v192 offset:18432
	ds_read_b128 v[216:219], v192 offset:20480
	ds_read_b128 v[220:223], v192 offset:22528
	s_add_i32 s10, s9, 0xc0
	ds_read_b128 v[196:199], v170
	ds_read_b128 v[200:203], v170 offset:2048
	s_cmpk_lt_u32 s9, 0x340
	s_cselect_b32 s42, s10, 0x3c0
	ds_read_b128 v[204:207], v170 offset:4096
	s_lshl_b64 s[10:11], s[42:43], 1
	v_lshl_add_u64 v[160:161], v[154:155], 0, s[10:11]
	ds_read_b128 v[130:133], v170 offset:6144
	ds_read_b128 v[244:247], v243 offset:16384
	ds_read_b128 v[248:251], v243 offset:18432
	ds_read_b128 v[252:255], v243 offset:20480
	s_waitcnt lgkmcnt(6)
	v_mfma_f32_16x16x32_f16 v[126:129], v[208:211], v[196:199], v[126:129]
	v_lshl_add_u64 v[158:159], v[156:157], 0, s[10:11]
	s_add_i32 s10, s9, 0x100
	s_cmpk_lt_u32 s9, 0x300
	v_mfma_f32_16x16x32_f16 v[122:125], v[212:215], v[196:199], v[122:125]
	s_cselect_b32 s42, s10, 0x3c0
	s_lshl_b64 s[10:11], s[42:43], 1
	v_mfma_f32_16x16x32_f16 v[118:121], v[216:219], v[196:199], v[118:121]
	v_mfma_f32_16x16x32_f16 v[114:117], v[220:223], v[196:199], v[114:117]
	ds_read_b128 v[196:199], v243 offset:22528
	s_waitcnt vmcnt(7)
	ds_write_b128 v169, v[34:37] offset:32768
	s_waitcnt lgkmcnt(7)
	v_mfma_f32_16x16x32_f16 v[110:113], v[208:211], v[200:203], v[110:113]
	v_mfma_f32_16x16x32_f16 v[106:109], v[212:215], v[200:203], v[106:109]
	v_mfma_f32_16x16x32_f16 v[102:105], v[216:219], v[200:203], v[102:105]
	v_mfma_f32_16x16x32_f16 v[98:101], v[220:223], v[200:203], v[98:101]
	ds_read_b128 v[200:203], v242
	s_waitcnt vmcnt(6)
	ds_write_b128 v169, v[42:45] offset:36864
	s_waitcnt lgkmcnt(8)
	v_mfma_f32_16x16x32_f16 v[30:33], v[208:211], v[204:207], v[30:33]
	v_mfma_f32_16x16x32_f16 v[26:29], v[212:215], v[204:207], v[26:29]
	v_mfma_f32_16x16x32_f16 v[22:25], v[216:219], v[204:207], v[22:25]
	v_mfma_f32_16x16x32_f16 v[18:21], v[220:223], v[204:207], v[18:21]
	ds_read_b128 v[204:207], v242 offset:2048
	s_waitcnt vmcnt(5)
	ds_write_b128 v169, v[46:49] offset:40960
	s_waitcnt lgkmcnt(9)
; template <int NJ>
; __device__ __forceinline__ void gemm_tile(const f16* __restrict__ A, int lda, const f16* __restrict__ Bt, int ldb,
;                                           int K, f32x4 (&acc)[4][NJ], f16* sA, f16* sB, const int tid) {
;     ...
;   G_LOAD(ra0, rb0, 0)
;   if (K > 64) G_LOAD(ra1, rb1, 64)
;   __syncthreads();
;   G_STORE(ra0, rb0, 0)
;   if (K > 128) G_LOAD(ra0, rb0, 128)
;   __syncthreads();
; #pragma unroll 1
;   for (int k0 = 0; k0 < K; k0 += 128) {
;     {
;       const int kof = (k0 + 192 < K) ? k0 + 192 : K - 64;
;       G_STEP(0, ra1, rb1, true, true, kof)
;     }
;     __syncthreads();
;     if (k0 + 64 >= K) break;
;     {
;       const int kof = (k0 + 256 < K) ? k0 + 256 : K - 64;
;       G_STEP(1, ra0, rb0, true, true, kof)
;     }
;     __syncthreads();
;   }
; template <int NJ>
; __device__ __forceinline__ void gres_tile(const Params& p, const f16* A, int lda, const f16* W, int K, const float* mod,
;                                           bool first_in, f16* sA, f16* sB, int m0, int n0) {
;     ...
;   for (int i = 0; i < 4; ++i) {
;     int m = m0 + wm * 64 + i * 16 + (lane & 15);
;     const float* xi = xrow_in(p, first_in ? 0 : 1, m);
;     float* xo = xrow_out(p, m);
;     const float* gt = mod + (size_t)modrow_of(m) * 6 * DM;
; #pragma unroll
;     for (int j = 0; j < NJ; ++j) {
;       int n = n0 + wn * (NJ * 16) + j * 16 + 4 * (lane >> 4);
;       float4 xv = *(const float4*)(xi + n);
	v_mfma_f32_16x16x32_f16 v[14:17], v[208:211], v[130:133], v[14:17]
	v_mfma_f32_16x16x32_f16 v[10:13], v[212:215], v[130:133], v[10:13]
	v_mfma_f32_16x16x32_f16 v[6:9], v[216:219], v[130:133], v[6:9]
	v_mfma_f32_16x16x32_f16 v[2:5], v[220:223], v[130:133], v[2:5]
	ds_read_b128 v[130:133], v242 offset:4096
	ds_read_b128 v[208:211], v242 offset:6144
	s_waitcnt vmcnt(4)
	ds_write_b128 v169, v[50:53] offset:45056
	s_waitcnt lgkmcnt(6)
	v_mfma_f32_16x16x32_f16 v[126:129], v[244:247], v[200:203], v[126:129]
	v_mfma_f32_16x16x32_f16 v[122:125], v[248:251], v[200:203], v[122:125]
	v_mfma_f32_16x16x32_f16 v[118:121], v[252:255], v[200:203], v[118:121]
	v_mfma_f32_16x16x32_f16 v[114:117], v[196:199], v[200:203], v[114:117]
	s_waitcnt vmcnt(3)
	ds_write_b128 v169, v[38:41] offset:49152
	v_lshl_add_u64 v[222:223], v[154:155], 0, s[10:11]
	s_waitcnt lgkmcnt(5)
	v_mfma_f32_16x16x32_f16 v[110:113], v[244:247], v[204:207], v[110:113]
	v_lshl_add_u64 v[220:221], v[156:157], 0, s[10:11]
	s_add_i32 s10, s9, 0x80
	s_cmpk_lt_u32 s9, 0x380
	v_mfma_f32_16x16x32_f16 v[106:109], v[248:251], v[204:207], v[106:109]
	s_mov_b32 s9, s10
	v_mfma_f32_16x16x32_f16 v[102:105], v[252:255], v[204:207], v[102:105]
	v_mfma_f32_16x16x32_f16 v[98:101], v[196:199], v[204:207], v[98:101]
	s_waitcnt vmcnt(2)
	ds_write_b128 v169, v[54:57] offset:53248
	s_waitcnt lgkmcnt(4)
	v_mfma_f32_16x16x32_f16 v[30:33], v[244:247], v[130:133], v[30:33]
	v_mfma_f32_16x16x32_f16 v[26:29], v[248:251], v[130:133], v[26:29]
	v_mfma_f32_16x16x32_f16 v[22:25], v[252:255], v[130:133], v[22:25]
	v_mfma_f32_16x16x32_f16 v[18:21], v[196:199], v[130:133], v[18:21]
	s_waitcnt vmcnt(1)
	ds_write_b128 v169, v[62:65] offset:57344
	s_waitcnt lgkmcnt(4)
	v_mfma_f32_16x16x32_f16 v[14:17], v[244:247], v[208:211], v[14:17]
	v_mfma_f32_16x16x32_f16 v[10:13], v[248:251], v[208:211], v[10:13]
	v_mfma_f32_16x16x32_f16 v[6:9], v[252:255], v[208:211], v[6:9]
	v_mfma_f32_16x16x32_f16 v[2:5], v[196:199], v[208:211], v[2:5]
	s_waitcnt vmcnt(0)
	ds_write_b128 v169, v[66:69] offset:61440
	s_waitcnt lgkmcnt(0)
	s_barrier
	ds_read_b128 v[204:207], v192 offset:49152
	ds_read_b128 v[208:211], v192 offset:51200
	ds_read_b128 v[212:215], v192 offset:53248
	ds_read_b128 v[216:219], v192 offset:55296
	ds_read_b128 v[130:133], v170 offset:32768
	ds_read_b128 v[158:161], v170 offset:34816
	ds_read_b128 v[196:199], v170 offset:36864
	ds_read_b128 v[200:203], v170 offset:38912
	ds_read_b128 v[244:247], v243 offset:49152
	ds_read_b128 v[248:251], v243 offset:51200
	ds_read_b128 v[252:255], v243 offset:53248
	s_waitcnt lgkmcnt(6)
	v_mfma_f32_16x16x32_f16 v[126:129], v[204:207], v[130:133], v[126:129]
	v_mfma_f32_16x16x32_f16 v[122:125], v[208:211], v[130:133], v[122:125]
	v_mfma_f32_16x16x32_f16 v[118:121], v[212:215], v[130:133], v[118:121]
	v_mfma_f32_16x16x32_f16 v[114:117], v[216:219], v[130:133], v[114:117]
	ds_read_b128 v[130:133], v243 offset:55296
	s_waitcnt lgkmcnt(6)
	v_mfma_f32_16x16x32_f16 v[110:113], v[204:207], v[158:161], v[110:113]
	v_mfma_f32_16x16x32_f16 v[106:109], v[208:211], v[158:161], v[106:109]
	v_mfma_f32_16x16x32_f16 v[102:105], v[212:215], v[158:161], v[102:105]
	v_mfma_f32_16x16x32_f16 v[98:101], v[216:219], v[158:161], v[98:101]
	ds_read_b128 v[158:161], v242 offset:32768
	s_waitcnt lgkmcnt(6)
	v_mfma_f32_16x16x32_f16 v[30:33], v[204:207], v[196:199], v[30:33]
	v_mfma_f32_16x16x32_f16 v[26:29], v[208:211], v[196:199], v[26:29]
	v_mfma_f32_16x16x32_f16 v[22:25], v[212:215], v[196:199], v[22:25]
	v_mfma_f32_16x16x32_f16 v[18:21], v[216:219], v[196:199], v[18:21]
	ds_read_b128 v[196:199], v242 offset:34816
	s_waitcnt lgkmcnt(6)
	v_mfma_f32_16x16x32_f16 v[14:17], v[204:207], v[200:203], v[14:17]
	v_mfma_f32_16x16x32_f16 v[10:13], v[208:211], v[200:203], v[10:13]
	v_mfma_f32_16x16x32_f16 v[6:9], v[212:215], v[200:203], v[6:9]
	v_mfma_f32_16x16x32_f16 v[2:5], v[216:219], v[200:203], v[2:5]
	ds_read_b128 v[200:203], v242 offset:36864
	ds_read_b128 v[204:207], v242 offset:38912
	s_waitcnt lgkmcnt(3)
	v_mfma_f32_16x16x32_f16 v[126:129], v[244:247], v[158:161], v[126:129]
	v_mfma_f32_16x16x32_f16 v[122:125], v[248:251], v[158:161], v[122:125]
	v_mfma_f32_16x16x32_f16 v[118:121], v[252:255], v[158:161], v[118:121]
	v_mfma_f32_16x16x32_f16 v[114:117], v[130:133], v[158:161], v[114:117]
	s_waitcnt lgkmcnt(2)
	v_mfma_f32_16x16x32_f16 v[110:113], v[244:247], v[196:199], v[110:113]
	v_mfma_f32_16x16x32_f16 v[106:109], v[248:251], v[196:199], v[106:109]
	v_mfma_f32_16x16x32_f16 v[102:105], v[252:255], v[196:199], v[102:105]
	v_mfma_f32_16x16x32_f16 v[98:101], v[130:133], v[196:199], v[98:101]
	s_waitcnt lgkmcnt(1)
	v_mfma_f32_16x16x32_f16 v[30:33], v[244:247], v[200:203], v[30:33]
	v_mfma_f32_16x16x32_f16 v[26:29], v[248:251], v[200:203], v[26:29]
	v_mfma_f32_16x16x32_f16 v[22:25], v[252:255], v[200:203], v[22:25]
	v_mfma_f32_16x16x32_f16 v[18:21], v[130:133], v[200:203], v[18:21]
	s_waitcnt lgkmcnt(0)
	v_mfma_f32_16x16x32_f16 v[14:17], v[244:247], v[204:207], v[14:17]
	v_mfma_f32_16x16x32_f16 v[10:13], v[248:251], v[204:207], v[10:13]
	v_mfma_f32_16x16x32_f16 v[6:9], v[252:255], v[204:207], v[6:9]
	v_mfma_f32_16x16x32_f16 v[2:5], v[130:133], v[204:207], v[2:5]
	s_waitcnt lgkmcnt(0)
	s_barrier
	s_waitcnt vmcnt(15)
	v_or_b32_e32 v34, s8, v162
	v_add_u32_e32 v34, v34, v147
	v_cmp_gt_i32_e64 s[8:9], s80, v34
	v_cmp_lt_i32_e64 s[10:11], s82, v34
	s_mov_b64 s[14:15], -1
	s_and_b64 vcc, exec, s[30:31]
	s_cbranch_vccz .LBB0_1193
	v_mov_b64_e32 v[36:37], v[0:1]
	s_and_saveexec_b64 s[14:15], s[10:11]
	s_xor_b64 s[14:15], exec, s[14:15]
	s_cbranch_execz .LBB0_1190
	v_add_u32_e32 v164, 0xffff8000, v34
	v_mov_b64_e32 v[36:37], v[152:153]
	s_waitcnt vmcnt(11)
	v_mov_b64_e32 v[38:39], v[164:165]

; template <int NJ>
; __device__ __forceinline__ void gemm_tile(const f16* __restrict__ A, int lda, const f16* __restrict__ Bt, int ldb,
;                                           int K, f32x4 (&acc)[4][NJ], f16* sA, f16* sB, const int tid) {
;     ...
;   G_LOAD(ra0, rb0, 0)
;   if (K > 64) G_LOAD(ra1, rb1, 64)
;   __syncthreads();
;   G_STORE(ra0, rb0, 0)
;   if (K > 128) G_LOAD(ra0, rb0, 128)
;   __syncthreads();
; #pragma unroll 1
;   for (int k0 = 0; k0 < K; k0 += 128) {
;     {
;       const int kof = (k0 + 192 < K) ? k0 + 192 : K - 64;
;       G_STEP(0, ra1, rb1, true, true, kof)
.LBB0_1398:
	ds_read_b128 v[166:169], v148 offset:16384
	ds_read_b128 v[192:195], v148 offset:18432
	ds_read_b128 v[196:199], v148 offset:20480
	ds_read_b128 v[200:203], v148 offset:22528
	s_add_i32 s13, s11, 0xc0
	ds_read_b128 v[152:155], v150
	ds_read_b128 v[156:159], v150 offset:2048
	s_cmpk_lt_u32 s11, 0x340
	s_cselect_b32 s42, s13, 0x3c0
	ds_read_b128 v[160:163], v150 offset:4096
	s_lshl_b64 s[14:15], s[42:43], 1
	v_lshl_add_u64 v[144:145], v[138:139], 0, s[14:15]
	ds_read_b128 v[128:131], v150 offset:6144
	ds_read_b128 v[244:247], v243 offset:16384
	ds_read_b128 v[248:251], v243 offset:18432
	ds_read_b128 v[252:255], v243 offset:20480
	s_waitcnt lgkmcnt(6)
	v_mfma_f32_16x16x32_f16 v[124:127], v[166:169], v[152:155], v[124:127]
	v_lshl_add_u64 v[142:143], v[140:141], 0, s[14:15]
	s_add_i32 s13, s11, 0x100
	s_cmpk_lt_u32 s11, 0x300
	v_mfma_f32_16x16x32_f16 v[116:119], v[192:195], v[152:155], v[116:119]
	s_cselect_b32 s42, s13, 0x3c0
	s_lshl_b64 s[14:15], s[42:43], 1
	s_add_i32 s13, s11, 0x80
	v_mfma_f32_16x16x32_f16 v[120:123], v[196:199], v[152:155], v[120:123]
	s_cmpk_lt_u32 s11, 0x280
	s_mov_b32 s11, s13
	v_mfma_f32_16x16x32_f16 v[112:115], v[200:203], v[152:155], v[112:115]
	ds_read_b128 v[152:155], v243 offset:22528
	s_waitcnt vmcnt(15)
	ds_write_b128 v147, v[40:43] offset:32768
	global_load_dwordx4 v[40:43], v[144:145], off
	s_waitcnt lgkmcnt(7)
	v_mfma_f32_16x16x32_f16 v[108:111], v[166:169], v[156:159], v[108:111]
	v_mfma_f32_16x16x32_f16 v[36:39], v[192:195], v[156:159], v[36:39]
	v_mfma_f32_16x16x32_f16 v[104:107], v[196:199], v[156:159], v[104:107]
	v_mfma_f32_16x16x32_f16 v[32:35], v[200:203], v[156:159], v[32:35]
	ds_read_b128 v[156:159], v242
	s_waitcnt vmcnt(14)
	ds_write_b128 v147, v[48:51] offset:36864
	v_add_co_u32_e32 v48, vcc, s94, v144
	s_nop 1
	v_addc_co_u32_e32 v49, vcc, 0, v145, vcc
	global_load_dwordx4 v[48:51], v[48:49], off
	s_waitcnt lgkmcnt(8)
	v_mfma_f32_16x16x32_f16 v[28:31], v[166:169], v[160:163], v[28:31]
	v_mfma_f32_16x16x32_f16 v[20:23], v[192:195], v[160:163], v[20:23]
	v_mfma_f32_16x16x32_f16 v[24:27], v[196:199], v[160:163], v[24:27]
	v_mfma_f32_16x16x32_f16 v[16:19], v[200:203], v[160:163], v[16:19]
	ds_read_b128 v[160:163], v242 offset:2048
	s_waitcnt vmcnt(14)
	ds_write_b128 v147, v[52:55] offset:40960
	v_add_co_u32_e32 v52, vcc, s72, v144
	s_nop 1
	v_addc_co_u32_e32 v53, vcc, 0, v145, vcc
	global_load_dwordx4 v[52:55], v[52:53], off
	s_waitcnt lgkmcnt(9)
	v_mfma_f32_16x16x32_f16 v[12:15], v[166:169], v[128:131], v[12:15]
	v_mfma_f32_16x16x32_f16 v[4:7], v[192:195], v[128:131], v[4:7]
	v_mfma_f32_16x16x32_f16 v[8:11], v[196:199], v[128:131], v[8:11]
	v_mfma_f32_16x16x32_f16 v[0:3], v[200:203], v[128:131], v[0:3]
	ds_read_b128 v[128:131], v242 offset:4096
	ds_read_b128 v[166:169], v242 offset:6144
	s_waitcnt vmcnt(14)
	ds_write_b128 v147, v[56:59] offset:45056
	v_add_co_u32_e32 v56, vcc, s73, v144
	s_nop 1
	v_addc_co_u32_e32 v57, vcc, 0, v145, vcc
	global_load_dwordx4 v[56:59], v[56:57], off
	s_waitcnt lgkmcnt(6)
	v_mfma_f32_16x16x32_f16 v[124:127], v[244:247], v[156:159], v[124:127]
	v_mfma_f32_16x16x32_f16 v[116:119], v[248:251], v[156:159], v[116:119]
	v_mfma_f32_16x16x32_f16 v[120:123], v[252:255], v[156:159], v[120:123]
	v_mfma_f32_16x16x32_f16 v[112:115], v[152:155], v[156:159], v[112:115]
	ds_write_b128 v147, v[44:47] offset:49152
	global_load_dwordx4 v[44:47], v[142:143], off
	v_lshl_add_u64 v[202:203], v[138:139], 0, s[14:15]
	s_waitcnt lgkmcnt(5)
	v_mfma_f32_16x16x32_f16 v[108:111], v[244:247], v[160:163], v[108:111]
	v_lshl_add_u64 v[200:201], v[140:141], 0, s[14:15]
	v_mfma_f32_16x16x32_f16 v[36:39], v[248:251], v[160:163], v[36:39]
	v_mfma_f32_16x16x32_f16 v[104:107], v[252:255], v[160:163], v[104:107]
	v_mfma_f32_16x16x32_f16 v[32:35], v[152:155], v[160:163], v[32:35]
	s_waitcnt vmcnt(15)
	ds_write_b128 v147, v[60:63] offset:53248
	v_add_co_u32_e32 v60, vcc, s94, v142
	s_nop 1
	v_addc_co_u32_e32 v61, vcc, 0, v143, vcc
	global_load_dwordx4 v[60:63], v[60:61], off
	s_waitcnt lgkmcnt(4)
	v_mfma_f32_16x16x32_f16 v[28:31], v[244:247], v[128:131], v[28:31]
	v_mfma_f32_16x16x32_f16 v[20:23], v[248:251], v[128:131], v[20:23]
	v_mfma_f32_16x16x32_f16 v[24:27], v[252:255], v[128:131], v[24:27]
	v_mfma_f32_16x16x32_f16 v[16:19], v[152:155], v[128:131], v[16:19]
	s_waitcnt vmcnt(15)
	ds_write_b128 v147, v[68:71] offset:57344
	v_add_co_u32_e32 v68, vcc, s72, v142
	s_nop 1
	v_addc_co_u32_e32 v69, vcc, 0, v143, vcc
	global_load_dwordx4 v[68:71], v[68:69], off
	s_waitcnt lgkmcnt(4)
	v_mfma_f32_16x16x32_f16 v[12:15], v[244:247], v[166:169], v[12:15]
	v_mfma_f32_16x16x32_f16 v[4:7], v[248:251], v[166:169], v[4:7]
	v_mfma_f32_16x16x32_f16 v[8:11], v[252:255], v[166:169], v[8:11]
	v_mfma_f32_16x16x32_f16 v[0:3], v[152:155], v[166:169], v[0:3]
	s_waitcnt vmcnt(15)
	ds_write_b128 v147, v[72:75] offset:61440
	v_add_co_u32_e32 v72, vcc, s73, v142
	s_nop 1
	v_addc_co_u32_e32 v73, vcc, 0, v143, vcc
	global_load_dwordx4 v[72:75], v[72:73], off
	s_waitcnt lgkmcnt(0)
	s_barrier
; template <int NJ>
; __device__ __forceinline__ void gemm_tile(const f16* __restrict__ A, int lda, const f16* __restrict__ Bt, int ldb,
;                                           int K, f32x4 (&acc)[4][NJ], f16* sA, f16* sB, const int tid) {
;     ...
;     {
;       const int kof = (k0 + 256 < K) ? k0 + 256 : K - 64;
;       G_STEP(1, ra0, rb0, true, true, kof)
;     }
;     __syncthreads();
;   }
	ds_read_b128 v[160:163], v148 offset:49152
	ds_read_b128 v[166:169], v148 offset:51200
	ds_read_b128 v[192:195], v148 offset:53248
	ds_read_b128 v[196:199], v148 offset:55296
	ds_read_b128 v[128:131], v150 offset:32768
	ds_read_b128 v[142:145], v150 offset:34816
	ds_read_b128 v[152:155], v150 offset:36864
	ds_read_b128 v[156:159], v150 offset:38912
	ds_read_b128 v[244:247], v243 offset:49152
	ds_read_b128 v[248:251], v243 offset:51200
	ds_read_b128 v[252:255], v243 offset:53248
	s_waitcnt lgkmcnt(6)
	v_mfma_f32_16x16x32_f16 v[124:127], v[160:163], v[128:131], v[124:127]
	v_mfma_f32_16x16x32_f16 v[116:119], v[166:169], v[128:131], v[116:119]
	v_mfma_f32_16x16x32_f16 v[120:123], v[192:195], v[128:131], v[120:123]
	v_mfma_f32_16x16x32_f16 v[112:115], v[196:199], v[128:131], v[112:115]
	ds_read_b128 v[128:131], v243 offset:55296
	s_waitcnt vmcnt(13)
	ds_write_b128 v147, v[64:67]
	global_load_dwordx4 v[64:67], v[202:203], off
	s_waitcnt lgkmcnt(7)
	v_mfma_f32_16x16x32_f16 v[108:111], v[160:163], v[142:145], v[108:111]
	v_mfma_f32_16x16x32_f16 v[36:39], v[166:169], v[142:145], v[36:39]
	v_mfma_f32_16x16x32_f16 v[104:107], v[192:195], v[142:145], v[104:107]
	v_mfma_f32_16x16x32_f16 v[32:35], v[196:199], v[142:145], v[32:35]
	ds_read_b128 v[142:145], v242 offset:32768
	ds_write_b128 v147, v[80:83] offset:4096
	v_add_co_u32_e32 v80, vcc, s94, v202
	s_nop 1
	v_addc_co_u32_e32 v81, vcc, 0, v203, vcc
	global_load_dwordx4 v[80:83], v[80:81], off
	s_waitcnt lgkmcnt(8)
	v_mfma_f32_16x16x32_f16 v[28:31], v[160:163], v[152:155], v[28:31]
	v_mfma_f32_16x16x32_f16 v[20:23], v[166:169], v[152:155], v[20:23]
	v_mfma_f32_16x16x32_f16 v[24:27], v[192:195], v[152:155], v[24:27]
	v_mfma_f32_16x16x32_f16 v[16:19], v[196:199], v[152:155], v[16:19]
	ds_read_b128 v[152:155], v242 offset:34816
	ds_write_b128 v147, v[84:87] offset:8192
	v_add_co_u32_e32 v84, vcc, s72, v202
	s_nop 1
	v_addc_co_u32_e32 v85, vcc, 0, v203, vcc
	global_load_dwordx4 v[84:87], v[84:85], off
	s_waitcnt lgkmcnt(9)
	v_mfma_f32_16x16x32_f16 v[12:15], v[160:163], v[156:159], v[12:15]
	v_mfma_f32_16x16x32_f16 v[4:7], v[166:169], v[156:159], v[4:7]
	v_mfma_f32_16x16x32_f16 v[8:11], v[192:195], v[156:159], v[8:11]
	v_mfma_f32_16x16x32_f16 v[0:3], v[196:199], v[156:159], v[0:3]
	ds_read_b128 v[156:159], v242 offset:36864
	ds_read_b128 v[160:163], v242 offset:38912
	s_waitcnt vmcnt(14)
	ds_write_b128 v147, v[88:91] offset:12288
	v_add_co_u32_e32 v88, vcc, s73, v202
	s_nop 1
	v_addc_co_u32_e32 v89, vcc, 0, v203, vcc
	global_load_dwordx4 v[88:91], v[88:89], off
	s_waitcnt lgkmcnt(6)
	v_mfma_f32_16x16x32_f16 v[124:127], v[244:247], v[142:145], v[124:127]
	v_mfma_f32_16x16x32_f16 v[116:119], v[248:251], v[142:145], v[116:119]
	v_mfma_f32_16x16x32_f16 v[120:123], v[252:255], v[142:145], v[120:123]
	v_mfma_f32_16x16x32_f16 v[112:115], v[128:131], v[142:145], v[112:115]
	ds_write_b128 v147, v[76:79] offset:16384
	global_load_dwordx4 v[76:79], v[200:201], off
	s_waitcnt lgkmcnt(5)
	v_mfma_f32_16x16x32_f16 v[108:111], v[244:247], v[152:155], v[108:111]
	v_mfma_f32_16x16x32_f16 v[36:39], v[248:251], v[152:155], v[36:39]
	v_mfma_f32_16x16x32_f16 v[104:107], v[252:255], v[152:155], v[104:107]
	v_mfma_f32_16x16x32_f16 v[32:35], v[128:131], v[152:155], v[32:35]
	s_waitcnt vmcnt(15)
	ds_write_b128 v147, v[92:95] offset:20480
	v_add_co_u32_e32 v92, vcc, s94, v200
	s_nop 1
	v_addc_co_u32_e32 v93, vcc, 0, v201, vcc
	global_load_dwordx4 v[92:95], v[92:93], off
	s_waitcnt lgkmcnt(4)
	v_mfma_f32_16x16x32_f16 v[28:31], v[244:247], v[156:159], v[28:31]
	v_mfma_f32_16x16x32_f16 v[20:23], v[248:251], v[156:159], v[20:23]
	v_mfma_f32_16x16x32_f16 v[24:27], v[252:255], v[156:159], v[24:27]
	v_mfma_f32_16x16x32_f16 v[16:19], v[128:131], v[156:159], v[16:19]
	s_waitcnt vmcnt(15)
	ds_write_b128 v147, v[96:99] offset:24576
	v_add_co_u32_e32 v96, vcc, s72, v200
	s_nop 1
	v_addc_co_u32_e32 v97, vcc, 0, v201, vcc
	global_load_dwordx4 v[96:99], v[96:97], off
	s_waitcnt lgkmcnt(4)
	v_mfma_f32_16x16x32_f16 v[12:15], v[244:247], v[160:163], v[12:15]
	v_mfma_f32_16x16x32_f16 v[4:7], v[248:251], v[160:163], v[4:7]
	v_mfma_f32_16x16x32_f16 v[8:11], v[252:255], v[160:163], v[8:11]
	v_mfma_f32_16x16x32_f16 v[0:3], v[128:131], v[160:163], v[0:3]
	s_waitcnt vmcnt(15)
	ds_write_b128 v147, v[100:103] offset:28672
	v_add_co_u32_e32 v100, vcc, s73, v200
	s_nop 1
	v_addc_co_u32_e32 v101, vcc, 0, v201, vcc
	global_load_dwordx4 v[100:103], v[100:101], off
	s_waitcnt lgkmcnt(0)
	s_barrier
	s_cbranch_scc1 .LBB0_1398
; template <int NJ>
; __device__ __forceinline__ void gemm_tile(const f16* __restrict__ A, int lda, const f16* __restrict__ Bt, int ldb,
;                                           int K, f32x4 (&acc)[4][NJ], f16* sA, f16* sB, const int tid) {
;     ...
;   G_LOAD(ra0, rb0, 0)
;   if (K > 64) G_LOAD(ra1, rb1, 64)
;   __syncthreads();
;   G_STORE(ra0, rb0, 0)
;   if (K > 128) G_LOAD(ra0, rb0, 128)
;   __syncthreads();
; #pragma unroll 1
;   for (int k0 = 0; k0 < K; k0 += 128) {
;     {
;       const int kof = (k0 + 192 < K) ? k0 + 192 : K - 64;
;       G_STEP(0, ra1, rb1, true, true, kof)
	ds_read_b128 v[166:169], v148 offset:16384
	ds_read_b128 v[192:195], v148 offset:18432
	ds_read_b128 v[196:199], v148 offset:20480
	ds_read_b128 v[200:203], v148 offset:22528
	s_add_i32 s13, s11, 0xc0
	ds_read_b128 v[152:155], v150
	ds_read_b128 v[156:159], v150 offset:2048
	s_cmpk_lt_u32 s11, 0x340
	s_cselect_b32 s42, s13, 0x3c0
	ds_read_b128 v[160:163], v150 offset:4096
	s_lshl_b64 s[14:15], s[42:43], 1
	v_lshl_add_u64 v[144:145], v[138:139], 0, s[14:15]
	ds_read_b128 v[128:131], v150 offset:6144
	ds_read_b128 v[244:247], v243 offset:16384
	ds_read_b128 v[248:251], v243 offset:18432
	ds_read_b128 v[252:255], v243 offset:20480
	s_waitcnt lgkmcnt(6)
	v_mfma_f32_16x16x32_f16 v[124:127], v[166:169], v[152:155], v[124:127]
	v_lshl_add_u64 v[142:143], v[140:141], 0, s[14:15]
	s_add_i32 s13, s11, 0x100
	s_cmpk_lt_u32 s11, 0x300
	v_mfma_f32_16x16x32_f16 v[116:119], v[192:195], v[152:155], v[116:119]
	s_cselect_b32 s42, s13, 0x3c0
	s_lshl_b64 s[14:15], s[42:43], 1
	s_add_i32 s13, s11, 0x80
	v_mfma_f32_16x16x32_f16 v[120:123], v[196:199], v[152:155], v[120:123]
	s_cmpk_lt_u32 s11, 0x380
	s_mov_b32 s11, s13
	v_mfma_f32_16x16x32_f16 v[112:115], v[200:203], v[152:155], v[112:115]
	ds_read_b128 v[152:155], v243 offset:22528
	s_waitcnt vmcnt(15)
	ds_write_b128 v147, v[40:43] offset:32768
	global_load_dwordx4 v[40:43], v[144:145], off
	s_waitcnt lgkmcnt(7)
	v_mfma_f32_16x16x32_f16 v[108:111], v[166:169], v[156:159], v[108:111]
	v_mfma_f32_16x16x32_f16 v[36:39], v[192:195], v[156:159], v[36:39]
	v_mfma_f32_16x16x32_f16 v[104:107], v[196:199], v[156:159], v[104:107]
	v_mfma_f32_16x16x32_f16 v[32:35], v[200:203], v[156:159], v[32:35]
	ds_read_b128 v[156:159], v242
	s_waitcnt vmcnt(15)
	ds_write_b128 v147, v[48:51] offset:36864
	v_add_co_u32_e32 v48, vcc, s94, v144
	s_nop 1
	v_addc_co_u32_e32 v49, vcc, 0, v145, vcc
	global_load_dwordx4 v[48:51], v[48:49], off
	s_waitcnt lgkmcnt(8)
	v_mfma_f32_16x16x32_f16 v[28:31], v[166:169], v[160:163], v[28:31]
	v_mfma_f32_16x16x32_f16 v[20:23], v[192:195], v[160:163], v[20:23]
	v_mfma_f32_16x16x32_f16 v[24:27], v[196:199], v[160:163], v[24:27]
	v_mfma_f32_16x16x32_f16 v[16:19], v[200:203], v[160:163], v[16:19]
	ds_read_b128 v[160:163], v242 offset:2048
	s_waitcnt vmcnt(15)
	ds_write_b128 v147, v[52:55] offset:40960
	v_add_co_u32_e32 v52, vcc, s72, v144
	s_nop 1
	v_addc_co_u32_e32 v53, vcc, 0, v145, vcc
	global_load_dwordx4 v[52:55], v[52:53], off
	s_waitcnt lgkmcnt(9)
	v_mfma_f32_16x16x32_f16 v[12:15], v[166:169], v[128:131], v[12:15]
	v_mfma_f32_16x16x32_f16 v[4:7], v[192:195], v[128:131], v[4:7]
	v_mfma_f32_16x16x32_f16 v[8:11], v[196:199], v[128:131], v[8:11]
	v_mfma_f32_16x16x32_f16 v[0:3], v[200:203], v[128:131], v[0:3]
	ds_read_b128 v[128:131], v242 offset:4096
	ds_read_b128 v[166:169], v242 offset:6144
	s_waitcnt vmcnt(15)
	ds_write_b128 v147, v[56:59] offset:45056
	v_add_co_u32_e32 v56, vcc, s73, v144
	s_nop 1
	v_addc_co_u32_e32 v57, vcc, 0, v145, vcc
	global_load_dwordx4 v[56:59], v[56:57], off
	s_waitcnt lgkmcnt(6)
	v_mfma_f32_16x16x32_f16 v[124:127], v[244:247], v[156:159], v[124:127]
	v_mfma_f32_16x16x32_f16 v[116:119], v[248:251], v[156:159], v[116:119]
	v_mfma_f32_16x16x32_f16 v[120:123], v[252:255], v[156:159], v[120:123]
	v_mfma_f32_16x16x32_f16 v[112:115], v[152:155], v[156:159], v[112:115]
	s_waitcnt vmcnt(15)
	ds_write_b128 v147, v[44:47] offset:49152
	global_load_dwordx4 v[44:47], v[142:143], off
	v_lshl_add_u64 v[202:203], v[138:139], 0, s[14:15]
	s_waitcnt lgkmcnt(5)
	v_mfma_f32_16x16x32_f16 v[108:111], v[244:247], v[160:163], v[108:111]
	v_lshl_add_u64 v[200:201], v[140:141], 0, s[14:15]
	v_mfma_f32_16x16x32_f16 v[36:39], v[248:251], v[160:163], v[36:39]
	v_mfma_f32_16x16x32_f16 v[104:107], v[252:255], v[160:163], v[104:107]
	v_mfma_f32_16x16x32_f16 v[32:35], v[152:155], v[160:163], v[32:35]
	s_waitcnt vmcnt(15)
	ds_write_b128 v147, v[60:63] offset:53248
	v_add_co_u32_e32 v60, vcc, s94, v142
	s_nop 1
	v_addc_co_u32_e32 v61, vcc, 0, v143, vcc
	global_load_dwordx4 v[60:63], v[60:61], off
	s_waitcnt lgkmcnt(4)
	v_mfma_f32_16x16x32_f16 v[28:31], v[244:247], v[128:131], v[28:31]
	v_mfma_f32_16x16x32_f16 v[20:23], v[248:251], v[128:131], v[20:23]
	v_mfma_f32_16x16x32_f16 v[24:27], v[252:255], v[128:131], v[24:27]
	v_mfma_f32_16x16x32_f16 v[16:19], v[152:155], v[128:131], v[16:19]
	s_waitcnt vmcnt(15)
	ds_write_b128 v147, v[68:71] offset:57344
	v_add_co_u32_e32 v68, vcc, s72, v142
	s_nop 1
	v_addc_co_u32_e32 v69, vcc, 0, v143, vcc
	global_load_dwordx4 v[68:71], v[68:69], off
	s_waitcnt lgkmcnt(4)
	v_mfma_f32_16x16x32_f16 v[12:15], v[244:247], v[166:169], v[12:15]
	v_mfma_f32_16x16x32_f16 v[4:7], v[248:251], v[166:169], v[4:7]
	v_mfma_f32_16x16x32_f16 v[8:11], v[252:255], v[166:169], v[8:11]
	v_mfma_f32_16x16x32_f16 v[0:3], v[152:155], v[166:169], v[0:3]
	s_waitcnt vmcnt(15)
	ds_write_b128 v147, v[72:75] offset:61440
	v_add_co_u32_e32 v72, vcc, s73, v142
	s_nop 1
	v_addc_co_u32_e32 v73, vcc, 0, v143, vcc
	global_load_dwordx4 v[72:75], v[72:73], off
	s_waitcnt lgkmcnt(0)
	s_barrier
; template <int NJ>
; __device__ __forceinline__ void gemm_tile(const f16* __restrict__ A, int lda, const f16* __restrict__ Bt, int ldb,
;                                           int K, f32x4 (&acc)[4][NJ], f16* sA, f16* sB, const int tid) {
;     ...
;   G_LOAD(ra0, rb0, 0)
;   if (K > 64) G_LOAD(ra1, rb1, 64)
;   __syncthreads();
;   G_STORE(ra0, rb0, 0)
;   if (K > 128) G_LOAD(ra0, rb0, 128)
;   __syncthreads();
; #pragma unroll 1
;   for (int k0 = 0; k0 < K; k0 += 128) {
;     {
;       const int kof = (k0 + 192 < K) ? k0 + 192 : K - 64;
;       G_STEP(0, ra1, rb1, true, true, kof)
;     }
;     __syncthreads();
;     if (k0 + 64 >= K) break;
;     {
;       const int kof = (k0 + 256 < K) ? k0 + 256 : K - 64;
;       G_STEP(1, ra0, rb0, true, true, kof)
	ds_read_b128 v[160:163], v148 offset:49152
	ds_read_b128 v[166:169], v148 offset:51200
	ds_read_b128 v[192:195], v148 offset:53248
	ds_read_b128 v[196:199], v148 offset:55296
	ds_read_b128 v[128:131], v150 offset:32768
	ds_read_b128 v[142:145], v150 offset:34816
	ds_read_b128 v[152:155], v150 offset:36864
	ds_read_b128 v[156:159], v150 offset:38912
	ds_read_b128 v[244:247], v243 offset:49152
	ds_read_b128 v[248:251], v243 offset:51200
	ds_read_b128 v[252:255], v243 offset:53248
	s_waitcnt lgkmcnt(6)
	v_mfma_f32_16x16x32_f16 v[124:127], v[160:163], v[128:131], v[124:127]
	v_mfma_f32_16x16x32_f16 v[116:119], v[166:169], v[128:131], v[116:119]
	v_mfma_f32_16x16x32_f16 v[120:123], v[192:195], v[128:131], v[120:123]
	v_mfma_f32_16x16x32_f16 v[112:115], v[196:199], v[128:131], v[112:115]
	ds_read_b128 v[128:131], v243 offset:55296
	s_waitcnt vmcnt(15)
	ds_write_b128 v147, v[64:67]
	s_waitcnt lgkmcnt(7)
	v_mfma_f32_16x16x32_f16 v[108:111], v[160:163], v[142:145], v[108:111]
	v_mfma_f32_16x16x32_f16 v[36:39], v[166:169], v[142:145], v[36:39]
	v_mfma_f32_16x16x32_f16 v[104:107], v[192:195], v[142:145], v[104:107]
	v_mfma_f32_16x16x32_f16 v[32:35], v[196:199], v[142:145], v[32:35]
	ds_read_b128 v[142:145], v242 offset:32768
	s_waitcnt vmcnt(14)
	ds_write_b128 v147, v[80:83] offset:4096
	s_waitcnt lgkmcnt(8)
	v_mfma_f32_16x16x32_f16 v[28:31], v[160:163], v[152:155], v[28:31]
	v_mfma_f32_16x16x32_f16 v[20:23], v[166:169], v[152:155], v[20:23]
	v_mfma_f32_16x16x32_f16 v[24:27], v[192:195], v[152:155], v[24:27]
	v_mfma_f32_16x16x32_f16 v[16:19], v[196:199], v[152:155], v[16:19]
	ds_read_b128 v[152:155], v242 offset:34816
	s_waitcnt vmcnt(13)
	ds_write_b128 v147, v[84:87] offset:8192
	s_waitcnt lgkmcnt(9)
	v_mfma_f32_16x16x32_f16 v[12:15], v[160:163], v[156:159], v[12:15]
	v_mfma_f32_16x16x32_f16 v[4:7], v[166:169], v[156:159], v[4:7]
	v_mfma_f32_16x16x32_f16 v[8:11], v[192:195], v[156:159], v[8:11]
	v_mfma_f32_16x16x32_f16 v[0:3], v[196:199], v[156:159], v[0:3]
	ds_read_b128 v[156:159], v242 offset:36864
	ds_read_b128 v[160:163], v242 offset:38912
	s_waitcnt vmcnt(12)
	ds_write_b128 v147, v[88:91] offset:12288
	s_waitcnt lgkmcnt(6)
	v_mfma_f32_16x16x32_f16 v[124:127], v[244:247], v[142:145], v[124:127]
	v_mfma_f32_16x16x32_f16 v[116:119], v[248:251], v[142:145], v[116:119]
	v_mfma_f32_16x16x32_f16 v[120:123], v[252:255], v[142:145], v[120:123]
	v_mfma_f32_16x16x32_f16 v[112:115], v[128:131], v[142:145], v[112:115]
	s_waitcnt vmcnt(11)
	ds_write_b128 v147, v[76:79] offset:16384
	s_waitcnt lgkmcnt(5)
	v_mfma_f32_16x16x32_f16 v[108:111], v[244:247], v[152:155], v[108:111]
	v_mfma_f32_16x16x32_f16 v[36:39], v[248:251], v[152:155], v[36:39]
	v_mfma_f32_16x16x32_f16 v[104:107], v[252:255], v[152:155], v[104:107]
	v_mfma_f32_16x16x32_f16 v[32:35], v[128:131], v[152:155], v[32:35]
	s_waitcnt vmcnt(10)
	ds_write_b128 v147, v[92:95] offset:20480
	s_waitcnt lgkmcnt(4)
	v_mfma_f32_16x16x32_f16 v[28:31], v[244:247], v[156:159], v[28:31]
	v_mfma_f32_16x16x32_f16 v[20:23], v[248:251], v[156:159], v[20:23]
	v_mfma_f32_16x16x32_f16 v[24:27], v[252:255], v[156:159], v[24:27]
	v_mfma_f32_16x16x32_f16 v[16:19], v[128:131], v[156:159], v[16:19]
	s_waitcnt vmcnt(9)
	ds_write_b128 v147, v[96:99] offset:24576
	s_waitcnt lgkmcnt(4)
	v_mfma_f32_16x16x32_f16 v[12:15], v[244:247], v[160:163], v[12:15]
	v_mfma_f32_16x16x32_f16 v[4:7], v[248:251], v[160:163], v[4:7]
	v_mfma_f32_16x16x32_f16 v[8:11], v[252:255], v[160:163], v[8:11]
	v_mfma_f32_16x16x32_f16 v[0:3], v[128:131], v[160:163], v[0:3]
	s_waitcnt vmcnt(8)
	ds_write_b128 v147, v[100:103] offset:28672
	s_waitcnt lgkmcnt(0)
	s_barrier
	ds_read_b128 v[166:169], v148 offset:16384
	ds_read_b128 v[192:195], v148 offset:18432
	ds_read_b128 v[196:199], v148 offset:20480
	ds_read_b128 v[200:203], v148 offset:22528
	s_add_i32 s13, s11, 0xc0
	ds_read_b128 v[152:155], v150
	ds_read_b128 v[156:159], v150 offset:2048
	s_cmpk_lt_u32 s11, 0x340
	s_cselect_b32 s42, s13, 0x3c0
	ds_read_b128 v[160:163], v150 offset:4096
	s_lshl_b64 s[14:15], s[42:43], 1
	v_lshl_add_u64 v[144:145], v[138:139], 0, s[14:15]
	ds_read_b128 v[128:131], v150 offset:6144
	ds_read_b128 v[244:247], v243 offset:16384
	ds_read_b128 v[248:251], v243 offset:18432
	ds_read_b128 v[252:255], v243 offset:20480
	s_waitcnt lgkmcnt(6)
	v_mfma_f32_16x16x32_f16 v[124:127], v[166:169], v[152:155], v[124:127]
	v_lshl_add_u64 v[142:143], v[140:141], 0, s[14:15]
	s_add_i32 s13, s11, 0x100
	s_cmpk_lt_u32 s11, 0x300
	v_mfma_f32_16x16x32_f16 v[116:119], v[192:195], v[152:155], v[116:119]
	s_cselect_b32 s42, s13, 0x3c0
	s_lshl_b64 s[14:15], s[42:43], 1
	s_add_i32 s13, s11, 0x80
	v_mfma_f32_16x16x32_f16 v[120:123], v[196:199], v[152:155], v[120:123]
	s_cmpk_lt_u32 s11, 0x380
	s_mov_b32 s11, s13
	v_mfma_f32_16x16x32_f16 v[112:115], v[200:203], v[152:155], v[112:115]
	ds_read_b128 v[152:155], v243 offset:22528
	s_waitcnt vmcnt(7)
	ds_write_b128 v147, v[40:43] offset:32768
	s_waitcnt lgkmcnt(7)
	v_mfma_f32_16x16x32_f16 v[108:111], v[166:169], v[156:159], v[108:111]
	v_mfma_f32_16x16x32_f16 v[36:39], v[192:195], v[156:159], v[36:39]
	v_mfma_f32_16x16x32_f16 v[104:107], v[196:199], v[156:159], v[104:107]
	v_mfma_f32_16x16x32_f16 v[32:35], v[200:203], v[156:159], v[32:35]
	ds_read_b128 v[156:159], v242
	s_waitcnt vmcnt(6)
	ds_write_b128 v147, v[48:51] offset:36864
	s_waitcnt lgkmcnt(8)
	v_mfma_f32_16x16x32_f16 v[28:31], v[166:169], v[160:163], v[28:31]
	v_mfma_f32_16x16x32_f16 v[20:23], v[192:195], v[160:163], v[20:23]
	v_mfma_f32_16x16x32_f16 v[24:27], v[196:199], v[160:163], v[24:27]
	v_mfma_f32_16x16x32_f16 v[16:19], v[200:203], v[160:163], v[16:19]
	ds_read_b128 v[160:163], v242 offset:2048
	s_waitcnt vmcnt(5)
; template <int NJ>
; __device__ __forceinline__ void gemm_tile(const f16* __restrict__ A, int lda, const f16* __restrict__ Bt, int ldb,
;                                           int K, f32x4 (&acc)[4][NJ], f16* sA, f16* sB, const int tid) {
;     ...
;   G_LOAD(ra0, rb0, 0)
;   if (K > 64) G_LOAD(ra1, rb1, 64)
;   __syncthreads();
;   G_STORE(ra0, rb0, 0)
;   if (K > 128) G_LOAD(ra0, rb0, 128)
;   __syncthreads();
; #pragma unroll 1
;   for (int k0 = 0; k0 < K; k0 += 128) {
;     {
;       const int kof = (k0 + 192 < K) ? k0 + 192 : K - 64;
;       G_STEP(0, ra1, rb1, true, true, kof)
;     }
;     __syncthreads();
;     if (k0 + 64 >= K) break;
;     {
;       const int kof = (k0 + 256 < K) ? k0 + 256 : K - 64;
;       G_STEP(1, ra0, rb0, true, true, kof)
;     }
;     __syncthreads();
;   }
	ds_write_b128 v147, v[52:55] offset:40960
	s_waitcnt lgkmcnt(9)
	v_mfma_f32_16x16x32_f16 v[12:15], v[166:169], v[128:131], v[12:15]
	v_mfma_f32_16x16x32_f16 v[4:7], v[192:195], v[128:131], v[4:7]
	v_mfma_f32_16x16x32_f16 v[8:11], v[196:199], v[128:131], v[8:11]
	v_mfma_f32_16x16x32_f16 v[0:3], v[200:203], v[128:131], v[0:3]
	ds_read_b128 v[128:131], v242 offset:4096
	ds_read_b128 v[166:169], v242 offset:6144
	s_waitcnt vmcnt(4)
	ds_write_b128 v147, v[56:59] offset:45056
	s_waitcnt lgkmcnt(6)
	v_mfma_f32_16x16x32_f16 v[124:127], v[244:247], v[156:159], v[124:127]
	v_mfma_f32_16x16x32_f16 v[116:119], v[248:251], v[156:159], v[116:119]
	v_mfma_f32_16x16x32_f16 v[120:123], v[252:255], v[156:159], v[120:123]
	v_mfma_f32_16x16x32_f16 v[112:115], v[152:155], v[156:159], v[112:115]
	s_waitcnt vmcnt(3)
	ds_write_b128 v147, v[44:47] offset:49152
	v_lshl_add_u64 v[202:203], v[138:139], 0, s[14:15]
	s_waitcnt lgkmcnt(5)
	v_mfma_f32_16x16x32_f16 v[108:111], v[244:247], v[160:163], v[108:111]
	v_lshl_add_u64 v[200:201], v[140:141], 0, s[14:15]
	v_mfma_f32_16x16x32_f16 v[36:39], v[248:251], v[160:163], v[36:39]
	v_mfma_f32_16x16x32_f16 v[104:107], v[252:255], v[160:163], v[104:107]
	v_mfma_f32_16x16x32_f16 v[32:35], v[152:155], v[160:163], v[32:35]
	s_waitcnt vmcnt(2)
	ds_write_b128 v147, v[60:63] offset:53248
	s_waitcnt lgkmcnt(4)
	v_mfma_f32_16x16x32_f16 v[28:31], v[244:247], v[128:131], v[28:31]
	v_mfma_f32_16x16x32_f16 v[20:23], v[248:251], v[128:131], v[20:23]
	v_mfma_f32_16x16x32_f16 v[24:27], v[252:255], v[128:131], v[24:27]
	v_mfma_f32_16x16x32_f16 v[16:19], v[152:155], v[128:131], v[16:19]
	s_waitcnt vmcnt(1)
	ds_write_b128 v147, v[68:71] offset:57344
	s_waitcnt lgkmcnt(4)
	v_mfma_f32_16x16x32_f16 v[12:15], v[244:247], v[166:169], v[12:15]
	v_mfma_f32_16x16x32_f16 v[4:7], v[248:251], v[166:169], v[4:7]
	v_mfma_f32_16x16x32_f16 v[8:11], v[252:255], v[166:169], v[8:11]
	v_mfma_f32_16x16x32_f16 v[0:3], v[152:155], v[166:169], v[0:3]
	s_waitcnt vmcnt(0)
	ds_write_b128 v147, v[72:75] offset:61440
	s_waitcnt lgkmcnt(0)
	s_barrier
	ds_read_b128 v[160:163], v148 offset:49152
	ds_read_b128 v[166:169], v148 offset:51200
	ds_read_b128 v[192:195], v148 offset:53248
	ds_read_b128 v[196:199], v148 offset:55296
	ds_read_b128 v[128:131], v150 offset:32768
	ds_read_b128 v[142:145], v150 offset:34816
	ds_read_b128 v[152:155], v150 offset:36864
	ds_read_b128 v[156:159], v150 offset:38912
	ds_read_b128 v[244:247], v243 offset:49152
	ds_read_b128 v[248:251], v243 offset:51200
	ds_read_b128 v[252:255], v243 offset:53248
	s_waitcnt lgkmcnt(6)
	v_mfma_f32_16x16x32_f16 v[124:127], v[160:163], v[128:131], v[124:127]
	v_mfma_f32_16x16x32_f16 v[116:119], v[166:169], v[128:131], v[116:119]
	v_mfma_f32_16x16x32_f16 v[120:123], v[192:195], v[128:131], v[120:123]
	v_mfma_f32_16x16x32_f16 v[112:115], v[196:199], v[128:131], v[112:115]
	ds_read_b128 v[128:131], v243 offset:55296
	s_waitcnt lgkmcnt(6)
	v_mfma_f32_16x16x32_f16 v[108:111], v[160:163], v[142:145], v[108:111]
	v_mfma_f32_16x16x32_f16 v[36:39], v[166:169], v[142:145], v[36:39]
	v_mfma_f32_16x16x32_f16 v[104:107], v[192:195], v[142:145], v[104:107]
	v_mfma_f32_16x16x32_f16 v[32:35], v[196:199], v[142:145], v[32:35]
	ds_read_b128 v[142:145], v242 offset:32768
	s_waitcnt lgkmcnt(6)
	v_mfma_f32_16x16x32_f16 v[28:31], v[160:163], v[152:155], v[28:31]
	v_mfma_f32_16x16x32_f16 v[20:23], v[166:169], v[152:155], v[20:23]
	v_mfma_f32_16x16x32_f16 v[24:27], v[192:195], v[152:155], v[24:27]
	v_mfma_f32_16x16x32_f16 v[16:19], v[196:199], v[152:155], v[16:19]
	ds_read_b128 v[152:155], v242 offset:34816
	s_waitcnt lgkmcnt(6)
	v_mfma_f32_16x16x32_f16 v[12:15], v[160:163], v[156:159], v[12:15]
	v_mfma_f32_16x16x32_f16 v[4:7], v[166:169], v[156:159], v[4:7]
	v_mfma_f32_16x16x32_f16 v[8:11], v[192:195], v[156:159], v[8:11]
	v_mfma_f32_16x16x32_f16 v[0:3], v[196:199], v[156:159], v[0:3]
	ds_read_b128 v[156:159], v242 offset:36864
	ds_read_b128 v[160:163], v242 offset:38912
	s_waitcnt lgkmcnt(3)
	v_mfma_f32_16x16x32_f16 v[124:127], v[244:247], v[142:145], v[124:127]
	v_mfma_f32_16x16x32_f16 v[116:119], v[248:251], v[142:145], v[116:119]
	v_mfma_f32_16x16x32_f16 v[120:123], v[252:255], v[142:145], v[120:123]
	v_mfma_f32_16x16x32_f16 v[112:115], v[128:131], v[142:145], v[112:115]
	s_waitcnt lgkmcnt(2)
	v_mfma_f32_16x16x32_f16 v[108:111], v[244:247], v[152:155], v[108:111]
	v_mfma_f32_16x16x32_f16 v[36:39], v[248:251], v[152:155], v[36:39]
	v_mfma_f32_16x16x32_f16 v[104:107], v[252:255], v[152:155], v[104:107]
	v_mfma_f32_16x16x32_f16 v[32:35], v[128:131], v[152:155], v[32:35]
	s_waitcnt lgkmcnt(1)
	v_mfma_f32_16x16x32_f16 v[28:31], v[244:247], v[156:159], v[28:31]
	v_mfma_f32_16x16x32_f16 v[20:23], v[248:251], v[156:159], v[20:23]
	v_mfma_f32_16x16x32_f16 v[24:27], v[252:255], v[156:159], v[24:27]
	v_mfma_f32_16x16x32_f16 v[16:19], v[128:131], v[156:159], v[16:19]
	s_waitcnt lgkmcnt(0)
	v_mfma_f32_16x16x32_f16 v[12:15], v[244:247], v[160:163], v[12:15]
	v_mfma_f32_16x16x32_f16 v[4:7], v[248:251], v[160:163], v[4:7]
	v_mfma_f32_16x16x32_f16 v[8:11], v[252:255], v[160:163], v[8:11]
	v_mfma_f32_16x16x32_f16 v[0:3], v[128:131], v[160:163], v[0:3]
	s_waitcnt lgkmcnt(0)
	s_barrier
; __device__ __forceinline__ float siluf_(float x) { return x / (1.0f + __expf(-x)); }
; __device__ __forceinline__ void phase_g4(const Params& p, f16* smem) {
;     ...
; #pragma unroll
;     for (int i = 0; i < 4; ++i) {
;       int m = m0 + wm * 64 + i * 16 + (lane & 15);
; #pragma unroll
;       for (int jj = 0; jj < 2; ++jj) {
;         int u = nt * 64 + wn * 32 + jj * 16 + 4 * (lane >> 4);
;         f16x4 o;
; #pragma unroll
;         for (int r = 0; r < 4; ++r) o[r] = (f16)(siluf_(acc[i][jj][r]) * acc[i][jj + 2][r]);
;         *(f16x4*)(hid + (size_t)m * FF + u) = o;
;       }
	s_waitcnt vmcnt(15)
	v_mul_f32_e32 v41, 0xbfb8aa3b, v124
	s_waitcnt vmcnt(11)
	v_exp_f32_e32 v46, v41
	v_mul_f32_e32 v41, 0xbfb8aa3b, v125
	v_exp_f32_e32 v47, v41
	v_add_u32_e32 v42, s10, v146
	v_lshl_or_b32 v40, s12, 6, v149
	v_mad_i64_i32 v[44:45], s[10:11], v42, s96, v[132:133]
	v_pk_add_f32 v[46:47], v[46:47], 1.0 op_sel_hi:[1,0]
	s_add_i32 s5, s5, s26
	s_movk_i32 s14, 0x2cb0
	s_cmp_eq_u32 s4, 3
	s_cselect_b32 s14, 0x2c00, s14
	s_cmp_lt_i32 s5, s14
	v_rcp_f32_e32 v43, v47
	s_nop 0
	v_mul_f32_e32 v41, v125, v43
	v_mov_b32_e32 v47, v41
	s_nop 0
	v_rcp_f32_e32 v43, v46
	s_nop 0
	v_mul_f32_e32 v41, v124, v43
	v_mov_b32_e32 v46, v41
	v_mul_f32_e32 v41, 0xbfb8aa3b, v126
	v_exp_f32_e32 v48, v41
	v_mul_f32_e32 v41, 0xbfb8aa3b, v127
	v_exp_f32_e32 v49, v41
	v_pk_mul_f32 v[46:47], v[120:121], v[46:47]
	v_pk_add_f32 v[48:49], v[48:49], 1.0 op_sel_hi:[1,0]
	s_nop 0
	v_cvt_pk_f16_f32 v46, v46, v47
	v_rcp_f32_e32 v43, v49
	s_nop 0
	v_mul_f32_e32 v41, v127, v43
	v_mov_b32_e32 v49, v41
	s_nop 0
	v_rcp_f32_e32 v43, v48
	s_nop 0
	v_mul_f32_e32 v41, v126, v43
	v_mov_b32_e32 v48, v41
	v_ashrrev_i32_e32 v41, 31, v40
	v_pk_mul_f32 v[48:49], v[122:123], v[48:49]
	v_lshlrev_b64 v[40:41], 1, v[40:41]
	v_cvt_pk_f16_f32 v47, v48, v49
	v_lshl_add_u64 v[44:45], v[44:45], 0, v[40:41]
	v_mul_f32_e32 v43, 0xbfb8aa3b, v116
	global_store_dwordx2 v[44:45], v[46:47], off
	v_exp_f32_e32 v46, v43
	v_mul_f32_e32 v43, 0xbfb8aa3b, v117
	v_exp_f32_e32 v47, v43
	s_nop 0
	v_pk_add_f32 v[46:47], v[46:47], 1.0 op_sel_hi:[1,0]
	s_nop 0
	s_nop 0
	v_rcp_f32_e32 v48, v47
	s_nop 0
	v_mul_f32_e32 v43, v117, v48
	v_mov_b32_e32 v47, v43
	s_nop 0
	v_rcp_f32_e32 v48, v46
	s_nop 0
	v_mul_f32_e32 v43, v116, v48
	v_mov_b32_e32 v46, v43
	v_mul_f32_e32 v43, 0xbfb8aa3b, v118
	v_exp_f32_e32 v48, v43
	v_mul_f32_e32 v43, 0xbfb8aa3b, v119
	v_exp_f32_e32 v49, v43
	v_pk_mul_f32 v[46:47], v[112:113], v[46:47]
	v_pk_add_f32 v[48:49], v[48:49], 1.0 op_sel_hi:[1,0]
	s_nop 0
	v_cvt_pk_f16_f32 v46, v46, v47
	s_nop 0
	v_rcp_f32_e32 v47, v49
	s_nop 0
	v_mul_f32_e32 v43, v119, v47
	v_mov_b32_e32 v49, v43
	s_nop 0
	v_rcp_f32_e32 v47, v48
	s_nop 0
	v_mul_f32_e32 v43, v118, v47
	v_mov_b32_e32 v48, v43
	v_pk_mul_f32 v[48:49], v[114:115], v[48:49]
	v_or_b32_e32 v43, 16, v42
	v_cvt_pk_f16_f32 v47, v48, v49
	global_store_dwordx2 v[44:45], v[46:47], off offset:32
	v_mad_i64_i32 v[44:45], s[10:11], v43, s96, v[132:133]
	v_mul_f32_e32 v43, 0xbfb8aa3b, v108
	v_exp_f32_e32 v46, v43
	v_mul_f32_e32 v43, 0xbfb8aa3b, v109
	v_exp_f32_e32 v47, v43
	v_lshl_add_u64 v[44:45], v[44:45], 0, v[40:41]
	v_pk_add_f32 v[46:47], v[46:47], 1.0 op_sel_hi:[1,0]
	s_nop 0
	s_nop 0
	v_rcp_f32_e32 v48, v47
	s_nop 0
	v_mul_f32_e32 v43, v109, v48
	v_mov_b32_e32 v47, v43
	s_nop 0
	v_rcp_f32_e32 v48, v46
	s_nop 0
	v_mul_f32_e32 v43, v108, v48
	v_mov_b32_e32 v46, v43
	v_mul_f32_e32 v43, 0xbfb8aa3b, v110
	v_exp_f32_e32 v48, v43
	v_mul_f32_e32 v43, 0xbfb8aa3b, v111
	v_exp_f32_e32 v49, v43
	v_pk_mul_f32 v[46:47], v[104:105], v[46:47]
	v_pk_add_f32 v[48:49], v[48:49], 1.0 op_sel_hi:[1,0]
	s_nop 0
	v_cvt_pk_f16_f32 v46, v46, v47
	s_nop 0
	v_rcp_f32_e32 v47, v49
	s_nop 0
	v_mul_f32_e32 v43, v111, v47
	v_mov_b32_e32 v49, v43
	s_nop 0
	v_rcp_f32_e32 v47, v48
	s_nop 0
	v_mul_f32_e32 v43, v110, v47
	v_mov_b32_e32 v48, v43
	v_pk_mul_f32 v[48:49], v[106:107], v[48:49]
	v_mul_f32_e32 v43, 0xbfb8aa3b, v36
	v_cvt_pk_f16_f32 v47, v48, v49
	global_store_dwordx2 v[44:45], v[46:47], off
	v_exp_f32_e32 v46, v43
	v_mul_f32_e32 v43, 0xbfb8aa3b, v37
	v_exp_f32_e32 v47, v43
	s_nop 0
	v_pk_add_f32 v[46:47], v[46:47], 1.0 op_sel_hi:[1,0]
	s_nop 0
	s_nop 0
	v_rcp_f32_e32 v48, v47
	s_nop 0
	v_mul_f32_e32 v43, v37, v48
	v_mov_b32_e32 v37, v43
	s_nop 0
	v_rcp_f32_e32 v47, v46
	s_nop 0
	v_mul_f32_e32 v43, v36, v47
	v_mov_b32_e32 v36, v43
	v_pk_mul_f32 v[32:33], v[32:33], v[36:37]
	s_nop 0
	v_cvt_pk_f16_f32 v32, v32, v33
	v_mul_f32_e32 v33, 0xbfb8aa3b, v38
	v_exp_f32_e32 v36, v33
	v_mul_f32_e32 v33, 0xbfb8aa3b, v39
	v_exp_f32_e32 v37, v33
	s_nop 0
	v_pk_add_f32 v[36:37], v[36:37], 1.0 op_sel_hi:[1,0]
	s_nop 0
	s_nop 0
	v_rcp_f32_e32 v43, v37
	s_nop 0
	v_mul_f32_e32 v33, v39, v43
	v_mov_b32_e32 v37, v33
	s_nop 0
	v_rcp_f32_e32 v39, v36
	s_nop 0
	v_mul_f32_e32 v33, v38, v39
	v_mov_b32_e32 v36, v33
; __device__ __forceinline__ float siluf_(float x) { return x / (1.0f + __expf(-x)); }
; __device__ __forceinline__ void phase_g4(const Params& p, f16* smem) {
;     ...
; #pragma unroll
;     for (int i = 0; i < 4; ++i) {
;       int m = m0 + wm * 64 + i * 16 + (lane & 15);
; #pragma unroll
;       for (int jj = 0; jj < 2; ++jj) {
;         int u = nt * 64 + wn * 32 + jj * 16 + 4 * (lane >> 4);
;         f16x4 o;
; #pragma unroll
;         for (int r = 0; r < 4; ++r) o[r] = (f16)(siluf_(acc[i][jj][r]) * acc[i][jj + 2][r]);
;         *(f16x4*)(hid + (size_t)m * FF + u) = o;
;       }
	v_pk_mul_f32 v[34:35], v[34:35], v[36:37]
	s_nop 0
	v_cvt_pk_f16_f32 v33, v34, v35
	v_mul_f32_e32 v34, 0xbfb8aa3b, v28
	v_mul_f32_e32 v35, 0xbfb8aa3b, v29
	v_exp_f32_e32 v34, v34
	v_exp_f32_e32 v35, v35
	global_store_dwordx2 v[44:45], v[32:33], off offset:32
	v_or_b32_e32 v32, 32, v42
	v_mad_i64_i32 v[32:33], s[10:11], v32, s96, v[132:133]
	v_pk_add_f32 v[34:35], v[34:35], 1.0 op_sel_hi:[1,0]
	s_nop 0
	s_nop 0
	v_rcp_f32_e32 v37, v35
	s_nop 0
	v_mul_f32_e32 v36, v29, v37
	v_mov_b32_e32 v29, v36
	s_nop 0
	v_rcp_f32_e32 v36, v34
	s_nop 0
	v_mul_f32_e32 v35, v28, v36
	v_mov_b32_e32 v28, v35
	v_pk_mul_f32 v[24:25], v[24:25], v[28:29]
	s_nop 0
	v_cvt_pk_f16_f32 v24, v24, v25
	v_mul_f32_e32 v25, 0xbfb8aa3b, v30
	v_exp_f32_e32 v28, v25
	v_mul_f32_e32 v25, 0xbfb8aa3b, v31
	v_exp_f32_e32 v29, v25
	s_nop 0
	v_pk_add_f32 v[28:29], v[28:29], 1.0 op_sel_hi:[1,0]
	s_nop 0
	s_nop 0
	v_rcp_f32_e32 v34, v29
	s_nop 0
	v_mul_f32_e32 v25, v31, v34
	v_mov_b32_e32 v29, v25
	s_nop 0
	v_rcp_f32_e32 v31, v28
	s_nop 0
	v_mul_f32_e32 v25, v30, v31
	v_mov_b32_e32 v28, v25
	v_pk_mul_f32 v[26:27], v[26:27], v[28:29]
	s_nop 0
	v_cvt_pk_f16_f32 v25, v26, v27
	v_lshl_add_u64 v[26:27], v[32:33], 0, v[40:41]
	global_store_dwordx2 v[26:27], v[24:25], off
	v_mul_f32_e32 v24, 0xbfb8aa3b, v20
	v_mul_f32_e32 v25, 0xbfb8aa3b, v21
	v_exp_f32_e32 v24, v24
	v_exp_f32_e32 v25, v25
	s_nop 0
	v_pk_add_f32 v[24:25], v[24:25], 1.0 op_sel_hi:[1,0]
	s_nop 0
	s_nop 0
	v_rcp_f32_e32 v29, v25
	s_nop 0
	v_mul_f32_e32 v28, v21, v29
	v_mov_b32_e32 v21, v28
	s_nop 0
	v_rcp_f32_e32 v28, v24
	s_nop 0
	v_mul_f32_e32 v25, v20, v28
	v_mov_b32_e32 v20, v25
	v_pk_mul_f32 v[16:17], v[16:17], v[20:21]
	s_nop 0
	v_cvt_pk_f16_f32 v16, v16, v17
	v_mul_f32_e32 v17, 0xbfb8aa3b, v22
	v_exp_f32_e32 v20, v17
	v_mul_f32_e32 v17, 0xbfb8aa3b, v23
	v_exp_f32_e32 v21, v17
	s_nop 0
	v_pk_add_f32 v[20:21], v[20:21], 1.0 op_sel_hi:[1,0]
	s_nop 0
	s_nop 0
	v_rcp_f32_e32 v24, v21
	s_nop 0
	v_mul_f32_e32 v17, v23, v24
	v_mov_b32_e32 v21, v17
	s_nop 0
	v_rcp_f32_e32 v23, v20
	s_nop 0
	v_mul_f32_e32 v17, v22, v23
	v_mov_b32_e32 v20, v17
	v_pk_mul_f32 v[18:19], v[18:19], v[20:21]
	s_nop 0
	v_cvt_pk_f16_f32 v17, v18, v19
	v_mul_f32_e32 v18, 0xbfb8aa3b, v12
	v_mul_f32_e32 v19, 0xbfb8aa3b, v13
	v_exp_f32_e32 v18, v18
	v_exp_f32_e32 v19, v19
	global_store_dwordx2 v[26:27], v[16:17], off offset:32
	v_or_b32_e32 v16, 48, v42
	v_mad_i64_i32 v[16:17], s[10:11], v16, s96, v[132:133]
	v_pk_add_f32 v[18:19], v[18:19], 1.0 op_sel_hi:[1,0]
	s_nop 0
	s_nop 0
	v_rcp_f32_e32 v21, v19
	s_nop 0
	v_mul_f32_e32 v20, v13, v21
	v_mov_b32_e32 v13, v20
	s_nop 0
	v_rcp_f32_e32 v20, v18
	s_nop 0
	v_mul_f32_e32 v19, v12, v20
	v_mov_b32_e32 v12, v19
	v_pk_mul_f32 v[8:9], v[8:9], v[12:13]
	s_nop 0
	v_cvt_pk_f16_f32 v8, v8, v9
	v_mul_f32_e32 v9, 0xbfb8aa3b, v14
	v_exp_f32_e32 v12, v9
	v_mul_f32_e32 v9, 0xbfb8aa3b, v15
	v_exp_f32_e32 v13, v9
	s_nop 0
	v_pk_add_f32 v[12:13], v[12:13], 1.0 op_sel_hi:[1,0]
	s_nop 0
	s_nop 0
	v_rcp_f32_e32 v18, v13
	s_nop 0
	v_mul_f32_e32 v9, v15, v18
	v_mov_b32_e32 v13, v9
	s_nop 0
	v_rcp_f32_e32 v15, v12
	s_nop 0
	v_mul_f32_e32 v9, v14, v15
	v_mov_b32_e32 v12, v9
	v_pk_mul_f32 v[10:11], v[10:11], v[12:13]
	s_nop 0
	v_cvt_pk_f16_f32 v9, v10, v11
	v_lshl_add_u64 v[10:11], v[16:17], 0, v[40:41]
	global_store_dwordx2 v[10:11], v[8:9], off
	v_mul_f32_e32 v8, 0xbfb8aa3b, v4
	v_mul_f32_e32 v9, 0xbfb8aa3b, v5
	v_exp_f32_e32 v8, v8
	v_exp_f32_e32 v9, v9
	s_nop 0
	v_pk_add_f32 v[8:9], v[8:9], 1.0 op_sel_hi:[1,0]
	s_nop 0
	s_nop 0
	v_rcp_f32_e32 v13, v9
	s_nop 0
	v_mul_f32_e32 v12, v5, v13
	v_mov_b32_e32 v5, v12
	s_nop 0
	v_rcp_f32_e32 v12, v8
	s_nop 0
	v_mul_f32_e32 v9, v4, v12
	v_mov_b32_e32 v4, v9
	v_pk_mul_f32 v[0:1], v[0:1], v[4:5]
	s_nop 0
	v_cvt_pk_f16_f32 v0, v0, v1
	v_mul_f32_e32 v1, 0xbfb8aa3b, v6
	v_exp_f32_e32 v4, v1
	v_mul_f32_e32 v1, 0xbfb8aa3b, v7
	v_exp_f32_e32 v5, v1
	s_nop 0
	v_pk_add_f32 v[4:5], v[4:5], 1.0 op_sel_hi:[1,0]
	s_nop 0
	s_nop 0
	v_rcp_f32_e32 v8, v5
	s_nop 0
	v_mul_f32_e32 v1, v7, v8
	v_mov_b32_e32 v5, v1
	s_nop 0
	v_rcp_f32_e32 v7, v4
	s_nop 0
	v_mul_f32_e32 v1, v6, v7
	v_mov_b32_e32 v4, v1
	v_pk_mul_f32 v[2:3], v[2:3], v[4:5]
	s_nop 0
	v_cvt_pk_f16_f32 v1, v2, v3
	global_store_dwordx2 v[10:11], v[0:1], off offset:32
	s_cbranch_scc1 .LBB0_1397

; template <int NJ>
; __device__ __forceinline__ void gemm_tile(const f16* __restrict__ A, int lda, const f16* __restrict__ Bt, int ldb,
;                                           int K, f32x4 (&acc)[4][NJ], f16* sA, f16* sB, const int tid) {
;     ...
;   G_LOAD(ra0, rb0, 0)
;   if (K > 64) G_LOAD(ra1, rb1, 64)
;   __syncthreads();
;   G_STORE(ra0, rb0, 0)
;   if (K > 128) G_LOAD(ra0, rb0, 128)
;   __syncthreads();
; #pragma unroll 1
;   for (int k0 = 0; k0 < K; k0 += 128) {
;     {
;       const int kof = (k0 + 192 < K) ? k0 + 192 : K - 64;
;       G_STEP(0, ra1, rb1, true, true, kof)
.LBB0_1457:
	ds_read_b128 v[204:207], v163 offset:16384
	ds_read_b128 v[208:211], v163 offset:18432
	ds_read_b128 v[212:215], v163 offset:20480
	ds_read_b128 v[216:219], v163 offset:22528
	s_add_i32 s11, s10, 0xc0
	ds_read_b128 v[192:195], v162
	ds_read_b128 v[196:199], v162 offset:2048
	s_cmpk_lt_u32 s10, 0xa40
	s_cselect_b32 s42, s11, 0xac0
	ds_read_b128 v[200:203], v162 offset:4096
	s_lshl_b64 s[12:13], s[42:43], 1
	v_lshl_add_u64 v[152:153], v[146:147], 0, s[12:13]
	ds_read_b128 v[130:133], v162 offset:6144
	ds_read_b128 v[244:247], v243 offset:16384
	ds_read_b128 v[248:251], v243 offset:18432
	ds_read_b128 v[252:255], v243 offset:20480
	s_waitcnt lgkmcnt(6)
	v_mfma_f32_16x16x32_f16 v[126:129], v[204:207], v[192:195], v[126:129]
	v_lshl_add_u64 v[150:151], v[148:149], 0, s[12:13]
	s_add_i32 s11, s10, 0x100
	s_cmpk_lt_u32 s10, 0xa00
	v_mfma_f32_16x16x32_f16 v[122:125], v[208:211], v[192:195], v[122:125]
	s_cselect_b32 s42, s11, 0xac0
	s_lshl_b64 s[12:13], s[42:43], 1
	v_lshl_add_u64 v[168:169], v[148:149], 0, s[12:13]
	v_mfma_f32_16x16x32_f16 v[118:121], v[212:215], v[192:195], v[118:121]
	s_add_i32 s11, s10, 0x80
	s_cmpk_lt_u32 s10, 0x980
	s_mov_b32 s10, s11
	v_mfma_f32_16x16x32_f16 v[114:117], v[216:219], v[192:195], v[114:117]
	ds_read_b128 v[192:195], v243 offset:22528
	s_waitcnt vmcnt(15)
	ds_write_b128 v161, v[18:21] offset:32768
	global_load_dwordx4 v[18:21], v[152:153], off
	s_waitcnt lgkmcnt(7)
	v_mfma_f32_16x16x32_f16 v[110:113], v[204:207], v[196:199], v[110:113]
	v_mfma_f32_16x16x32_f16 v[106:109], v[208:211], v[196:199], v[106:109]
	v_mfma_f32_16x16x32_f16 v[102:105], v[212:215], v[196:199], v[102:105]
	v_mfma_f32_16x16x32_f16 v[98:101], v[216:219], v[196:199], v[98:101]
	ds_read_b128 v[196:199], v242
	s_waitcnt vmcnt(15)
	ds_write_b128 v161, v[26:29] offset:36864
	v_add_co_u32_e32 v26, vcc, s81, v152
	s_nop 1
	v_addc_co_u32_e32 v27, vcc, 0, v153, vcc
	global_load_dwordx4 v[26:29], v[26:27], off
	s_waitcnt lgkmcnt(8)
	v_mfma_f32_16x16x32_f16 v[94:97], v[204:207], v[200:203], v[94:97]
	v_mfma_f32_16x16x32_f16 v[90:93], v[208:211], v[200:203], v[90:93]
	v_mfma_f32_16x16x32_f16 v[86:89], v[212:215], v[200:203], v[86:89]
	v_mfma_f32_16x16x32_f16 v[82:85], v[216:219], v[200:203], v[82:85]
	ds_read_b128 v[200:203], v242 offset:2048
	s_waitcnt vmcnt(14)
	ds_write_b128 v161, v[30:33] offset:40960
	v_add_co_u32_e32 v30, vcc, s97, v152
	s_nop 1
	v_addc_co_u32_e32 v31, vcc, 0, v153, vcc
	global_load_dwordx4 v[30:33], v[30:31], off
	s_waitcnt lgkmcnt(9)
	v_mfma_f32_16x16x32_f16 v[14:17], v[204:207], v[130:133], v[14:17]
	v_mfma_f32_16x16x32_f16 v[10:13], v[208:211], v[130:133], v[10:13]
	v_mfma_f32_16x16x32_f16 v[6:9], v[212:215], v[130:133], v[6:9]
	v_mfma_f32_16x16x32_f16 v[2:5], v[216:219], v[130:133], v[2:5]
	ds_read_b128 v[130:133], v242 offset:4096
	ds_read_b128 v[204:207], v242 offset:6144
	s_waitcnt vmcnt(14)
	ds_write_b128 v161, v[34:37] offset:45056
	v_add_co_u32_e32 v34, vcc, s27, v152
	s_nop 1
	v_addc_co_u32_e32 v35, vcc, 0, v153, vcc
	global_load_dwordx4 v[34:37], v[34:35], off
	s_waitcnt lgkmcnt(6)
	v_mfma_f32_16x16x32_f16 v[126:129], v[244:247], v[196:199], v[126:129]
	v_mfma_f32_16x16x32_f16 v[122:125], v[248:251], v[196:199], v[122:125]
	v_mfma_f32_16x16x32_f16 v[118:121], v[252:255], v[196:199], v[118:121]
	v_mfma_f32_16x16x32_f16 v[114:117], v[192:195], v[196:199], v[114:117]
	ds_write_b128 v161, v[22:25] offset:49152
	global_load_dwordx4 v[22:25], v[150:151], off
	v_lshl_add_u64 v[216:217], v[146:147], 0, s[12:13]
	s_waitcnt lgkmcnt(5)
	v_mfma_f32_16x16x32_f16 v[110:113], v[244:247], v[200:203], v[110:113]
	v_mfma_f32_16x16x32_f16 v[106:109], v[248:251], v[200:203], v[106:109]
	v_mfma_f32_16x16x32_f16 v[102:105], v[252:255], v[200:203], v[102:105]
	v_mfma_f32_16x16x32_f16 v[98:101], v[192:195], v[200:203], v[98:101]
	s_waitcnt vmcnt(15)
	ds_write_b128 v161, v[38:41] offset:53248
	v_add_co_u32_e32 v38, vcc, s81, v150
	s_nop 1
	v_addc_co_u32_e32 v39, vcc, 0, v151, vcc
	global_load_dwordx4 v[38:41], v[38:39], off
	s_waitcnt lgkmcnt(4)
	v_mfma_f32_16x16x32_f16 v[94:97], v[244:247], v[130:133], v[94:97]
	v_mfma_f32_16x16x32_f16 v[90:93], v[248:251], v[130:133], v[90:93]
	v_mfma_f32_16x16x32_f16 v[86:89], v[252:255], v[130:133], v[86:89]
	v_mfma_f32_16x16x32_f16 v[82:85], v[192:195], v[130:133], v[82:85]
	s_waitcnt vmcnt(15)
	ds_write_b128 v161, v[46:49] offset:57344
	v_add_co_u32_e32 v46, vcc, s97, v150
	s_nop 1
	v_addc_co_u32_e32 v47, vcc, 0, v151, vcc
	global_load_dwordx4 v[46:49], v[46:47], off
	s_waitcnt lgkmcnt(4)
	v_mfma_f32_16x16x32_f16 v[14:17], v[244:247], v[204:207], v[14:17]
	v_mfma_f32_16x16x32_f16 v[10:13], v[248:251], v[204:207], v[10:13]
	v_mfma_f32_16x16x32_f16 v[6:9], v[252:255], v[204:207], v[6:9]
	v_mfma_f32_16x16x32_f16 v[2:5], v[192:195], v[204:207], v[2:5]
	s_waitcnt vmcnt(15)
	ds_write_b128 v161, v[50:53] offset:61440
	v_add_co_u32_e32 v50, vcc, s27, v150
	s_nop 1
	v_addc_co_u32_e32 v51, vcc, 0, v151, vcc
	global_load_dwordx4 v[50:53], v[50:51], off
	s_waitcnt lgkmcnt(0)
	s_barrier
; template <int NJ>
; __device__ __forceinline__ void gemm_tile(const f16* __restrict__ A, int lda, const f16* __restrict__ Bt, int ldb,
;                                           int K, f32x4 (&acc)[4][NJ], f16* sA, f16* sB, const int tid) {
;     ...
;     {
;       const int kof = (k0 + 256 < K) ? k0 + 256 : K - 64;
;       G_STEP(1, ra0, rb0, true, true, kof)
;     }
;     __syncthreads();
;   }
	ds_read_b128 v[200:203], v163 offset:49152
	ds_read_b128 v[204:207], v163 offset:51200
	ds_read_b128 v[208:211], v163 offset:53248
	ds_read_b128 v[212:215], v163 offset:55296
	ds_read_b128 v[130:133], v162 offset:32768
	ds_read_b128 v[150:153], v162 offset:34816
	ds_read_b128 v[192:195], v162 offset:36864
	ds_read_b128 v[196:199], v162 offset:38912
	ds_read_b128 v[244:247], v243 offset:49152
	ds_read_b128 v[248:251], v243 offset:51200
	ds_read_b128 v[252:255], v243 offset:53248
	s_waitcnt lgkmcnt(6)
	v_mfma_f32_16x16x32_f16 v[126:129], v[200:203], v[130:133], v[126:129]
	v_mfma_f32_16x16x32_f16 v[122:125], v[204:207], v[130:133], v[122:125]
	v_mfma_f32_16x16x32_f16 v[118:121], v[208:211], v[130:133], v[118:121]
	v_mfma_f32_16x16x32_f16 v[114:117], v[212:215], v[130:133], v[114:117]
	ds_read_b128 v[130:133], v243 offset:55296
	s_waitcnt vmcnt(13)
	ds_write_b128 v161, v[42:45]
	global_load_dwordx4 v[42:45], v[216:217], off
	s_waitcnt lgkmcnt(7)
	v_mfma_f32_16x16x32_f16 v[110:113], v[200:203], v[150:153], v[110:113]
	v_mfma_f32_16x16x32_f16 v[106:109], v[204:207], v[150:153], v[106:109]
	v_mfma_f32_16x16x32_f16 v[102:105], v[208:211], v[150:153], v[102:105]
	v_mfma_f32_16x16x32_f16 v[98:101], v[212:215], v[150:153], v[98:101]
	ds_read_b128 v[150:153], v242 offset:32768
	ds_write_b128 v161, v[58:61] offset:4096
	v_add_co_u32_e32 v58, vcc, s81, v216
	s_nop 1
	v_addc_co_u32_e32 v59, vcc, 0, v217, vcc
	global_load_dwordx4 v[58:61], v[58:59], off
	s_waitcnt lgkmcnt(8)
	v_mfma_f32_16x16x32_f16 v[94:97], v[200:203], v[192:195], v[94:97]
	v_mfma_f32_16x16x32_f16 v[90:93], v[204:207], v[192:195], v[90:93]
	v_mfma_f32_16x16x32_f16 v[86:89], v[208:211], v[192:195], v[86:89]
	v_mfma_f32_16x16x32_f16 v[82:85], v[212:215], v[192:195], v[82:85]
	ds_read_b128 v[192:195], v242 offset:34816
	ds_write_b128 v161, v[62:65] offset:8192
	v_add_co_u32_e32 v62, vcc, s97, v216
	s_nop 1
	v_addc_co_u32_e32 v63, vcc, 0, v217, vcc
	global_load_dwordx4 v[62:65], v[62:63], off
	s_waitcnt lgkmcnt(9)
	v_mfma_f32_16x16x32_f16 v[14:17], v[200:203], v[196:199], v[14:17]
	v_mfma_f32_16x16x32_f16 v[10:13], v[204:207], v[196:199], v[10:13]
	v_mfma_f32_16x16x32_f16 v[6:9], v[208:211], v[196:199], v[6:9]
	v_mfma_f32_16x16x32_f16 v[2:5], v[212:215], v[196:199], v[2:5]
	ds_read_b128 v[196:199], v242 offset:36864
	ds_read_b128 v[200:203], v242 offset:38912
	s_waitcnt vmcnt(14)
	ds_write_b128 v161, v[66:69] offset:12288
	v_add_co_u32_e32 v66, vcc, s27, v216
	s_nop 1
	v_addc_co_u32_e32 v67, vcc, 0, v217, vcc
	global_load_dwordx4 v[66:69], v[66:67], off
	s_waitcnt lgkmcnt(6)
	v_mfma_f32_16x16x32_f16 v[126:129], v[244:247], v[150:153], v[126:129]
	v_mfma_f32_16x16x32_f16 v[122:125], v[248:251], v[150:153], v[122:125]
	v_mfma_f32_16x16x32_f16 v[118:121], v[252:255], v[150:153], v[118:121]
	v_mfma_f32_16x16x32_f16 v[114:117], v[130:133], v[150:153], v[114:117]
	ds_write_b128 v161, v[54:57] offset:16384
	global_load_dwordx4 v[54:57], v[168:169], off
	s_waitcnt lgkmcnt(5)
	v_mfma_f32_16x16x32_f16 v[110:113], v[244:247], v[192:195], v[110:113]
	v_mfma_f32_16x16x32_f16 v[106:109], v[248:251], v[192:195], v[106:109]
	v_mfma_f32_16x16x32_f16 v[102:105], v[252:255], v[192:195], v[102:105]
	v_mfma_f32_16x16x32_f16 v[98:101], v[130:133], v[192:195], v[98:101]
	s_waitcnt vmcnt(15)
	ds_write_b128 v161, v[70:73] offset:20480
	v_add_co_u32_e32 v70, vcc, s81, v168
	s_nop 1
	v_addc_co_u32_e32 v71, vcc, 0, v169, vcc
	global_load_dwordx4 v[70:73], v[70:71], off
	s_waitcnt lgkmcnt(4)
	v_mfma_f32_16x16x32_f16 v[94:97], v[244:247], v[196:199], v[94:97]
	v_mfma_f32_16x16x32_f16 v[90:93], v[248:251], v[196:199], v[90:93]
	v_mfma_f32_16x16x32_f16 v[86:89], v[252:255], v[196:199], v[86:89]
	v_mfma_f32_16x16x32_f16 v[82:85], v[130:133], v[196:199], v[82:85]
	s_waitcnt vmcnt(15)
	ds_write_b128 v161, v[74:77] offset:24576
	v_add_co_u32_e32 v74, vcc, s97, v168
	s_nop 1
	v_addc_co_u32_e32 v75, vcc, 0, v169, vcc
	global_load_dwordx4 v[74:77], v[74:75], off
	s_waitcnt lgkmcnt(4)
	v_mfma_f32_16x16x32_f16 v[14:17], v[244:247], v[200:203], v[14:17]
	v_mfma_f32_16x16x32_f16 v[10:13], v[248:251], v[200:203], v[10:13]
	v_mfma_f32_16x16x32_f16 v[6:9], v[252:255], v[200:203], v[6:9]
	v_mfma_f32_16x16x32_f16 v[2:5], v[130:133], v[200:203], v[2:5]
	s_waitcnt vmcnt(15)
	ds_write_b128 v161, v[78:81] offset:28672
	v_add_co_u32_e32 v78, vcc, s27, v168
	s_nop 1
	v_addc_co_u32_e32 v79, vcc, 0, v169, vcc
	global_load_dwordx4 v[78:81], v[78:79], off
	s_waitcnt lgkmcnt(0)
	s_barrier
	s_cbranch_scc1 .LBB0_1457
; template <int NJ>
; __device__ __forceinline__ void gemm_tile(const f16* __restrict__ A, int lda, const f16* __restrict__ Bt, int ldb,
;                                           int K, f32x4 (&acc)[4][NJ], f16* sA, f16* sB, const int tid) {
;     ...
;   G_LOAD(ra0, rb0, 0)
;   if (K > 64) G_LOAD(ra1, rb1, 64)
;   __syncthreads();
;   G_STORE(ra0, rb0, 0)
;   if (K > 128) G_LOAD(ra0, rb0, 128)
;   __syncthreads();
; #pragma unroll 1
;   for (int k0 = 0; k0 < K; k0 += 128) {
;     {
;       const int kof = (k0 + 192 < K) ? k0 + 192 : K - 64;
;       G_STEP(0, ra1, rb1, true, true, kof)
	ds_read_b128 v[204:207], v163 offset:16384
	ds_read_b128 v[208:211], v163 offset:18432
	ds_read_b128 v[212:215], v163 offset:20480
	ds_read_b128 v[216:219], v163 offset:22528
	s_add_i32 s11, s10, 0xc0
	ds_read_b128 v[192:195], v162
	ds_read_b128 v[196:199], v162 offset:2048
	s_cmpk_lt_u32 s10, 0xa40
	s_cselect_b32 s42, s11, 0xac0
	ds_read_b128 v[200:203], v162 offset:4096
	s_lshl_b64 s[12:13], s[42:43], 1
	v_lshl_add_u64 v[152:153], v[146:147], 0, s[12:13]
	ds_read_b128 v[130:133], v162 offset:6144
	ds_read_b128 v[244:247], v243 offset:16384
	ds_read_b128 v[248:251], v243 offset:18432
	ds_read_b128 v[252:255], v243 offset:20480
	s_waitcnt lgkmcnt(6)
	v_mfma_f32_16x16x32_f16 v[126:129], v[204:207], v[192:195], v[126:129]
	v_lshl_add_u64 v[150:151], v[148:149], 0, s[12:13]
	s_add_i32 s11, s10, 0x100
	s_cmpk_lt_u32 s10, 0xa00
	v_mfma_f32_16x16x32_f16 v[122:125], v[208:211], v[192:195], v[122:125]
	s_cselect_b32 s42, s11, 0xac0
	s_lshl_b64 s[12:13], s[42:43], 1
	v_lshl_add_u64 v[168:169], v[148:149], 0, s[12:13]
	v_mfma_f32_16x16x32_f16 v[118:121], v[212:215], v[192:195], v[118:121]
	s_add_i32 s11, s10, 0x80
	s_cmpk_lt_u32 s10, 0xa80
	s_mov_b32 s10, s11
	v_mfma_f32_16x16x32_f16 v[114:117], v[216:219], v[192:195], v[114:117]
	ds_read_b128 v[192:195], v243 offset:22528
	s_waitcnt vmcnt(15)
	ds_write_b128 v161, v[18:21] offset:32768
	global_load_dwordx4 v[18:21], v[152:153], off
	s_waitcnt lgkmcnt(7)
	v_mfma_f32_16x16x32_f16 v[110:113], v[204:207], v[196:199], v[110:113]
	v_mfma_f32_16x16x32_f16 v[106:109], v[208:211], v[196:199], v[106:109]
	v_mfma_f32_16x16x32_f16 v[102:105], v[212:215], v[196:199], v[102:105]
	v_mfma_f32_16x16x32_f16 v[98:101], v[216:219], v[196:199], v[98:101]
	ds_read_b128 v[196:199], v242
	s_waitcnt vmcnt(15)
	ds_write_b128 v161, v[26:29] offset:36864
	v_add_co_u32_e32 v26, vcc, s81, v152
	s_nop 1
	v_addc_co_u32_e32 v27, vcc, 0, v153, vcc
	global_load_dwordx4 v[26:29], v[26:27], off
	s_waitcnt lgkmcnt(8)
	v_mfma_f32_16x16x32_f16 v[94:97], v[204:207], v[200:203], v[94:97]
	v_mfma_f32_16x16x32_f16 v[90:93], v[208:211], v[200:203], v[90:93]
	v_mfma_f32_16x16x32_f16 v[86:89], v[212:215], v[200:203], v[86:89]
	v_mfma_f32_16x16x32_f16 v[82:85], v[216:219], v[200:203], v[82:85]
	ds_read_b128 v[200:203], v242 offset:2048
	s_waitcnt vmcnt(15)
	ds_write_b128 v161, v[30:33] offset:40960
	v_add_co_u32_e32 v30, vcc, s97, v152
	s_nop 1
	v_addc_co_u32_e32 v31, vcc, 0, v153, vcc
	global_load_dwordx4 v[30:33], v[30:31], off
	s_waitcnt lgkmcnt(9)
	v_mfma_f32_16x16x32_f16 v[14:17], v[204:207], v[130:133], v[14:17]
	v_mfma_f32_16x16x32_f16 v[10:13], v[208:211], v[130:133], v[10:13]
	v_mfma_f32_16x16x32_f16 v[6:9], v[212:215], v[130:133], v[6:9]
	v_mfma_f32_16x16x32_f16 v[2:5], v[216:219], v[130:133], v[2:5]
	ds_read_b128 v[130:133], v242 offset:4096
	ds_read_b128 v[204:207], v242 offset:6144
	s_waitcnt vmcnt(15)
	ds_write_b128 v161, v[34:37] offset:45056
	v_add_co_u32_e32 v34, vcc, s27, v152
	s_nop 1
	v_addc_co_u32_e32 v35, vcc, 0, v153, vcc
	global_load_dwordx4 v[34:37], v[34:35], off
	s_waitcnt lgkmcnt(6)
	v_mfma_f32_16x16x32_f16 v[126:129], v[244:247], v[196:199], v[126:129]
	v_mfma_f32_16x16x32_f16 v[122:125], v[248:251], v[196:199], v[122:125]
	v_mfma_f32_16x16x32_f16 v[118:121], v[252:255], v[196:199], v[118:121]
	v_mfma_f32_16x16x32_f16 v[114:117], v[192:195], v[196:199], v[114:117]
	s_waitcnt vmcnt(15)
	ds_write_b128 v161, v[22:25] offset:49152
	global_load_dwordx4 v[22:25], v[150:151], off
	v_lshl_add_u64 v[216:217], v[146:147], 0, s[12:13]
	s_waitcnt lgkmcnt(5)
	v_mfma_f32_16x16x32_f16 v[110:113], v[244:247], v[200:203], v[110:113]
	v_mfma_f32_16x16x32_f16 v[106:109], v[248:251], v[200:203], v[106:109]
	v_mfma_f32_16x16x32_f16 v[102:105], v[252:255], v[200:203], v[102:105]
	v_mfma_f32_16x16x32_f16 v[98:101], v[192:195], v[200:203], v[98:101]
	s_waitcnt vmcnt(15)
	ds_write_b128 v161, v[38:41] offset:53248
	v_add_co_u32_e32 v38, vcc, s81, v150
	s_nop 1
	v_addc_co_u32_e32 v39, vcc, 0, v151, vcc
	global_load_dwordx4 v[38:41], v[38:39], off
	s_waitcnt lgkmcnt(4)
	v_mfma_f32_16x16x32_f16 v[94:97], v[244:247], v[130:133], v[94:97]
	v_mfma_f32_16x16x32_f16 v[90:93], v[248:251], v[130:133], v[90:93]
	v_mfma_f32_16x16x32_f16 v[86:89], v[252:255], v[130:133], v[86:89]
	v_mfma_f32_16x16x32_f16 v[82:85], v[192:195], v[130:133], v[82:85]
	s_waitcnt vmcnt(15)
	ds_write_b128 v161, v[46:49] offset:57344
	v_add_co_u32_e32 v46, vcc, s97, v150
	s_nop 1
	v_addc_co_u32_e32 v47, vcc, 0, v151, vcc
	global_load_dwordx4 v[46:49], v[46:47], off
	s_waitcnt lgkmcnt(4)
	v_mfma_f32_16x16x32_f16 v[14:17], v[244:247], v[204:207], v[14:17]
	v_mfma_f32_16x16x32_f16 v[10:13], v[248:251], v[204:207], v[10:13]
	v_mfma_f32_16x16x32_f16 v[6:9], v[252:255], v[204:207], v[6:9]
	v_mfma_f32_16x16x32_f16 v[2:5], v[192:195], v[204:207], v[2:5]
	s_waitcnt vmcnt(15)
	ds_write_b128 v161, v[50:53] offset:61440
	v_add_co_u32_e32 v50, vcc, s27, v150
	s_nop 1
	v_addc_co_u32_e32 v51, vcc, 0, v151, vcc
	global_load_dwordx4 v[50:53], v[50:51], off
	s_waitcnt lgkmcnt(0)
	s_barrier
; template <int NJ>
; __device__ __forceinline__ void gemm_tile(const f16* __restrict__ A, int lda, const f16* __restrict__ Bt, int ldb,
;                                           int K, f32x4 (&acc)[4][NJ], f16* sA, f16* sB, const int tid) {
;     ...
;   G_LOAD(ra0, rb0, 0)
;   if (K > 64) G_LOAD(ra1, rb1, 64)
;   __syncthreads();
;   G_STORE(ra0, rb0, 0)
;   if (K > 128) G_LOAD(ra0, rb0, 128)
;   __syncthreads();
; #pragma unroll 1
;   for (int k0 = 0; k0 < K; k0 += 128) {
;     {
;       const int kof = (k0 + 192 < K) ? k0 + 192 : K - 64;
;       G_STEP(0, ra1, rb1, true, true, kof)
;     }
;     __syncthreads();
;     if (k0 + 64 >= K) break;
;     {
;       const int kof = (k0 + 256 < K) ? k0 + 256 : K - 64;
;       G_STEP(1, ra0, rb0, true, true, kof)
;     }
;     __syncthreads();
	ds_read_b128 v[200:203], v163 offset:49152
	ds_read_b128 v[204:207], v163 offset:51200
	ds_read_b128 v[208:211], v163 offset:53248
	ds_read_b128 v[212:215], v163 offset:55296
	ds_read_b128 v[130:133], v162 offset:32768
	ds_read_b128 v[150:153], v162 offset:34816
	ds_read_b128 v[192:195], v162 offset:36864
	ds_read_b128 v[196:199], v162 offset:38912
	ds_read_b128 v[244:247], v243 offset:49152
	ds_read_b128 v[248:251], v243 offset:51200
	ds_read_b128 v[252:255], v243 offset:53248
	s_waitcnt lgkmcnt(6)
	v_mfma_f32_16x16x32_f16 v[126:129], v[200:203], v[130:133], v[126:129]
	v_mfma_f32_16x16x32_f16 v[122:125], v[204:207], v[130:133], v[122:125]
	v_mfma_f32_16x16x32_f16 v[118:121], v[208:211], v[130:133], v[118:121]
	v_mfma_f32_16x16x32_f16 v[114:117], v[212:215], v[130:133], v[114:117]
	ds_read_b128 v[130:133], v243 offset:55296
	s_waitcnt vmcnt(15)
	ds_write_b128 v161, v[42:45]
	s_waitcnt lgkmcnt(7)
	v_mfma_f32_16x16x32_f16 v[110:113], v[200:203], v[150:153], v[110:113]
	v_mfma_f32_16x16x32_f16 v[106:109], v[204:207], v[150:153], v[106:109]
	v_mfma_f32_16x16x32_f16 v[102:105], v[208:211], v[150:153], v[102:105]
	v_mfma_f32_16x16x32_f16 v[98:101], v[212:215], v[150:153], v[98:101]
	ds_read_b128 v[150:153], v242 offset:32768
	s_waitcnt vmcnt(14)
	ds_write_b128 v161, v[58:61] offset:4096
	s_waitcnt lgkmcnt(8)
	v_mfma_f32_16x16x32_f16 v[94:97], v[200:203], v[192:195], v[94:97]
	v_mfma_f32_16x16x32_f16 v[90:93], v[204:207], v[192:195], v[90:93]
	v_mfma_f32_16x16x32_f16 v[86:89], v[208:211], v[192:195], v[86:89]
	v_mfma_f32_16x16x32_f16 v[82:85], v[212:215], v[192:195], v[82:85]
	ds_read_b128 v[192:195], v242 offset:34816
	s_waitcnt vmcnt(13)
	ds_write_b128 v161, v[62:65] offset:8192
	s_waitcnt lgkmcnt(9)
	v_mfma_f32_16x16x32_f16 v[14:17], v[200:203], v[196:199], v[14:17]
	v_mfma_f32_16x16x32_f16 v[10:13], v[204:207], v[196:199], v[10:13]
	v_mfma_f32_16x16x32_f16 v[6:9], v[208:211], v[196:199], v[6:9]
	v_mfma_f32_16x16x32_f16 v[2:5], v[212:215], v[196:199], v[2:5]
	ds_read_b128 v[196:199], v242 offset:36864
	ds_read_b128 v[200:203], v242 offset:38912
	s_waitcnt vmcnt(12)
	ds_write_b128 v161, v[66:69] offset:12288
	s_waitcnt lgkmcnt(6)
	v_mfma_f32_16x16x32_f16 v[126:129], v[244:247], v[150:153], v[126:129]
	v_mfma_f32_16x16x32_f16 v[122:125], v[248:251], v[150:153], v[122:125]
	v_mfma_f32_16x16x32_f16 v[118:121], v[252:255], v[150:153], v[118:121]
	v_mfma_f32_16x16x32_f16 v[114:117], v[130:133], v[150:153], v[114:117]
	s_waitcnt vmcnt(11)
	ds_write_b128 v161, v[54:57] offset:16384
	s_waitcnt lgkmcnt(5)
	v_mfma_f32_16x16x32_f16 v[110:113], v[244:247], v[192:195], v[110:113]
	v_mfma_f32_16x16x32_f16 v[106:109], v[248:251], v[192:195], v[106:109]
	v_mfma_f32_16x16x32_f16 v[102:105], v[252:255], v[192:195], v[102:105]
	v_mfma_f32_16x16x32_f16 v[98:101], v[130:133], v[192:195], v[98:101]
	s_waitcnt vmcnt(10)
	ds_write_b128 v161, v[70:73] offset:20480
	s_waitcnt lgkmcnt(4)
	v_mfma_f32_16x16x32_f16 v[94:97], v[244:247], v[196:199], v[94:97]
	v_mfma_f32_16x16x32_f16 v[90:93], v[248:251], v[196:199], v[90:93]
	v_mfma_f32_16x16x32_f16 v[86:89], v[252:255], v[196:199], v[86:89]
	v_mfma_f32_16x16x32_f16 v[82:85], v[130:133], v[196:199], v[82:85]
	s_waitcnt vmcnt(9)
	ds_write_b128 v161, v[74:77] offset:24576
	s_waitcnt lgkmcnt(4)
	v_mfma_f32_16x16x32_f16 v[14:17], v[244:247], v[200:203], v[14:17]
	v_mfma_f32_16x16x32_f16 v[10:13], v[248:251], v[200:203], v[10:13]
	v_mfma_f32_16x16x32_f16 v[6:9], v[252:255], v[200:203], v[6:9]
	v_mfma_f32_16x16x32_f16 v[2:5], v[130:133], v[200:203], v[2:5]
	s_waitcnt vmcnt(8)
	ds_write_b128 v161, v[78:81] offset:28672
	s_waitcnt lgkmcnt(0)
	s_barrier
	ds_read_b128 v[204:207], v163 offset:16384
	ds_read_b128 v[208:211], v163 offset:18432
	ds_read_b128 v[212:215], v163 offset:20480
	ds_read_b128 v[216:219], v163 offset:22528
	s_add_i32 s11, s10, 0xc0
	ds_read_b128 v[192:195], v162
	ds_read_b128 v[196:199], v162 offset:2048
	s_cmpk_lt_u32 s10, 0xa40
	s_cselect_b32 s42, s11, 0xac0
	ds_read_b128 v[200:203], v162 offset:4096
	s_lshl_b64 s[12:13], s[42:43], 1
	v_lshl_add_u64 v[152:153], v[146:147], 0, s[12:13]
	ds_read_b128 v[130:133], v162 offset:6144
	ds_read_b128 v[244:247], v243 offset:16384
	ds_read_b128 v[248:251], v243 offset:18432
	ds_read_b128 v[252:255], v243 offset:20480
	s_waitcnt lgkmcnt(6)
	v_mfma_f32_16x16x32_f16 v[126:129], v[204:207], v[192:195], v[126:129]
	v_lshl_add_u64 v[150:151], v[148:149], 0, s[12:13]
	s_add_i32 s11, s10, 0x100
	s_cmpk_lt_u32 s10, 0xa00
	v_mfma_f32_16x16x32_f16 v[122:125], v[208:211], v[192:195], v[122:125]
	s_cselect_b32 s42, s11, 0xac0
	s_lshl_b64 s[12:13], s[42:43], 1
	v_lshl_add_u64 v[168:169], v[148:149], 0, s[12:13]
	v_mfma_f32_16x16x32_f16 v[118:121], v[212:215], v[192:195], v[118:121]
	s_add_i32 s11, s10, 0x80
	s_cmpk_lt_u32 s10, 0xa80
	s_mov_b32 s10, s11
	v_mfma_f32_16x16x32_f16 v[114:117], v[216:219], v[192:195], v[114:117]
	ds_read_b128 v[192:195], v243 offset:22528
	s_waitcnt vmcnt(7)
	ds_write_b128 v161, v[18:21] offset:32768
	s_waitcnt lgkmcnt(7)
	v_mfma_f32_16x16x32_f16 v[110:113], v[204:207], v[196:199], v[110:113]
	v_mfma_f32_16x16x32_f16 v[106:109], v[208:211], v[196:199], v[106:109]
	v_mfma_f32_16x16x32_f16 v[102:105], v[212:215], v[196:199], v[102:105]
	v_mfma_f32_16x16x32_f16 v[98:101], v[216:219], v[196:199], v[98:101]
	ds_read_b128 v[196:199], v242
	s_waitcnt vmcnt(6)
	ds_write_b128 v161, v[26:29] offset:36864
	s_waitcnt lgkmcnt(8)
	v_mfma_f32_16x16x32_f16 v[94:97], v[204:207], v[200:203], v[94:97]
	v_mfma_f32_16x16x32_f16 v[90:93], v[208:211], v[200:203], v[90:93]
	v_mfma_f32_16x16x32_f16 v[86:89], v[212:215], v[200:203], v[86:89]
	v_mfma_f32_16x16x32_f16 v[82:85], v[216:219], v[200:203], v[82:85]
	ds_read_b128 v[200:203], v242 offset:2048
	s_waitcnt vmcnt(5)
; template <int NJ>
; __device__ __forceinline__ void gemm_tile(const f16* __restrict__ A, int lda, const f16* __restrict__ Bt, int ldb,
;                                           int K, f32x4 (&acc)[4][NJ], f16* sA, f16* sB, const int tid) {
;     ...
;   G_LOAD(ra0, rb0, 0)
;   if (K > 64) G_LOAD(ra1, rb1, 64)
;   __syncthreads();
;   G_STORE(ra0, rb0, 0)
;   if (K > 128) G_LOAD(ra0, rb0, 128)
;   __syncthreads();
; #pragma unroll 1
;   for (int k0 = 0; k0 < K; k0 += 128) {
;     {
;       const int kof = (k0 + 192 < K) ? k0 + 192 : K - 64;
;       G_STEP(0, ra1, rb1, true, true, kof)
;     }
;     __syncthreads();
;     if (k0 + 64 >= K) break;
;     {
;       const int kof = (k0 + 256 < K) ? k0 + 256 : K - 64;
;       G_STEP(1, ra0, rb0, true, true, kof)
;     }
;     __syncthreads();
	ds_write_b128 v161, v[30:33] offset:40960
	s_waitcnt lgkmcnt(9)
	v_mfma_f32_16x16x32_f16 v[14:17], v[204:207], v[130:133], v[14:17]
	v_mfma_f32_16x16x32_f16 v[10:13], v[208:211], v[130:133], v[10:13]
	v_mfma_f32_16x16x32_f16 v[6:9], v[212:215], v[130:133], v[6:9]
	v_mfma_f32_16x16x32_f16 v[2:5], v[216:219], v[130:133], v[2:5]
	ds_read_b128 v[130:133], v242 offset:4096
	ds_read_b128 v[204:207], v242 offset:6144
	s_waitcnt vmcnt(4)
	ds_write_b128 v161, v[34:37] offset:45056
	s_waitcnt lgkmcnt(6)
	v_mfma_f32_16x16x32_f16 v[126:129], v[244:247], v[196:199], v[126:129]
	v_mfma_f32_16x16x32_f16 v[122:125], v[248:251], v[196:199], v[122:125]
	v_mfma_f32_16x16x32_f16 v[118:121], v[252:255], v[196:199], v[118:121]
	v_mfma_f32_16x16x32_f16 v[114:117], v[192:195], v[196:199], v[114:117]
	s_waitcnt vmcnt(3)
	ds_write_b128 v161, v[22:25] offset:49152
	v_lshl_add_u64 v[216:217], v[146:147], 0, s[12:13]
	s_waitcnt lgkmcnt(5)
	v_mfma_f32_16x16x32_f16 v[110:113], v[244:247], v[200:203], v[110:113]
	v_mfma_f32_16x16x32_f16 v[106:109], v[248:251], v[200:203], v[106:109]
	v_mfma_f32_16x16x32_f16 v[102:105], v[252:255], v[200:203], v[102:105]
	v_mfma_f32_16x16x32_f16 v[98:101], v[192:195], v[200:203], v[98:101]
	s_waitcnt vmcnt(2)
	ds_write_b128 v161, v[38:41] offset:53248
	s_waitcnt lgkmcnt(4)
	v_mfma_f32_16x16x32_f16 v[94:97], v[244:247], v[130:133], v[94:97]
	v_mfma_f32_16x16x32_f16 v[90:93], v[248:251], v[130:133], v[90:93]
	v_mfma_f32_16x16x32_f16 v[86:89], v[252:255], v[130:133], v[86:89]
	v_mfma_f32_16x16x32_f16 v[82:85], v[192:195], v[130:133], v[82:85]
	s_waitcnt vmcnt(1)
	ds_write_b128 v161, v[46:49] offset:57344
	s_waitcnt lgkmcnt(4)
	v_mfma_f32_16x16x32_f16 v[14:17], v[244:247], v[204:207], v[14:17]
	v_mfma_f32_16x16x32_f16 v[10:13], v[248:251], v[204:207], v[10:13]
	v_mfma_f32_16x16x32_f16 v[6:9], v[252:255], v[204:207], v[6:9]
	v_mfma_f32_16x16x32_f16 v[2:5], v[192:195], v[204:207], v[2:5]
	s_waitcnt vmcnt(0)
	ds_write_b128 v161, v[50:53] offset:61440
	s_waitcnt lgkmcnt(0)
	s_barrier
	ds_read_b128 v[200:203], v163 offset:49152
	ds_read_b128 v[204:207], v163 offset:51200
	ds_read_b128 v[208:211], v163 offset:53248
	ds_read_b128 v[212:215], v163 offset:55296
	ds_read_b128 v[130:133], v162 offset:32768
	ds_read_b128 v[150:153], v162 offset:34816
	ds_read_b128 v[192:195], v162 offset:36864
	ds_read_b128 v[196:199], v162 offset:38912
	ds_read_b128 v[244:247], v243 offset:49152
	ds_read_b128 v[248:251], v243 offset:51200
	ds_read_b128 v[252:255], v243 offset:53248
	s_waitcnt lgkmcnt(6)
	v_mfma_f32_16x16x32_f16 v[126:129], v[200:203], v[130:133], v[126:129]
	v_mfma_f32_16x16x32_f16 v[122:125], v[204:207], v[130:133], v[122:125]
	v_mfma_f32_16x16x32_f16 v[118:121], v[208:211], v[130:133], v[118:121]
	v_mfma_f32_16x16x32_f16 v[114:117], v[212:215], v[130:133], v[114:117]
	ds_read_b128 v[130:133], v243 offset:55296
	s_waitcnt lgkmcnt(6)
	v_mfma_f32_16x16x32_f16 v[110:113], v[200:203], v[150:153], v[110:113]
	v_mfma_f32_16x16x32_f16 v[106:109], v[204:207], v[150:153], v[106:109]
	v_mfma_f32_16x16x32_f16 v[102:105], v[208:211], v[150:153], v[102:105]
	v_mfma_f32_16x16x32_f16 v[98:101], v[212:215], v[150:153], v[98:101]
	ds_read_b128 v[150:153], v242 offset:32768
	s_waitcnt lgkmcnt(6)
	v_mfma_f32_16x16x32_f16 v[94:97], v[200:203], v[192:195], v[94:97]
	v_mfma_f32_16x16x32_f16 v[90:93], v[204:207], v[192:195], v[90:93]
	v_mfma_f32_16x16x32_f16 v[86:89], v[208:211], v[192:195], v[86:89]
	v_mfma_f32_16x16x32_f16 v[82:85], v[212:215], v[192:195], v[82:85]
	ds_read_b128 v[192:195], v242 offset:34816
	s_waitcnt lgkmcnt(6)
	v_mfma_f32_16x16x32_f16 v[14:17], v[200:203], v[196:199], v[14:17]
	v_mfma_f32_16x16x32_f16 v[10:13], v[204:207], v[196:199], v[10:13]
	v_mfma_f32_16x16x32_f16 v[6:9], v[208:211], v[196:199], v[6:9]
	v_mfma_f32_16x16x32_f16 v[2:5], v[212:215], v[196:199], v[2:5]
	ds_read_b128 v[196:199], v242 offset:36864
	ds_read_b128 v[200:203], v242 offset:38912
	s_waitcnt lgkmcnt(3)
	v_mfma_f32_16x16x32_f16 v[126:129], v[244:247], v[150:153], v[126:129]
	v_mfma_f32_16x16x32_f16 v[122:125], v[248:251], v[150:153], v[122:125]
	v_mfma_f32_16x16x32_f16 v[118:121], v[252:255], v[150:153], v[118:121]
	v_mfma_f32_16x16x32_f16 v[114:117], v[130:133], v[150:153], v[114:117]
	s_waitcnt lgkmcnt(2)
	v_mfma_f32_16x16x32_f16 v[110:113], v[244:247], v[192:195], v[110:113]
	v_mfma_f32_16x16x32_f16 v[106:109], v[248:251], v[192:195], v[106:109]
	v_mfma_f32_16x16x32_f16 v[102:105], v[252:255], v[192:195], v[102:105]
	v_mfma_f32_16x16x32_f16 v[98:101], v[130:133], v[192:195], v[98:101]
	s_waitcnt lgkmcnt(1)
	v_mfma_f32_16x16x32_f16 v[94:97], v[244:247], v[196:199], v[94:97]
	v_mfma_f32_16x16x32_f16 v[90:93], v[248:251], v[196:199], v[90:93]
	v_mfma_f32_16x16x32_f16 v[86:89], v[252:255], v[196:199], v[86:89]
	v_mfma_f32_16x16x32_f16 v[82:85], v[130:133], v[196:199], v[82:85]
	s_waitcnt lgkmcnt(0)
	v_mfma_f32_16x16x32_f16 v[14:17], v[244:247], v[200:203], v[14:17]
	v_mfma_f32_16x16x32_f16 v[10:13], v[248:251], v[200:203], v[10:13]
	v_mfma_f32_16x16x32_f16 v[6:9], v[252:255], v[200:203], v[6:9]
	v_mfma_f32_16x16x32_f16 v[2:5], v[130:133], v[200:203], v[2:5]
	s_waitcnt lgkmcnt(0)
	s_barrier
; template <int NJ>
; __device__ __forceinline__ void gres_tile(const Params& p, const f16* A, int lda, const f16* W, int K, const float* mod,
;                                           bool first_in, f16* sA, f16* sB, int m0, int n0) {
;     ...
; #pragma unroll
;   for (int i = 0; i < 4; ++i) {
;     int m = m0 + wm * 64 + i * 16 + (lane & 15);
;     const float* xi = xrow_in(p, first_in ? 0 : 1, m);
;     float* xo = xrow_out(p, m);
;     const float* gt = mod + (size_t)modrow_of(m) * 6 * DM;
; #pragma unroll
;     for (int j = 0; j < NJ; ++j) {
;       int n = n0 + wn * (NJ * 16) + j * 16 + 4 * (lane >> 4);
;       float4 xv = *(const float4*)(xi + n);
;       float4 gv = *(const float4*)(gt + n);
;       float4 o;
;       o.x = xv.x + gv.x * acc[i][j][0];
;       o.y = xv.y + gv.y * acc[i][j][1];
;       o.z = xv.z + gv.z * acc[i][j][2];
;       o.w = xv.w + gv.w * acc[i][j][3];
;       *(float4*)(xo + n) = o;
;     }
;   }
	s_waitcnt vmcnt(15)
	v_or_b32_e32 v18, s6, v154
	v_add_u32_e32 v21, v18, v160
	v_cmp_gt_i32_e32 vcc, s80, v21
	v_ashrrev_i32_e32 v20, 31, v21
	s_waitcnt vmcnt(11)
	v_add_u32_e32 v22, 0xffff8000, v21
	v_cndmask_b32_e32 v23, 0, v20, vcc
	v_cndmask_b32_e32 v22, v22, v21, vcc
	v_cndmask_b32_e32 v25, v137, v1, vcc
	v_cndmask_b32_e32 v24, v136, v0, vcc
	v_lshlrev_b64 v[22:23], 12, v[22:23]
	v_lshrrev_b32_e32 v20, 18, v20
	v_lshl_add_u64 v[22:23], v[24:25], 0, v[22:23]
	v_add_u32_e32 v24, v21, v20
	v_lshl_or_b32 v18, s7, 7, v166
	v_ashrrev_i32_e32 v24, 14, v24
	v_ashrrev_i32_e32 v19, 31, v18
	v_cndmask_b32_e32 v24, 2, v24, vcc
	v_mul_hi_i32_i24_e32 v25, 0x6000, v24
	v_mul_i32_i24_e32 v24, 0x6000, v24
	v_lshlrev_b64 v[18:19], 2, v[18:19]
	v_lshl_add_u64 v[24:25], v[134:135], 0, v[24:25]
	v_lshl_add_u64 v[30:31], v[22:23], 0, v[18:19]
	v_lshl_add_u64 v[32:33], v[24:25], 0, v[18:19]
	global_load_dwordx4 v[22:25], v[30:31], off
	global_load_dwordx4 v[26:29], v[32:33], off
	s_add_i32 s5, s5, s26
	s_cmp_ge_i32 s5, s74
	s_waitcnt vmcnt(0)
	v_pk_fma_f32 v[22:23], v[126:127], v[26:27], v[22:23]
	v_pk_fma_f32 v[24:25], v[128:129], v[28:29], v[24:25]
	global_store_dwordx4 v[30:31], v[22:25], off
	global_load_dwordx4 v[22:25], v[30:31], off offset:64
	s_nop 0
	global_load_dwordx4 v[26:29], v[32:33], off offset:64
	s_waitcnt vmcnt(0)
	v_pk_fma_f32 v[22:23], v[122:123], v[26:27], v[22:23]
	v_pk_fma_f32 v[24:25], v[124:125], v[28:29], v[24:25]
	global_store_dwordx4 v[30:31], v[22:25], off offset:64
	global_load_dwordx4 v[22:25], v[30:31], off offset:128
	s_nop 0
	global_load_dwordx4 v[26:29], v[32:33], off offset:128
	s_waitcnt vmcnt(0)
	v_pk_fma_f32 v[22:23], v[118:119], v[26:27], v[22:23]
	v_pk_fma_f32 v[24:25], v[120:121], v[28:29], v[24:25]
	global_store_dwordx4 v[30:31], v[22:25], off offset:128
	global_load_dwordx4 v[22:25], v[30:31], off offset:192
	s_nop 0
	global_load_dwordx4 v[26:29], v[32:33], off offset:192
	s_waitcnt vmcnt(0)
	v_pk_fma_f32 v[22:23], v[114:115], v[26:27], v[22:23]
	v_pk_fma_f32 v[24:25], v[116:117], v[28:29], v[24:25]
	v_or_b32_e32 v26, 16, v21
	global_store_dwordx4 v[30:31], v[22:25], off offset:192
	v_cmp_gt_i32_e32 vcc, s80, v26
	s_nop 0
	v_ashrrev_i32_e32 v22, 31, v26
	v_add_u32_e32 v24, 0xffff8010, v21
	v_cndmask_b32_e32 v23, 0, v22, vcc
	v_cndmask_b32_e32 v22, v24, v26, vcc
	v_cndmask_b32_e32 v25, v137, v1, vcc
	v_cndmask_b32_e32 v24, v136, v0, vcc
	v_lshlrev_b64 v[22:23], 12, v[22:23]
	v_lshl_add_u64 v[22:23], v[24:25], 0, v[22:23]
	v_add_u32_e32 v24, v26, v20
	v_ashrrev_i32_e32 v24, 14, v24
	v_cndmask_b32_e32 v24, 2, v24, vcc
	v_mul_hi_i32_i24_e32 v25, 0x6000, v24
	v_mul_i32_i24_e32 v24, 0x6000, v24
	v_lshl_add_u64 v[24:25], v[134:135], 0, v[24:25]
	v_lshl_add_u64 v[30:31], v[22:23], 0, v[18:19]
	v_lshl_add_u64 v[32:33], v[24:25], 0, v[18:19]
	global_load_dwordx4 v[22:25], v[30:31], off
	global_load_dwordx4 v[26:29], v[32:33], off
	s_waitcnt vmcnt(0)
	v_pk_fma_f32 v[22:23], v[110:111], v[26:27], v[22:23]
	v_pk_fma_f32 v[24:25], v[112:113], v[28:29], v[24:25]
	global_store_dwordx4 v[30:31], v[22:25], off
	global_load_dwordx4 v[22:25], v[30:31], off offset:64
	s_nop 0
	global_load_dwordx4 v[26:29], v[32:33], off offset:64
	s_waitcnt vmcnt(0)
	v_pk_fma_f32 v[22:23], v[106:107], v[26:27], v[22:23]
	v_pk_fma_f32 v[24:25], v[108:109], v[28:29], v[24:25]
	global_store_dwordx4 v[30:31], v[22:25], off offset:64
	global_load_dwordx4 v[22:25], v[30:31], off offset:128
	s_nop 0
	global_load_dwordx4 v[26:29], v[32:33], off offset:128
	s_waitcnt vmcnt(0)
	v_pk_fma_f32 v[22:23], v[102:103], v[26:27], v[22:23]
	v_pk_fma_f32 v[24:25], v[104:105], v[28:29], v[24:25]
	global_store_dwordx4 v[30:31], v[22:25], off offset:128
	global_load_dwordx4 v[22:25], v[30:31], off offset:192
	s_nop 0
	global_load_dwordx4 v[26:29], v[32:33], off offset:192
	s_waitcnt vmcnt(0)
; template <int NJ>
; __device__ __forceinline__ void gres_tile(const Params& p, const f16* A, int lda, const f16* W, int K, const float* mod,
;                                           bool first_in, f16* sA, f16* sB, int m0, int n0) {
;     ...
;     for (int j = 0; j < NJ; ++j) {
;       int n = n0 + wn * (NJ * 16) + j * 16 + 4 * (lane >> 4);
;       float4 xv = *(const float4*)(xi + n);
;       float4 gv = *(const float4*)(gt + n);
;       float4 o;
;       o.x = xv.x + gv.x * acc[i][j][0];
;       o.y = xv.y + gv.y * acc[i][j][1];
;       o.z = xv.z + gv.z * acc[i][j][2];
;       o.w = xv.w + gv.w * acc[i][j][3];
;       *(float4*)(xo + n) = o;
;     }
;   }
; }
; __device__ __forceinline__ void phase_gres(const Params& p, int l, const f16* A, int lda, const f16* W, int K, int gate_idx,
;                            bool first_in, f16* smem) {
;   f16* sA = smem;
;   f16* sB = smem + 128 * LDT;
;   const float* mod = (const float*)(p.ws + MOD_OFF) + (size_t)l * 3 * 6 * DM + (size_t)gate_idx * DM;
;   constexpr int NT = DM / 128, MT = NTOK / 128;
;   const int full = (MT * NT / (int)gridDim.x) * (int)gridDim.x;
;   for (int t = blockIdx.x; t < full; t += gridDim.x)
;     gres_tile<4>(p, A, lda, W, K, mod, first_in, sA, sB, (t / NT) * 128, (t % NT) * 128);
	v_pk_fma_f32 v[22:23], v[98:99], v[26:27], v[22:23]
	v_pk_fma_f32 v[24:25], v[100:101], v[28:29], v[24:25]
	v_or_b32_e32 v26, 32, v21
	global_store_dwordx4 v[30:31], v[22:25], off offset:192
	v_cmp_gt_i32_e32 vcc, s80, v26
	s_nop 0
	v_ashrrev_i32_e32 v22, 31, v26
	v_add_u32_e32 v24, 0xffff8020, v21
	v_cndmask_b32_e32 v23, 0, v22, vcc
	v_cndmask_b32_e32 v22, v24, v26, vcc
	v_cndmask_b32_e32 v25, v137, v1, vcc
	v_cndmask_b32_e32 v24, v136, v0, vcc
	v_lshlrev_b64 v[22:23], 12, v[22:23]
	v_lshl_add_u64 v[22:23], v[24:25], 0, v[22:23]
	v_add_u32_e32 v24, v26, v20
	v_ashrrev_i32_e32 v24, 14, v24
	v_cndmask_b32_e32 v24, 2, v24, vcc
	v_mul_hi_i32_i24_e32 v25, 0x6000, v24
	v_mul_i32_i24_e32 v24, 0x6000, v24
	v_lshl_add_u64 v[24:25], v[134:135], 0, v[24:25]
	v_lshl_add_u64 v[30:31], v[22:23], 0, v[18:19]
	v_lshl_add_u64 v[32:33], v[24:25], 0, v[18:19]
	global_load_dwordx4 v[22:25], v[30:31], off
	global_load_dwordx4 v[26:29], v[32:33], off
	s_waitcnt vmcnt(0)
	v_pk_fma_f32 v[22:23], v[94:95], v[26:27], v[22:23]
	v_pk_fma_f32 v[24:25], v[96:97], v[28:29], v[24:25]
	global_store_dwordx4 v[30:31], v[22:25], off
	global_load_dwordx4 v[22:25], v[30:31], off offset:64
	s_nop 0
	global_load_dwordx4 v[26:29], v[32:33], off offset:64
	s_waitcnt vmcnt(0)
	v_pk_fma_f32 v[22:23], v[90:91], v[26:27], v[22:23]
	v_pk_fma_f32 v[24:25], v[92:93], v[28:29], v[24:25]
	global_store_dwordx4 v[30:31], v[22:25], off offset:64
	global_load_dwordx4 v[22:25], v[30:31], off offset:128
	s_nop 0
	global_load_dwordx4 v[26:29], v[32:33], off offset:128
	s_waitcnt vmcnt(0)
	v_pk_fma_f32 v[22:23], v[86:87], v[26:27], v[22:23]
	v_pk_fma_f32 v[24:25], v[88:89], v[28:29], v[24:25]
	global_store_dwordx4 v[30:31], v[22:25], off offset:128
	global_load_dwordx4 v[22:25], v[30:31], off offset:192
	s_nop 0
	global_load_dwordx4 v[26:29], v[32:33], off offset:192
	s_waitcnt vmcnt(0)
	v_pk_fma_f32 v[22:23], v[82:83], v[26:27], v[22:23]
	v_pk_fma_f32 v[24:25], v[84:85], v[28:29], v[24:25]
	v_or_b32_e32 v26, 48, v21
	global_store_dwordx4 v[30:31], v[22:25], off offset:192
	v_cmp_gt_i32_e32 vcc, s80, v26
	v_add_u32_e32 v21, 0xffff8030, v21
	v_ashrrev_i32_e32 v22, 31, v26
	v_add_u32_e32 v20, v26, v20
	v_cndmask_b32_e32 v23, 0, v22, vcc
	v_cndmask_b32_e32 v22, v21, v26, vcc
	v_ashrrev_i32_e32 v20, 14, v20
	v_cndmask_b32_e32 v25, v137, v1, vcc
	v_cndmask_b32_e32 v24, v136, v0, vcc
	v_lshlrev_b64 v[22:23], 12, v[22:23]
	v_cndmask_b32_e32 v20, 2, v20, vcc
	v_lshl_add_u64 v[22:23], v[24:25], 0, v[22:23]
	v_mul_hi_i32_i24_e32 v21, 0x6000, v20
	v_mul_i32_i24_e32 v20, 0x6000, v20
	v_lshl_add_u64 v[20:21], v[134:135], 0, v[20:21]
	v_lshl_add_u64 v[26:27], v[22:23], 0, v[18:19]
	v_lshl_add_u64 v[28:29], v[20:21], 0, v[18:19]
	global_load_dwordx4 v[18:21], v[26:27], off
	global_load_dwordx4 v[22:25], v[28:29], off
	s_waitcnt vmcnt(0)
	v_pk_fma_f32 v[14:15], v[14:15], v[22:23], v[18:19]
	v_pk_fma_f32 v[16:17], v[16:17], v[24:25], v[20:21]
	global_store_dwordx4 v[26:27], v[14:17], off
	global_load_dwordx4 v[14:17], v[26:27], off offset:64
	s_nop 0
	global_load_dwordx4 v[18:21], v[28:29], off offset:64
	s_waitcnt vmcnt(0)
	v_pk_fma_f32 v[10:11], v[10:11], v[18:19], v[14:15]
	v_pk_fma_f32 v[12:13], v[12:13], v[20:21], v[16:17]
	global_store_dwordx4 v[26:27], v[10:13], off offset:64
	global_load_dwordx4 v[10:13], v[26:27], off offset:128
	s_nop 0
	global_load_dwordx4 v[14:17], v[28:29], off offset:128
	s_waitcnt vmcnt(0)
	v_pk_fma_f32 v[6:7], v[6:7], v[14:15], v[10:11]
	v_pk_fma_f32 v[8:9], v[8:9], v[16:17], v[12:13]
	global_store_dwordx4 v[26:27], v[6:9], off offset:128
	global_load_dwordx4 v[6:9], v[26:27], off offset:192
	s_nop 0
	global_load_dwordx4 v[10:13], v[28:29], off offset:192
	s_waitcnt vmcnt(0)
	v_pk_fma_f32 v[2:3], v[2:3], v[10:11], v[6:7]
	v_pk_fma_f32 v[4:5], v[4:5], v[12:13], v[8:9]
	global_store_dwordx4 v[26:27], v[2:5], off offset:192
	s_cbranch_scc0 .LBB0_1456
